# GEMM epilogues: EpiGU row-stat loads hoisted (one round trip per tile), EpiIn c1/c2 loads hoisted out of the row loop and dead vmcnt(0) waits on stores removed
# speedup vs baseline: 1.0904x; 1.0436x over previous
; #define PG8_STAGE(bufoff, gbase, voff) do { _Pragma("unroll") for (int _i = 0; _i < 2; ++_i) \
;         __builtin_amdgcn_global_load_lds((const unsigned*)((const char*)(gbase) + (voff)[_i]), (LAS unsigned*)(lds + (bufoff) + ldsw + _i * 8192), 16, 0, 0); } while (0)
; #define PG8_LDA(dst, b, h) do { _Pragma("unroll") for (int m = 0; m < 4; ++m) _Pragma("unroll") for (int k = 0; k < 2; ++k) dst[m][k] = *(const LAS bf16x8*)(lds + PG8_SA(b, h) + aoff + m * 2048 + k * 1024); } while (0)
; #define PG8_WAIT_V(n) asm volatile("s_waitcnt vmcnt(" #n ")" ::: "memory")
; #define PG8_WAIT_L(n) asm volatile("s_waitcnt lgkmcnt(" #n ")" ::: "memory")
; template <class Epi>
; __device__ __forceinline__ void gemm_phase(const Tb tb, LAS unsigned char* lds, const Gemm g, const StaticOrder& S, const Epi& E) {
;     ...
;         for (int t = 0; t < nt; t += 2) {
;             const bool last = (t == nt - 2);
;             const char* a1 = cA + (size_t)(t + 1) * kstep;
;             const char* a2 = last ? nA : cA + (size_t)(t + 2) * kstep; const char* b2 = last ? nB : cB + (size_t)(t + 2) * kstep;
;             const char* a3 = a2 + kstep; const char* b3 = b2 + kstep;
;             PG8_LDB(B0, 0, 0); PG8_SCHED; PG8_LDA(At, 0, 0); PG8_STAGE(PG8_SA(1, 1), a1 + hstep, voffA);
;             PG8_WAIT_L(8); PG8_BAR; PG8_WAIT_L(0); PG8_MMA(0, 0, At, B0); PG8_BAR; PG8_SCHED;
;             PG8_LDB(B1, 0, 1); PG8_STAGE(PG8_SB(0, 0), b2, voffB);
;             PG8_BAR; PG8_WAIT_L(0); PG8_MMA(0, 1, At, B1); PG8_BAR;
;             PG8_LDA(At, 0, 1); PG8_STAGE(PG8_SA(0, 0), a2, voffA);
;             PG8_BAR; PG8_WAIT_L(0); PG8_MMA(1, 0, At, B0); PG8_BAR; PG8_SCHED;
;             PG8_STAGE(PG8_SB(0, 1), b2 + hstep, voffB);
;             PG8_WAIT_V(6); PG8_BAR; PG8_MMA(1, 1, At, B1); PG8_BAR;
;             PG8_LDB(B0, 1, 0); PG8_SCHED; PG8_LDA(At, 1, 0); PG8_STAGE(PG8_SA(0, 1), a2 + hstep, voffA);
;             PG8_WAIT_L(8); PG8_BAR; PG8_WAIT_L(0); PG8_MMA(0, 0, At, B0); PG8_BAR; PG8_SCHED;
;             PG8_LDB(B1, 1, 1); PG8_STAGE(PG8_SB(1, 0), b3, voffB);
;             PG8_BAR; PG8_WAIT_L(0); PG8_MMA(0, 1, At, B1); PG8_BAR;
;             PG8_LDA(At, 1, 1); PG8_STAGE(PG8_SA(1, 0), a3, voffA);
;             PG8_BAR; PG8_WAIT_L(0); PG8_MMA(1, 0, At, B0); PG8_BAR; PG8_SCHED;
;             PG8_STAGE(PG8_SB(1, 1), b3 + hstep, voffB);
;             PG8_WAIT_V(6); PG8_BAR; PG8_MMA(1, 1, At, B1); PG8_BAR;
.LBB0_184:
	s_add_u32 s28, s26, 0xfffc0080
	s_addc_u32 s29, s27, -1
	s_add_i32 s55, 0, 0x10000
	v_add_u32_e32 v60, s55, v177
	ds_read_b128 v[48:51], v60
	ds_read_b128 v[52:55], v60 offset:1024
	ds_read_b128 v[56:59], v60 offset:2048
	ds_read_b128 v[60:63], v60 offset:3072
	s_cmp_eq_u32 s54, 12
	s_cselect_b32 s31, s5, s29
	s_cselect_b32 s30, s21, s28
	s_cselect_b32 s29, s19, s53
	s_cselect_b32 s28, s51, s52
	v_lshl_add_u64 v[170:171], s[26:27], 0, v[164:165]
	s_add_i32 m0, s42, 0xc000
	ds_read_b128 v[72:75], v179
	ds_read_b128 v[76:79], v179 offset:1024
	ds_read_b128 v[80:83], v179 offset:2048
	ds_read_b128 v[84:87], v179 offset:3072
	ds_read_b128 v[166:169], v179 offset:4096
	ds_read_b128 v[204:207], v179 offset:5120
	ds_read_b128 v[208:211], v179 offset:6144
	ds_read_b128 v[212:215], v179 offset:7168
	global_load_lds_dwordx4 v[170:171], off
	v_lshl_add_u64 v[170:171], s[26:27], 0, v[162:163]
	s_add_i32 m0, s42, 0xe000
	s_nop 0
	global_load_lds_dwordx4 v[170:171], off
	s_waitcnt lgkmcnt(8)
	s_barrier
	s_waitcnt lgkmcnt(0)
	s_setprio 1
	s_waitcnt lgkmcnt(0)
	v_mfma_f32_16x16x32_bf16 v[156:159], v[48:51], v[72:75], v[156:159]
	v_mfma_f32_16x16x32_bf16 v[148:151], v[56:59], v[72:75], v[148:151]
	v_mfma_f32_16x16x32_bf16 v[140:143], v[48:51], v[80:83], v[140:143]
	v_mfma_f32_16x16x32_bf16 v[132:135], v[56:59], v[80:83], v[132:135]
	v_mfma_f32_16x16x32_bf16 v[124:127], v[48:51], v[166:169], v[124:127]
	v_mfma_f32_16x16x32_bf16 v[116:119], v[56:59], v[166:169], v[116:119]
	v_mfma_f32_16x16x32_bf16 v[108:111], v[48:51], v[208:211], v[108:111]
	v_mfma_f32_16x16x32_bf16 v[100:103], v[56:59], v[208:211], v[100:103]
	v_mfma_f32_16x16x32_bf16 v[156:159], v[52:55], v[76:79], v[156:159]
	v_mfma_f32_16x16x32_bf16 v[148:151], v[60:63], v[76:79], v[148:151]
	v_mfma_f32_16x16x32_bf16 v[140:143], v[52:55], v[84:87], v[140:143]
	v_mfma_f32_16x16x32_bf16 v[132:135], v[60:63], v[84:87], v[132:135]
	v_mfma_f32_16x16x32_bf16 v[124:127], v[52:55], v[204:207], v[124:127]
	v_mfma_f32_16x16x32_bf16 v[116:119], v[60:63], v[204:207], v[116:119]
	v_mfma_f32_16x16x32_bf16 v[108:111], v[52:55], v[212:215], v[108:111]
	v_mfma_f32_16x16x32_bf16 v[100:103], v[60:63], v[212:215], v[100:103]
	s_setprio 0
	s_barrier
	s_add_i32 s58, 0, 0x14000
	v_add_u32_e32 v170, s58, v177
	s_add_i32 s55, s55, s40
	ds_read_b128 v[216:219], v170
	ds_read_b128 v[220:223], v170 offset:1024
	ds_read_b128 v[224:227], v170 offset:2048
	ds_read_b128 v[228:231], v170 offset:3072
	v_lshl_add_u64 v[170:171], s[28:29], 0, v[180:181]
	s_mov_b32 m0, s55
	v_lshl_add_u64 v[174:175], s[28:29], 0, v[160:161]
	global_load_lds_dwordx4 v[170:171], off
	s_add_i32 m0, s55, 0x2000
	s_nop 0
	global_load_lds_dwordx4 v[174:175], off
	s_barrier
	s_waitcnt lgkmcnt(0)
	s_setprio 1
	s_waitcnt lgkmcnt(0)
	v_mfma_f32_16x16x32_bf16 v[152:155], v[216:219], v[72:75], v[152:155]
	v_mfma_f32_16x16x32_bf16 v[72:75], v[224:227], v[72:75], v[144:147]
	v_mfma_f32_16x16x32_bf16 v[152:155], v[220:223], v[76:79], v[152:155]
	v_mfma_f32_16x16x32_bf16 v[72:75], v[228:231], v[76:79], v[72:75]
	v_mfma_f32_16x16x32_bf16 v[76:79], v[216:219], v[80:83], v[136:139]
	v_mfma_f32_16x16x32_bf16 v[80:83], v[224:227], v[80:83], v[128:131]
	v_mfma_f32_16x16x32_bf16 v[112:115], v[224:227], v[166:169], v[112:115]
	v_mfma_f32_16x16x32_bf16 v[104:107], v[216:219], v[208:211], v[104:107]
	v_mfma_f32_16x16x32_bf16 v[96:99], v[224:227], v[208:211], v[96:99]
	v_mfma_f32_16x16x32_bf16 v[76:79], v[220:223], v[84:87], v[76:79]
	v_mfma_f32_16x16x32_bf16 v[80:83], v[228:231], v[84:87], v[80:83]
	v_mfma_f32_16x16x32_bf16 v[84:87], v[216:219], v[166:169], v[120:123]
	v_mfma_f32_16x16x32_bf16 v[112:115], v[228:231], v[204:207], v[112:115]
	v_mfma_f32_16x16x32_bf16 v[104:107], v[220:223], v[212:215], v[104:107]
	v_mfma_f32_16x16x32_bf16 v[96:99], v[228:231], v[212:215], v[96:99]
	v_mfma_f32_16x16x32_bf16 v[84:87], v[220:223], v[204:207], v[84:87]
	s_setprio 0
	s_mov_b32 m0, s42
	v_lshl_add_u64 v[198:199], s[30:31], 0, v[180:181]
	s_barrier
	ds_read_b128 v[120:123], v179 offset:16384
	ds_read_b128 v[128:131], v179 offset:17408
	ds_read_b128 v[136:139], v179 offset:18432
	ds_read_b128 v[144:147], v179 offset:19456
	ds_read_b128 v[166:169], v179 offset:20480
	ds_read_b128 v[204:207], v179 offset:21504
	ds_read_b128 v[208:211], v179 offset:22528
	ds_read_b128 v[212:215], v179 offset:23552
	global_load_lds_dwordx4 v[198:199], off
	v_lshl_add_u64 v[250:251], s[30:31], 0, v[160:161]
	s_mov_b32 m0, s43
	s_nop 0
	global_load_lds_dwordx4 v[250:251], off
	s_barrier
	s_waitcnt lgkmcnt(0)
	s_setprio 1
	s_waitcnt lgkmcnt(0)
	v_mfma_f32_16x16x32_bf16 v[92:95], v[48:51], v[120:123], v[92:95]
	v_mfma_f32_16x16x32_bf16 v[68:71], v[56:59], v[120:123], v[68:71]
	v_mfma_f32_16x16x32_bf16 v[44:47], v[48:51], v[136:139], v[44:47]
	v_mfma_f32_16x16x32_bf16 v[36:39], v[56:59], v[136:139], v[36:39]
	v_mfma_f32_16x16x32_bf16 v[28:31], v[48:51], v[166:169], v[28:31]
	v_mfma_f32_16x16x32_bf16 v[20:23], v[56:59], v[166:169], v[20:23]
	v_mfma_f32_16x16x32_bf16 v[12:15], v[48:51], v[208:211], v[12:15]
	v_mfma_f32_16x16x32_bf16 v[4:7], v[56:59], v[208:211], v[4:7]
	v_mfma_f32_16x16x32_bf16 v[92:95], v[52:55], v[128:131], v[92:95]
	v_mfma_f32_16x16x32_bf16 v[68:71], v[60:63], v[128:131], v[68:71]
	v_mfma_f32_16x16x32_bf16 v[44:47], v[52:55], v[144:147], v[44:47]
	v_mfma_f32_16x16x32_bf16 v[36:39], v[60:63], v[144:147], v[36:39]
	v_mfma_f32_16x16x32_bf16 v[28:31], v[52:55], v[204:207], v[28:31]
	v_mfma_f32_16x16x32_bf16 v[20:23], v[60:63], v[204:207], v[20:23]
	v_mfma_f32_16x16x32_bf16 v[12:15], v[52:55], v[212:215], v[12:15]
	v_mfma_f32_16x16x32_bf16 v[4:7], v[60:63], v[212:215], v[4:7]
	s_setprio 0
	s_barrier
; #define PG8_STAGE(bufoff, gbase, voff) do { _Pragma("unroll") for (int _i = 0; _i < 2; ++_i) \
;         __builtin_amdgcn_global_load_lds((const unsigned*)((const char*)(gbase) + (voff)[_i]), (LAS unsigned*)(lds + (bufoff) + ldsw + _i * 8192), 16, 0, 0); } while (0)
; #define PG8_LDA(dst, b, h) do { _Pragma("unroll") for (int m = 0; m < 4; ++m) _Pragma("unroll") for (int k = 0; k < 2; ++k) dst[m][k] = *(const LAS bf16x8*)(lds + PG8_SA(b, h) + aoff + m * 2048 + k * 1024); } while (0)
; #define PG8_LDB(dst, b, h) do { _Pragma("unroll") for (int n = 0; n < 2; ++n) _Pragma("unroll") for (int k = 0; k < 2; ++k) dst[n][k] = *(const LAS bf16x8*)(lds + PG8_SB(b, h) + boff + n * 2048 + k * 1024); } while (0)
; #define PG8_WAIT_V(n) asm volatile("s_waitcnt vmcnt(" #n ")" ::: "memory")
; #define PG8_WAIT_L(n) asm volatile("s_waitcnt lgkmcnt(" #n ")" ::: "memory")
; #define PG8_BAR __builtin_amdgcn_s_barrier()
; #define PG8_SCHED __builtin_amdgcn_sched_barrier(0)
; template <class Epi>
; __device__ __forceinline__ void gemm_phase(const Tb tb, LAS unsigned char* lds, const Gemm g, const StaticOrder& S, const Epi& E) {
;     ...
;             PG8_LDB(B0, 0, 0); PG8_SCHED; PG8_LDA(At, 0, 0); PG8_STAGE(PG8_SA(1, 1), a1 + hstep, voffA);
;             PG8_WAIT_L(8); PG8_BAR; PG8_WAIT_L(0); PG8_MMA(0, 0, At, B0); PG8_BAR; PG8_SCHED;
;             PG8_LDB(B1, 0, 1); PG8_STAGE(PG8_SB(0, 0), b2, voffB);
;             PG8_BAR; PG8_WAIT_L(0); PG8_MMA(0, 1, At, B1); PG8_BAR;
;             PG8_LDA(At, 0, 1); PG8_STAGE(PG8_SA(0, 0), a2, voffA);
;             PG8_BAR; PG8_WAIT_L(0); PG8_MMA(1, 0, At, B0); PG8_BAR; PG8_SCHED;
;             PG8_STAGE(PG8_SB(0, 1), b2 + hstep, voffB);
;             PG8_WAIT_V(6); PG8_BAR; PG8_MMA(1, 1, At, B1); PG8_BAR;
;             PG8_LDB(B0, 1, 0); PG8_SCHED; PG8_LDA(At, 1, 0); PG8_STAGE(PG8_SA(0, 1), a2 + hstep, voffA);
;             PG8_WAIT_L(8); PG8_BAR; PG8_WAIT_L(0); PG8_MMA(0, 0, At, B0); PG8_BAR; PG8_SCHED;
;             PG8_LDB(B1, 1, 1); PG8_STAGE(PG8_SB(1, 0), b3, voffB);
;             PG8_BAR; PG8_WAIT_L(0); PG8_MMA(0, 1, At, B1); PG8_BAR;
;             PG8_LDA(At, 1, 1); PG8_STAGE(PG8_SA(1, 0), a3, voffA);
;             PG8_BAR; PG8_WAIT_L(0); PG8_MMA(1, 0, At, B0); PG8_BAR; PG8_SCHED;
;             PG8_STAGE(PG8_SB(1, 1), b3 + hstep, voffB);
;             PG8_WAIT_V(6); PG8_BAR; PG8_MMA(1, 1, At, B1); PG8_BAR;
	s_add_u32 s56, s28, 0x40000
	s_addc_u32 s57, s29, 0
	s_add_i32 s55, s58, s40
	v_lshl_add_u64 v[48:49], s[56:57], 0, v[180:181]
	s_mov_b32 m0, s55
	s_nop 0
	global_load_lds_dwordx4 v[48:49], off
	v_lshl_add_u64 v[48:49], s[56:57], 0, v[160:161]
	s_add_i32 m0, s55, 0x2000
	s_nop 0
	global_load_lds_dwordx4 v[48:49], off
	s_waitcnt vmcnt(6)
	s_barrier
	s_setprio 1
	v_mfma_f32_16x16x32_bf16 v[40:43], v[216:219], v[136:139], v[40:43]
	v_mfma_f32_16x16x32_bf16 v[32:35], v[224:227], v[136:139], v[32:35]
	v_mfma_f32_16x16x32_bf16 v[24:27], v[216:219], v[166:169], v[24:27]
	v_mfma_f32_16x16x32_bf16 v[16:19], v[224:227], v[166:169], v[16:19]
	v_mfma_f32_16x16x32_bf16 v[8:11], v[216:219], v[208:211], v[8:11]
	v_mfma_f32_16x16x32_bf16 v[0:3], v[224:227], v[208:211], v[0:3]
	v_mfma_f32_16x16x32_bf16 v[48:51], v[216:219], v[120:123], v[88:91]
	v_mfma_f32_16x16x32_bf16 v[52:55], v[224:227], v[120:123], v[64:67]
	v_mfma_f32_16x16x32_bf16 v[40:43], v[220:223], v[144:147], v[40:43]
	v_mfma_f32_16x16x32_bf16 v[32:35], v[228:231], v[144:147], v[32:35]
	v_mfma_f32_16x16x32_bf16 v[24:27], v[220:223], v[204:207], v[24:27]
	v_mfma_f32_16x16x32_bf16 v[16:19], v[228:231], v[204:207], v[16:19]
	v_mfma_f32_16x16x32_bf16 v[8:11], v[220:223], v[212:215], v[8:11]
	v_mfma_f32_16x16x32_bf16 v[0:3], v[228:231], v[212:215], v[0:3]
	v_mfma_f32_16x16x32_bf16 v[48:51], v[220:223], v[128:131], v[48:51]
	v_mfma_f32_16x16x32_bf16 v[52:55], v[228:231], v[128:131], v[52:55]
	s_setprio 0
	s_add_i32 s55, 0, 0x18000
	v_add_u32_e32 v88, s55, v177
	s_barrier
	ds_read_b128 v[56:59], v88
	ds_read_b128 v[60:63], v88 offset:1024
	ds_read_b128 v[64:67], v88 offset:2048
	ds_read_b128 v[88:91], v88 offset:3072
	s_add_u32 s30, s30, 0x40000
	s_addc_u32 s31, s31, 0
	s_mov_b32 m0, s44
	v_lshl_add_u64 v[136:137], s[30:31], 0, v[180:181]
	ds_read_b128 v[120:123], v179 offset:32768
	ds_read_b128 v[128:131], v179 offset:33792
	ds_read_b128 v[166:169], v179 offset:34816
	ds_read_b128 v[204:207], v179 offset:35840
	ds_read_b128 v[208:211], v179 offset:36864
	ds_read_b128 v[212:215], v179 offset:37888
	ds_read_b128 v[216:219], v179 offset:38912
	ds_read_b128 v[220:223], v179 offset:39936
	global_load_lds_dwordx4 v[136:137], off
	v_lshl_add_u64 v[136:137], s[30:31], 0, v[160:161]
	s_mov_b32 m0, s45
	s_nop 0
	global_load_lds_dwordx4 v[136:137], off
	s_waitcnt lgkmcnt(8)
	s_barrier
	s_waitcnt lgkmcnt(0)
	s_setprio 1
	s_waitcnt lgkmcnt(0)
	v_mfma_f32_16x16x32_bf16 v[136:139], v[56:59], v[120:123], v[156:159]
	v_mfma_f32_16x16x32_bf16 v[156:159], v[60:63], v[128:131], v[136:139]
	v_mfma_f32_16x16x32_bf16 v[136:139], v[64:67], v[120:123], v[148:151]
	v_mfma_f32_16x16x32_bf16 v[148:151], v[88:91], v[128:131], v[136:139]
	v_mfma_f32_16x16x32_bf16 v[136:139], v[56:59], v[166:169], v[140:143]
	v_mfma_f32_16x16x32_bf16 v[132:135], v[64:67], v[166:169], v[132:135]
	v_mfma_f32_16x16x32_bf16 v[124:127], v[56:59], v[208:211], v[124:127]
	v_mfma_f32_16x16x32_bf16 v[116:119], v[64:67], v[208:211], v[116:119]
	v_mfma_f32_16x16x32_bf16 v[108:111], v[56:59], v[216:219], v[108:111]
	v_mfma_f32_16x16x32_bf16 v[100:103], v[64:67], v[216:219], v[100:103]
	v_mfma_f32_16x16x32_bf16 v[140:143], v[60:63], v[204:207], v[136:139]
	v_mfma_f32_16x16x32_bf16 v[132:135], v[88:91], v[204:207], v[132:135]
	v_mfma_f32_16x16x32_bf16 v[124:127], v[60:63], v[212:215], v[124:127]
	v_mfma_f32_16x16x32_bf16 v[116:119], v[88:91], v[212:215], v[116:119]
	v_mfma_f32_16x16x32_bf16 v[108:111], v[60:63], v[220:223], v[108:111]
	v_mfma_f32_16x16x32_bf16 v[100:103], v[88:91], v[220:223], v[100:103]
	s_setprio 0
	s_barrier
	s_add_i32 s30, 0, 0x1c000
	v_add_u32_e32 v136, s30, v177
	s_add_i32 s31, s55, s40
	ds_read_b128 v[224:227], v136
	ds_read_b128 v[228:231], v136 offset:1024
	ds_read_b128 v[232:235], v136 offset:2048
	ds_read_b128 v[242:245], v136 offset:3072
	v_lshl_add_u64 v[136:137], v[170:171], 0, s[0:1]
	s_mov_b32 m0, s31
	s_nop 0
	global_load_lds_dwordx4 v[136:137], off
	v_lshl_add_u64 v[136:137], v[174:175], 0, s[0:1]
	s_add_i32 m0, s31, 0x2000
	s_nop 0
	global_load_lds_dwordx4 v[136:137], off
	s_barrier
	s_waitcnt lgkmcnt(0)
	s_setprio 1
	s_waitcnt lgkmcnt(0)
	v_mfma_f32_16x16x32_bf16 v[72:75], v[232:235], v[120:123], v[72:75]
	v_mfma_f32_16x16x32_bf16 v[136:139], v[224:227], v[120:123], v[152:155]
	v_mfma_f32_16x16x32_bf16 v[144:147], v[242:245], v[128:131], v[72:75]
	v_mfma_f32_16x16x32_bf16 v[72:75], v[224:227], v[166:169], v[76:79]
	v_mfma_f32_16x16x32_bf16 v[152:155], v[228:231], v[128:131], v[136:139]
	v_mfma_f32_16x16x32_bf16 v[136:139], v[228:231], v[204:207], v[72:75]
	v_mfma_f32_16x16x32_bf16 v[72:75], v[232:235], v[166:169], v[80:83]
	v_mfma_f32_16x16x32_bf16 v[128:131], v[242:245], v[204:207], v[72:75]
	v_mfma_f32_16x16x32_bf16 v[72:75], v[224:227], v[208:211], v[84:87]
	v_mfma_f32_16x16x32_bf16 v[120:123], v[228:231], v[212:215], v[72:75]
	v_mfma_f32_16x16x32_bf16 v[72:75], v[232:235], v[208:211], v[112:115]
	v_mfma_f32_16x16x32_bf16 v[112:115], v[242:245], v[212:215], v[72:75]
	v_mfma_f32_16x16x32_bf16 v[72:75], v[224:227], v[216:219], v[104:107]
	v_mfma_f32_16x16x32_bf16 v[104:107], v[228:231], v[220:223], v[72:75]
	v_mfma_f32_16x16x32_bf16 v[72:75], v[232:235], v[216:219], v[96:99]
	v_mfma_f32_16x16x32_bf16 v[96:99], v[242:245], v[220:223], v[72:75]
	s_setprio 0
	s_mov_b32 m0, s46
	v_lshl_add_u64 v[170:171], v[198:199], 0, s[0:1]
	s_barrier
	s_nop 2
	ds_read_b128 v[72:75], v179 offset:49152
	ds_read_b128 v[76:79], v179 offset:50176
	ds_read_b128 v[80:83], v179 offset:51200
	ds_read_b128 v[84:87], v179 offset:52224
	ds_read_b128 v[166:169], v179 offset:53248
	ds_read_b128 v[204:207], v179 offset:54272
	ds_read_b128 v[208:211], v179 offset:55296
	ds_read_b128 v[212:215], v179 offset:56320
	global_load_lds_dwordx4 v[170:171], off
	v_lshl_add_u64 v[170:171], v[250:251], 0, s[0:1]
	s_mov_b32 m0, s47
	s_nop 0
	global_load_lds_dwordx4 v[170:171], off
	s_barrier
; #define PG8_STAGE(bufoff, gbase, voff) do { _Pragma("unroll") for (int _i = 0; _i < 2; ++_i) \
;         __builtin_amdgcn_global_load_lds((const unsigned*)((const char*)(gbase) + (voff)[_i]), (LAS unsigned*)(lds + (bufoff) + ldsw + _i * 8192), 16, 0, 0); } while (0)
; #define PG8_LDA(dst, b, h) do { _Pragma("unroll") for (int m = 0; m < 4; ++m) _Pragma("unroll") for (int k = 0; k < 2; ++k) dst[m][k] = *(const LAS bf16x8*)(lds + PG8_SA(b, h) + aoff + m * 2048 + k * 1024); } while (0)
; #define PG8_LDB(dst, b, h) do { _Pragma("unroll") for (int n = 0; n < 2; ++n) _Pragma("unroll") for (int k = 0; k < 2; ++k) dst[n][k] = *(const LAS bf16x8*)(lds + PG8_SB(b, h) + boff + n * 2048 + k * 1024); } while (0)
; template <class Epi>
; __device__ __forceinline__ void gemm_phase(const Tb tb, LAS unsigned char* lds, const Gemm g, const StaticOrder& S, const Epi& E) {
;     ...
;             PG8_WAIT_V(6); PG8_BAR; PG8_MMA(1, 1, At, B1); PG8_BAR;
;             PG8_LDB(B0, 1, 0); PG8_SCHED; PG8_LDA(At, 1, 0); PG8_STAGE(PG8_SA(0, 1), a2 + hstep, voffA);
;             PG8_WAIT_L(8); PG8_BAR; PG8_WAIT_L(0); PG8_MMA(0, 0, At, B0); PG8_BAR; PG8_SCHED;
;             PG8_LDB(B1, 1, 1); PG8_STAGE(PG8_SB(1, 0), b3, voffB);
;             PG8_BAR; PG8_WAIT_L(0); PG8_MMA(0, 1, At, B1); PG8_BAR;
;             PG8_LDA(At, 1, 1); PG8_STAGE(PG8_SA(1, 0), a3, voffA);
;             PG8_BAR; PG8_WAIT_L(0); PG8_MMA(1, 0, At, B0); PG8_BAR; PG8_SCHED;
;             PG8_STAGE(PG8_SB(1, 1), b3 + hstep, voffB);
;             PG8_WAIT_V(6); PG8_BAR; PG8_MMA(1, 1, At, B1); PG8_BAR;
;     __device__ __forceinline__ void operator()(const f32x4 (&acc)[2][2][4][2], const pg8::Unit& u, int wr, int wc, int fr, int fq) const {
;         const int row0 = u.pm * 256 + wr * 64 + fr, hcol0 = u.pn * 128 + wc * 32 + 4 * fq, ci0 = u.pn * 256 + wc * 32 + 4 * fq;
;         f32x4 c1g[2], c2g[2], c1u[2], c2u[2];
; #pragma unroll
;         for (int n = 0; n < 2; ++n) { c1g[n] = *(const f32x4*)(c1 + ci0 + 16 * n); c2g[n] = *(const f32x4*)(c2 + ci0 + 16 * n); c1u[n] = *(const f32x4*)(c1 + ci0 + 128 + 16 * n); c2u[n] = *(const f32x4*)(c2 + ci0 + 128 + 16 * n); }
; #pragma unroll
;         for (int ai = 0; ai < 2; ++ai)
; #pragma unroll
;             for (int m = 0; m < 4; ++m) {
;                 const int row = row0 + ai * 128 + m * 16; float mu, rstd; row_stats(stats, row, mu, rstd);
	s_waitcnt lgkmcnt(0)
	s_setprio 1
	s_waitcnt lgkmcnt(0)
	v_mfma_f32_16x16x32_bf16 v[92:95], v[56:59], v[72:75], v[92:95]
	v_mfma_f32_16x16x32_bf16 v[68:71], v[64:67], v[72:75], v[68:71]
	v_mfma_f32_16x16x32_bf16 v[44:47], v[56:59], v[80:83], v[44:47]
	v_mfma_f32_16x16x32_bf16 v[36:39], v[64:67], v[80:83], v[36:39]
	v_mfma_f32_16x16x32_bf16 v[28:31], v[56:59], v[166:169], v[28:31]
	v_mfma_f32_16x16x32_bf16 v[20:23], v[64:67], v[166:169], v[20:23]
	v_mfma_f32_16x16x32_bf16 v[12:15], v[56:59], v[208:211], v[12:15]
	v_mfma_f32_16x16x32_bf16 v[4:7], v[64:67], v[208:211], v[4:7]
	v_mfma_f32_16x16x32_bf16 v[92:95], v[60:63], v[76:79], v[92:95]
	v_mfma_f32_16x16x32_bf16 v[68:71], v[88:91], v[76:79], v[68:71]
	v_mfma_f32_16x16x32_bf16 v[44:47], v[60:63], v[84:87], v[44:47]
	v_mfma_f32_16x16x32_bf16 v[36:39], v[88:91], v[84:87], v[36:39]
	v_mfma_f32_16x16x32_bf16 v[28:31], v[60:63], v[204:207], v[28:31]
	v_mfma_f32_16x16x32_bf16 v[20:23], v[88:91], v[204:207], v[20:23]
	v_mfma_f32_16x16x32_bf16 v[12:15], v[60:63], v[212:215], v[12:15]
	v_mfma_f32_16x16x32_bf16 v[4:7], v[88:91], v[212:215], v[4:7]
	s_setprio 0
	s_barrier
	s_add_u32 s28, s28, 0x40080
	s_addc_u32 s29, s29, 0
	s_add_i32 s30, s30, s40
	v_lshl_add_u64 v[56:57], s[28:29], 0, v[180:181]
	s_mov_b32 m0, s30
	s_nop 0
	global_load_lds_dwordx4 v[56:57], off
	v_lshl_add_u64 v[56:57], s[28:29], 0, v[160:161]
	s_add_i32 m0, s30, 0x2000
	s_nop 0
	global_load_lds_dwordx4 v[56:57], off
	s_waitcnt vmcnt(6)
	s_barrier
	s_setprio 1
	v_mfma_f32_16x16x32_bf16 v[48:51], v[224:227], v[72:75], v[48:51]
	v_mfma_f32_16x16x32_bf16 v[88:91], v[228:231], v[76:79], v[48:51]
	v_mfma_f32_16x16x32_bf16 v[48:51], v[232:235], v[72:75], v[52:55]
	v_mfma_f32_16x16x32_bf16 v[40:43], v[224:227], v[80:83], v[40:43]
	v_mfma_f32_16x16x32_bf16 v[32:35], v[232:235], v[80:83], v[32:35]
	v_mfma_f32_16x16x32_bf16 v[24:27], v[224:227], v[166:169], v[24:27]
	v_mfma_f32_16x16x32_bf16 v[16:19], v[232:235], v[166:169], v[16:19]
	v_mfma_f32_16x16x32_bf16 v[8:11], v[224:227], v[208:211], v[8:11]
	v_mfma_f32_16x16x32_bf16 v[0:3], v[232:235], v[208:211], v[0:3]
	v_mfma_f32_16x16x32_bf16 v[64:67], v[242:245], v[76:79], v[48:51]
	v_mfma_f32_16x16x32_bf16 v[40:43], v[228:231], v[84:87], v[40:43]
	v_mfma_f32_16x16x32_bf16 v[32:35], v[242:245], v[84:87], v[32:35]
	v_mfma_f32_16x16x32_bf16 v[24:27], v[228:231], v[204:207], v[24:27]
	v_mfma_f32_16x16x32_bf16 v[16:19], v[242:245], v[204:207], v[16:19]
	v_mfma_f32_16x16x32_bf16 v[8:11], v[228:231], v[212:215], v[8:11]
	v_mfma_f32_16x16x32_bf16 v[0:3], v[242:245], v[212:215], v[0:3]
	s_setprio 0
	s_add_i32 s54, s54, 2
	s_add_u32 s52, s52, 0x100
	s_addc_u32 s53, s53, 0
	s_add_u32 s26, s26, 0x100
	s_addc_u32 s27, s27, 0
	s_cmp_gt_u32 s54, 13
	s_barrier
	s_cbranch_scc0 .LBB0_184
	v_lshl_or_b32 v48, s50, 8, v178
	v_ashrrev_i32_e32 v49, 31, v48
	v_lshlrev_b64 v[48:49], 2, v[48:49]
	v_lshl_add_u64 v[50:51], s[8:9], 0, v[48:49]
	v_lshl_add_u64 v[52:53], s[14:15], 0, v[48:49]
	global_load_dwordx4 v[72:75], v[50:51], off
	global_load_dwordx4 v[56:59], v[50:51], off offset:64
	global_load_dwordx4 v[84:87], v[52:53], off
	global_load_dwordx4 v[60:63], v[52:53], off offset:64
	global_load_dwordx4 v[76:79], v[50:51], off offset:512
	s_nop 0
	global_load_dwordx4 v[48:51], v[50:51], off offset:576
	s_nop 0
	global_load_dwordx4 v[80:83], v[52:53], off offset:512
	s_nop 0
	global_load_dwordx4 v[52:55], v[52:53], off offset:576
	v_lshl_add_u32 v168, s4, 8, v173
	v_cndmask_b32_e64 v166, 0, 1, s[16:17]
	v_ashrrev_i32_e32 v169, 31, v168
	v_mov_b32_e32 v172, 1.0
	v_mov_b32_e32 v170, 0
	v_cmp_ne_u32_e64 s[4:5], 1, v166
	s_andn2_b64 vcc, exec, s[16:17]
	v_mov_b32_e32 v174, 0
	v_mov_b32_e32 v176, 1.0
	s_cbranch_vccnz .LBB0_187
	v_lshl_add_u64 v[166:167], v[168:169], 3, s[12:13]
	global_load_dwordx2 v[174:175], v[166:167], off
	global_load_dwordx2 v[206:207], v[166:167], off offset:128
	global_load_dwordx2 v[208:209], v[166:167], off offset:256
	global_load_dwordx2 v[210:211], v[166:167], off offset:384
	global_load_dwordx2 v[212:213], v[166:167], off offset:1024
	global_load_dwordx2 v[214:215], v[166:167], off offset:1152
	global_load_dwordx2 v[216:217], v[166:167], off offset:1280
	global_load_dwordx2 v[218:219], v[166:167], off offset:1408
	s_waitcnt vmcnt(0)
	v_mov_b32_e32 v176, v175
; __device__ __forceinline__ unsigned pk2(float lo, float hi) { const f32x2_t v = {lo, hi}; const bf16x2_t b = __builtin_convertvector(v, bf16x2_t); return __builtin_bit_cast(unsigned, b); }
;     __device__ __forceinline__ void operator()(const f32x4 (&acc)[2][2][4][2], const pg8::Unit& u, int wr, int wc, int fr, int fq) const {
;     ...
;         for (int ai = 0; ai < 2; ++ai)
; #pragma unroll
;             for (int m = 0; m < 4; ++m) {
;                 const int row = row0 + ai * 128 + m * 16; float mu, rstd; row_stats(stats, row, mu, rstd);
; #pragma unroll
;                 for (int n = 0; n < 2; ++n) {
;                     float hv[4];
; #pragma unroll
;                     for (int j = 0; j < 4; ++j) {
;                         const float gt = rstd * (acc[ai][0][m][n][j] - mu * c1g[n][j]) + c2g[n][j];
;                         const float up = rstd * (acc[ai][1][m][n][j] - mu * c1u[n][j]) + c2u[n][j];
;                         hv[j] = gt * __builtin_amdgcn_rcpf(1.f + __expf(-gt)) * up;
;                     }
;                     u32x2 w; w.x = pk2(hv[0], hv[1]); w.y = pk2(hv[2], hv[3]);
;                     *(u32x2*)(H + (size_t)row * FF_ + hcol0 + 16 * n) = w;
;                 }
.LBB0_187:
	s_waitcnt vmcnt(0)
	v_pk_fma_f32 v[156:157], v[72:73], v[174:175], v[156:157] op_sel_hi:[1,0,1] neg_lo:[1,0,0] neg_hi:[1,0,0]
	v_pk_fma_f32 v[152:153], v[76:77], v[174:175], v[152:153] op_sel_hi:[1,0,1] neg_lo:[1,0,0] neg_hi:[1,0,0]
	v_pk_fma_f32 v[156:157], v[176:177], v[156:157], v[84:85] op_sel_hi:[0,1,1]
	v_mul_f32_e32 v169, 0xbfb8aa3b, v156
	v_exp_f32_e32 v169, v169
	v_pk_fma_f32 v[152:153], v[176:177], v[152:153], v[80:81] op_sel_hi:[0,1,1]
	v_pk_fma_f32 v[154:155], v[78:79], v[174:175], v[154:155] op_sel_hi:[1,0,1] neg_lo:[1,0,0] neg_hi:[1,0,0]
	v_lshl_or_b32 v166, s50, 7, v178
	v_add_f32_e32 v169, 1.0, v169
	v_rcp_f32_e32 v198, v169
	v_mul_f32_e32 v169, 0xbfb8aa3b, v157
	v_exp_f32_e32 v169, v169
	v_pk_fma_f32 v[154:155], v[176:177], v[154:155], v[82:83] op_sel_hi:[0,1,1]
	s_movk_i32 s19, 0x1600
	v_ashrrev_i32_e32 v167, 31, v166
	v_add_f32_e32 v169, 1.0, v169
	v_rcp_f32_e32 v199, v169
	v_pk_fma_f32 v[148:149], v[56:57], v[174:175], v[148:149] op_sel_hi:[1,0,1] neg_lo:[1,0,0] neg_hi:[1,0,0]
	v_pk_fma_f32 v[144:145], v[48:49], v[174:175], v[144:145] op_sel_hi:[1,0,1] neg_lo:[1,0,0] neg_hi:[1,0,0]
	v_pk_fma_f32 v[148:149], v[176:177], v[148:149], v[60:61] op_sel_hi:[0,1,1]
	v_pk_mul_f32 v[156:157], v[156:157], v[198:199]
	v_pk_fma_f32 v[144:145], v[176:177], v[144:145], v[52:53] op_sel_hi:[0,1,1]
	v_pk_mul_f32 v[152:153], v[152:153], v[156:157]
	v_pk_fma_f32 v[156:157], v[74:75], v[174:175], v[158:159] op_sel_hi:[1,0,1] neg_lo:[1,0,0] neg_hi:[1,0,0]
	v_cvt_pk_bf16_f32 v152, v152, v153
	v_pk_fma_f32 v[156:157], v[176:177], v[156:157], v[86:87] op_sel_hi:[0,1,1]
	v_mul_f32_e32 v158, 0xbfb8aa3b, v156
	v_mul_f32_e32 v159, 0xbfb8aa3b, v157
	v_exp_f32_e32 v158, v158
	v_exp_f32_e32 v159, v159
	v_pk_fma_f32 v[146:147], v[50:51], v[174:175], v[146:147] op_sel_hi:[1,0,1] neg_lo:[1,0,0] neg_hi:[1,0,0]
	s_and_b64 vcc, exec, s[4:5]
	v_add_f32_e32 v158, 1.0, v158
	v_add_f32_e32 v159, 1.0, v159
	v_rcp_f32_e32 v158, v158
	v_rcp_f32_e32 v159, v159
	v_pk_fma_f32 v[146:147], v[176:177], v[146:147], v[54:55] op_sel_hi:[0,1,1]
	v_pk_mul_f32 v[156:157], v[156:157], v[158:159]
	s_nop 0
	v_pk_mul_f32 v[154:155], v[154:155], v[156:157]
	s_nop 0
	v_cvt_pk_bf16_f32 v153, v154, v155
	v_mov_b64_e32 v[154:155], s[6:7]
	v_mad_i64_i32 v[154:155], s[26:27], v168, s19, v[154:155]
	v_lshl_add_u64 v[154:155], v[166:167], 1, v[154:155]
	global_store_dwordx2 v[154:155], v[152:153], off
	v_mul_f32_e32 v152, 0xbfb8aa3b, v148
	v_mul_f32_e32 v153, 0xbfb8aa3b, v149
	v_exp_f32_e32 v152, v152
	v_exp_f32_e32 v153, v153
	v_add_f32_e32 v152, 1.0, v152
	v_add_f32_e32 v153, 1.0, v153
	v_rcp_f32_e32 v152, v152
	v_rcp_f32_e32 v153, v153
	s_nop 0
	v_pk_mul_f32 v[148:149], v[148:149], v[152:153]
	s_nop 0
	v_pk_mul_f32 v[144:145], v[144:145], v[148:149]
	v_pk_fma_f32 v[148:149], v[58:59], v[174:175], v[150:151] op_sel_hi:[1,0,1] neg_lo:[1,0,0] neg_hi:[1,0,0]
	v_cvt_pk_bf16_f32 v144, v144, v145
	v_pk_fma_f32 v[148:149], v[176:177], v[148:149], v[62:63] op_sel_hi:[0,1,1]
	v_mul_f32_e32 v150, 0xbfb8aa3b, v148
	v_mul_f32_e32 v151, 0xbfb8aa3b, v149
	v_exp_f32_e32 v150, v150
	v_exp_f32_e32 v151, v151
	v_add_f32_e32 v150, 1.0, v150
	v_add_f32_e32 v151, 1.0, v151
	v_rcp_f32_e32 v150, v150
	v_rcp_f32_e32 v151, v151
	s_nop 0
	v_pk_mul_f32 v[148:149], v[148:149], v[150:151]
	s_nop 0
	v_pk_mul_f32 v[146:147], v[146:147], v[148:149]
	s_nop 0
	v_cvt_pk_bf16_f32 v145, v146, v147
	global_store_dwordx2 v[154:155], v[144:145], off offset:32
	v_or_b32_e32 v144, 16, v168
	v_ashrrev_i32_e32 v145, 31, v144
	s_cbranch_vccnz .LBB0_189
	v_mov_b32_e32 v170, v206
	v_mov_b32_e32 v171, v207
	v_mov_b32_e32 v172, v171
.LBB0_189:
	v_pk_fma_f32 v[140:141], v[72:73], v[170:171], v[140:141] op_sel_hi:[1,0,1] neg_lo:[1,0,0] neg_hi:[1,0,0]
	v_pk_fma_f32 v[142:143], v[74:75], v[170:171], v[142:143] op_sel_hi:[1,0,1] neg_lo:[1,0,0] neg_hi:[1,0,0]
	v_pk_fma_f32 v[146:147], v[172:173], v[140:141], v[84:85] op_sel_hi:[0,1,1]
	v_mul_f32_e32 v140, 0xbfb8aa3b, v146
	v_exp_f32_e32 v141, v140
	v_pk_fma_f32 v[142:143], v[172:173], v[142:143], v[86:87] op_sel_hi:[0,1,1]
	v_pk_fma_f32 v[136:137], v[76:77], v[170:171], v[136:137] op_sel_hi:[1,0,1] neg_lo:[1,0,0] neg_hi:[1,0,0]
	v_pk_fma_f32 v[138:139], v[78:79], v[170:171], v[138:139] op_sel_hi:[1,0,1] neg_lo:[1,0,0] neg_hi:[1,0,0]
	v_add_f32_e32 v141, 1.0, v141
	v_rcp_f32_e32 v148, v141
	v_mul_f32_e32 v141, 0xbfb8aa3b, v147
	v_exp_f32_e32 v141, v141
	v_pk_fma_f32 v[136:137], v[172:173], v[136:137], v[80:81] op_sel_hi:[0,1,1]
	v_pk_fma_f32 v[138:139], v[172:173], v[138:139], v[82:83] op_sel_hi:[0,1,1]
	v_pk_fma_f32 v[132:133], v[56:57], v[170:171], v[132:133] op_sel_hi:[1,0,1] neg_lo:[1,0,0] neg_hi:[1,0,0]
	v_add_f32_e32 v141, 1.0, v141
	v_rcp_f32_e32 v149, v141
	v_mul_f32_e32 v141, 0xbfb8aa3b, v142
	v_exp_f32_e32 v141, v141
	v_pk_fma_f32 v[132:133], v[172:173], v[132:133], v[60:61] op_sel_hi:[0,1,1]
	v_pk_mul_f32 v[146:147], v[146:147], v[148:149]
	v_pk_fma_f32 v[128:129], v[48:49], v[170:171], v[128:129] op_sel_hi:[1,0,1] neg_lo:[1,0,0] neg_hi:[1,0,0]
	v_add_f32_e32 v141, 1.0, v141
	v_pk_mul_f32 v[136:137], v[136:137], v[146:147]
	v_rcp_f32_e32 v146, v141
	v_mul_f32_e32 v141, 0xbfb8aa3b, v143
	v_exp_f32_e32 v141, v141
	v_cvt_pk_bf16_f32 v136, v136, v137
	v_pk_fma_f32 v[128:129], v[172:173], v[128:129], v[52:53] op_sel_hi:[0,1,1]
	v_pk_fma_f32 v[130:131], v[50:51], v[170:171], v[130:131] op_sel_hi:[1,0,1] neg_lo:[1,0,0] neg_hi:[1,0,0]
	v_add_f32_e32 v141, 1.0, v141
	v_rcp_f32_e32 v147, v141
	v_pk_fma_f32 v[130:131], v[172:173], v[130:131], v[54:55] op_sel_hi:[0,1,1]
	v_mov_b32_e32 v140, 1.0
	s_and_b64 vcc, exec, s[4:5]
	v_pk_mul_f32 v[142:143], v[142:143], v[146:147]
; __device__ __forceinline__ unsigned pk2(float lo, float hi) { const f32x2_t v = {lo, hi}; const bf16x2_t b = __builtin_convertvector(v, bf16x2_t); return __builtin_bit_cast(unsigned, b); }
;     __device__ __forceinline__ void operator()(const f32x4 (&acc)[2][2][4][2], const pg8::Unit& u, int wr, int wc, int fr, int fq) const {
;     ...
;         for (int ai = 0; ai < 2; ++ai)
; #pragma unroll
;             for (int m = 0; m < 4; ++m) {
;                 const int row = row0 + ai * 128 + m * 16; float mu, rstd; row_stats(stats, row, mu, rstd);
; #pragma unroll
;                 for (int n = 0; n < 2; ++n) {
;                     float hv[4];
; #pragma unroll
;                     for (int j = 0; j < 4; ++j) {
;                         const float gt = rstd * (acc[ai][0][m][n][j] - mu * c1g[n][j]) + c2g[n][j];
;                         const float up = rstd * (acc[ai][1][m][n][j] - mu * c1u[n][j]) + c2u[n][j];
;                         hv[j] = gt * __builtin_amdgcn_rcpf(1.f + __expf(-gt)) * up;
;                     }
;                     u32x2 w; w.x = pk2(hv[0], hv[1]); w.y = pk2(hv[2], hv[3]);
;                     *(u32x2*)(H + (size_t)row * FF_ + hcol0 + 16 * n) = w;
;                 }
	s_nop 0
	v_pk_mul_f32 v[138:139], v[138:139], v[142:143]
	s_nop 0
	v_cvt_pk_bf16_f32 v137, v138, v139
	v_mov_b64_e32 v[138:139], s[6:7]
	v_mad_i64_i32 v[138:139], s[26:27], v144, s19, v[138:139]
	v_lshl_add_u64 v[138:139], v[166:167], 1, v[138:139]
	global_store_dwordx2 v[138:139], v[136:137], off
	v_mul_f32_e32 v136, 0xbfb8aa3b, v132
	v_mul_f32_e32 v137, 0xbfb8aa3b, v133
	v_exp_f32_e32 v136, v136
	v_exp_f32_e32 v137, v137
	v_add_f32_e32 v136, 1.0, v136
	v_add_f32_e32 v137, 1.0, v137
	v_rcp_f32_e32 v136, v136
	v_rcp_f32_e32 v137, v137
	s_nop 0
	v_pk_mul_f32 v[132:133], v[132:133], v[136:137]
	s_nop 0
	v_pk_mul_f32 v[128:129], v[128:129], v[132:133]
	v_pk_fma_f32 v[132:133], v[58:59], v[170:171], v[134:135] op_sel_hi:[1,0,1] neg_lo:[1,0,0] neg_hi:[1,0,0]
	v_cvt_pk_bf16_f32 v128, v128, v129
	v_pk_fma_f32 v[132:133], v[172:173], v[132:133], v[62:63] op_sel_hi:[0,1,1]
	v_mul_f32_e32 v134, 0xbfb8aa3b, v132
	v_mul_f32_e32 v135, 0xbfb8aa3b, v133
	v_exp_f32_e32 v134, v134
	v_exp_f32_e32 v135, v135
	v_add_f32_e32 v134, 1.0, v134
	v_add_f32_e32 v135, 1.0, v135
	v_rcp_f32_e32 v134, v134
	v_rcp_f32_e32 v135, v135
	s_nop 0
	v_pk_mul_f32 v[132:133], v[132:133], v[134:135]
	s_nop 0
	v_pk_mul_f32 v[130:131], v[130:131], v[132:133]
	v_or_b32_e32 v134, 32, v168
	v_cvt_pk_bf16_f32 v129, v130, v131
	global_store_dwordx2 v[138:139], v[128:129], off offset:32
	v_ashrrev_i32_e32 v135, 31, v134
	v_mov_b32_e32 v128, 0
	v_mov_b32_e32 v130, 0
	v_mov_b32_e32 v132, 1.0
	s_cbranch_vccnz .LBB0_191
	v_mov_b32_e32 v130, v208
	v_mov_b32_e32 v131, v209
	v_mov_b32_e32 v132, v131
.LBB0_191:
	v_pk_fma_f32 v[124:125], v[72:73], v[130:131], v[124:125] op_sel_hi:[1,0,1] neg_lo:[1,0,0] neg_hi:[1,0,0]
	v_pk_fma_f32 v[120:121], v[76:77], v[130:131], v[120:121] op_sel_hi:[1,0,1] neg_lo:[1,0,0] neg_hi:[1,0,0]
	v_pk_fma_f32 v[124:125], v[132:133], v[124:125], v[84:85] op_sel_hi:[0,1,1]
	v_mul_f32_e32 v129, 0xbfb8aa3b, v124
	v_exp_f32_e32 v129, v129
	v_pk_fma_f32 v[120:121], v[132:133], v[120:121], v[80:81] op_sel_hi:[0,1,1]
	v_pk_fma_f32 v[122:123], v[78:79], v[130:131], v[122:123] op_sel_hi:[1,0,1] neg_lo:[1,0,0] neg_hi:[1,0,0]
	v_pk_fma_f32 v[116:117], v[56:57], v[130:131], v[116:117] op_sel_hi:[1,0,1] neg_lo:[1,0,0] neg_hi:[1,0,0]
	v_add_f32_e32 v129, 1.0, v129
	v_rcp_f32_e32 v136, v129
	v_mul_f32_e32 v129, 0xbfb8aa3b, v125
	v_exp_f32_e32 v129, v129
	v_pk_fma_f32 v[122:123], v[132:133], v[122:123], v[82:83] op_sel_hi:[0,1,1]
	v_pk_fma_f32 v[116:117], v[132:133], v[116:117], v[60:61] op_sel_hi:[0,1,1]
	v_pk_fma_f32 v[112:113], v[48:49], v[130:131], v[112:113] op_sel_hi:[1,0,1] neg_lo:[1,0,0] neg_hi:[1,0,0]
	v_add_f32_e32 v129, 1.0, v129
	v_rcp_f32_e32 v137, v129
	v_pk_fma_f32 v[112:113], v[132:133], v[112:113], v[52:53] op_sel_hi:[0,1,1]
	v_pk_fma_f32 v[114:115], v[50:51], v[130:131], v[114:115] op_sel_hi:[1,0,1] neg_lo:[1,0,0] neg_hi:[1,0,0]
	s_and_b64 vcc, exec, s[4:5]
	v_pk_mul_f32 v[124:125], v[124:125], v[136:137]
	v_pk_fma_f32 v[114:115], v[132:133], v[114:115], v[54:55] op_sel_hi:[0,1,1]
	v_pk_mul_f32 v[120:121], v[120:121], v[124:125]
	v_pk_fma_f32 v[124:125], v[74:75], v[130:131], v[126:127] op_sel_hi:[1,0,1] neg_lo:[1,0,0] neg_hi:[1,0,0]
	v_cvt_pk_bf16_f32 v120, v120, v121
	v_pk_fma_f32 v[124:125], v[132:133], v[124:125], v[86:87] op_sel_hi:[0,1,1]
	v_mul_f32_e32 v126, 0xbfb8aa3b, v124
	v_mul_f32_e32 v127, 0xbfb8aa3b, v125
	v_exp_f32_e32 v126, v126
	v_exp_f32_e32 v127, v127
	v_readlane_b32 s56, v254, 36
	v_readlane_b32 s57, v254, 37
	v_add_f32_e32 v126, 1.0, v126
	v_add_f32_e32 v127, 1.0, v127
	v_rcp_f32_e32 v126, v126
	v_rcp_f32_e32 v127, v127
	s_nop 0
	v_pk_mul_f32 v[124:125], v[124:125], v[126:127]
	s_nop 0
	v_pk_mul_f32 v[122:123], v[122:123], v[124:125]
	s_nop 0
	v_cvt_pk_bf16_f32 v121, v122, v123
	v_mov_b64_e32 v[122:123], s[6:7]
	v_mad_i64_i32 v[122:123], s[26:27], v134, s19, v[122:123]
	v_lshl_add_u64 v[122:123], v[166:167], 1, v[122:123]
	global_store_dwordx2 v[122:123], v[120:121], off
	v_mul_f32_e32 v120, 0xbfb8aa3b, v116
	v_mul_f32_e32 v121, 0xbfb8aa3b, v117
	v_exp_f32_e32 v120, v120
	v_exp_f32_e32 v121, v121
	v_add_f32_e32 v120, 1.0, v120
	v_add_f32_e32 v121, 1.0, v121
	v_rcp_f32_e32 v120, v120
	v_rcp_f32_e32 v121, v121
	s_nop 0
	v_pk_mul_f32 v[116:117], v[116:117], v[120:121]
	s_nop 0
	v_pk_mul_f32 v[112:113], v[112:113], v[116:117]
	v_pk_fma_f32 v[116:117], v[58:59], v[130:131], v[118:119] op_sel_hi:[1,0,1] neg_lo:[1,0,0] neg_hi:[1,0,0]
	v_cvt_pk_bf16_f32 v112, v112, v113
	v_pk_fma_f32 v[116:117], v[132:133], v[116:117], v[62:63] op_sel_hi:[0,1,1]
	v_mul_f32_e32 v118, 0xbfb8aa3b, v116
	v_mul_f32_e32 v119, 0xbfb8aa3b, v117
	v_exp_f32_e32 v118, v118
	v_exp_f32_e32 v119, v119
	v_add_f32_e32 v118, 1.0, v118
	v_add_f32_e32 v119, 1.0, v119
	v_rcp_f32_e32 v118, v118
	v_rcp_f32_e32 v119, v119
	s_nop 0
	v_pk_mul_f32 v[116:117], v[116:117], v[118:119]
	s_nop 0
	v_pk_mul_f32 v[114:115], v[114:115], v[116:117]
	s_nop 0
	v_cvt_pk_bf16_f32 v113, v114, v115
	global_store_dwordx2 v[122:123], v[112:113], off offset:32
	v_or_b32_e32 v112, 48, v168
	v_ashrrev_i32_e32 v113, 31, v112
	s_cbranch_vccnz .LBB0_193
	v_mov_b32_e32 v128, v210
	v_mov_b32_e32 v129, v211
	v_mov_b32_e32 v140, v129
; __device__ __forceinline__ unsigned pk2(float lo, float hi) { const f32x2_t v = {lo, hi}; const bf16x2_t b = __builtin_convertvector(v, bf16x2_t); return __builtin_bit_cast(unsigned, b); }
;     __device__ __forceinline__ void operator()(const f32x4 (&acc)[2][2][4][2], const pg8::Unit& u, int wr, int wc, int fr, int fq) const {
;     ...
;         for (int ai = 0; ai < 2; ++ai)
; #pragma unroll
;             for (int m = 0; m < 4; ++m) {
;                 const int row = row0 + ai * 128 + m * 16; float mu, rstd; row_stats(stats, row, mu, rstd);
; #pragma unroll
;                 for (int n = 0; n < 2; ++n) {
;                     float hv[4];
; #pragma unroll
;                     for (int j = 0; j < 4; ++j) {
;                         const float gt = rstd * (acc[ai][0][m][n][j] - mu * c1g[n][j]) + c2g[n][j];
;                         const float up = rstd * (acc[ai][1][m][n][j] - mu * c1u[n][j]) + c2u[n][j];
;                         hv[j] = gt * __builtin_amdgcn_rcpf(1.f + __expf(-gt)) * up;
;                     }
;                     u32x2 w; w.x = pk2(hv[0], hv[1]); w.y = pk2(hv[2], hv[3]);
;                     *(u32x2*)(H + (size_t)row * FF_ + hcol0 + 16 * n) = w;
;                 }
.LBB0_193:
	v_pk_fma_f32 v[108:109], v[72:73], v[128:129], v[108:109] op_sel_hi:[1,0,1] neg_lo:[1,0,0] neg_hi:[1,0,0]
	v_pk_fma_f32 v[110:111], v[74:75], v[128:129], v[110:111] op_sel_hi:[1,0,1] neg_lo:[1,0,0] neg_hi:[1,0,0]
	v_pk_fma_f32 v[114:115], v[140:141], v[108:109], v[84:85] op_sel_hi:[0,1,1]
	v_mul_f32_e32 v108, 0xbfb8aa3b, v114
	v_exp_f32_e32 v109, v108
	v_pk_fma_f32 v[110:111], v[140:141], v[110:111], v[86:87] op_sel_hi:[0,1,1]
	v_pk_fma_f32 v[104:105], v[76:77], v[128:129], v[104:105] op_sel_hi:[1,0,1] neg_lo:[1,0,0] neg_hi:[1,0,0]
	v_pk_fma_f32 v[106:107], v[78:79], v[128:129], v[106:107] op_sel_hi:[1,0,1] neg_lo:[1,0,0] neg_hi:[1,0,0]
	v_add_f32_e32 v109, 1.0, v109
	v_rcp_f32_e32 v116, v109
	v_mul_f32_e32 v109, 0xbfb8aa3b, v115
	v_exp_f32_e32 v109, v109
	v_pk_fma_f32 v[104:105], v[140:141], v[104:105], v[80:81] op_sel_hi:[0,1,1]
	v_pk_fma_f32 v[106:107], v[140:141], v[106:107], v[82:83] op_sel_hi:[0,1,1]
	v_pk_fma_f32 v[100:101], v[56:57], v[128:129], v[100:101] op_sel_hi:[1,0,1] neg_lo:[1,0,0] neg_hi:[1,0,0]
	v_add_f32_e32 v109, 1.0, v109
	v_rcp_f32_e32 v117, v109
	v_mul_f32_e32 v109, 0xbfb8aa3b, v110
	v_exp_f32_e32 v109, v109
	v_pk_fma_f32 v[100:101], v[140:141], v[100:101], v[60:61] op_sel_hi:[0,1,1]
	v_pk_mul_f32 v[114:115], v[114:115], v[116:117]
	v_pk_fma_f32 v[96:97], v[48:49], v[128:129], v[96:97] op_sel_hi:[1,0,1] neg_lo:[1,0,0] neg_hi:[1,0,0]
	v_add_f32_e32 v109, 1.0, v109
	v_pk_mul_f32 v[104:105], v[104:105], v[114:115]
	v_rcp_f32_e32 v114, v109
	v_mul_f32_e32 v109, 0xbfb8aa3b, v111
	v_exp_f32_e32 v109, v109
	v_cvt_pk_bf16_f32 v104, v104, v105
	v_pk_fma_f32 v[96:97], v[140:141], v[96:97], v[52:53] op_sel_hi:[0,1,1]
	v_pk_fma_f32 v[98:99], v[50:51], v[128:129], v[98:99] op_sel_hi:[1,0,1] neg_lo:[1,0,0] neg_hi:[1,0,0]
	v_add_f32_e32 v109, 1.0, v109
	v_rcp_f32_e32 v115, v109
	v_pk_fma_f32 v[98:99], v[140:141], v[98:99], v[54:55] op_sel_hi:[0,1,1]
	v_mov_b32_e32 v108, 1.0
	s_and_b64 vcc, exec, s[4:5]
	v_pk_mul_f32 v[110:111], v[110:111], v[114:115]
	s_nop 0
	v_pk_mul_f32 v[106:107], v[106:107], v[110:111]
	s_nop 0
	v_cvt_pk_bf16_f32 v105, v106, v107
	v_mov_b64_e32 v[106:107], s[6:7]
	v_mad_i64_i32 v[106:107], s[26:27], v112, s19, v[106:107]
	v_lshl_add_u64 v[106:107], v[166:167], 1, v[106:107]
	global_store_dwordx2 v[106:107], v[104:105], off
	v_mul_f32_e32 v104, 0xbfb8aa3b, v100
	v_mul_f32_e32 v105, 0xbfb8aa3b, v101
	v_exp_f32_e32 v104, v104
	v_exp_f32_e32 v105, v105
	v_add_f32_e32 v104, 1.0, v104
	v_add_f32_e32 v105, 1.0, v105
	v_rcp_f32_e32 v104, v104
	v_rcp_f32_e32 v105, v105
	s_nop 0
	v_pk_mul_f32 v[100:101], v[100:101], v[104:105]
	s_nop 0
	v_pk_mul_f32 v[96:97], v[96:97], v[100:101]
	v_pk_fma_f32 v[100:101], v[58:59], v[128:129], v[102:103] op_sel_hi:[1,0,1] neg_lo:[1,0,0] neg_hi:[1,0,0]
	v_cvt_pk_bf16_f32 v96, v96, v97
	v_pk_fma_f32 v[100:101], v[140:141], v[100:101], v[62:63] op_sel_hi:[0,1,1]
	v_mul_f32_e32 v102, 0xbfb8aa3b, v100
	v_mul_f32_e32 v103, 0xbfb8aa3b, v101
	v_exp_f32_e32 v102, v102
	v_exp_f32_e32 v103, v103
	v_add_f32_e32 v102, 1.0, v102
	v_add_f32_e32 v103, 1.0, v103
	v_rcp_f32_e32 v102, v102
	v_rcp_f32_e32 v103, v103
	s_nop 0
	v_pk_mul_f32 v[100:101], v[100:101], v[102:103]
	s_nop 0
	v_pk_mul_f32 v[98:99], v[98:99], v[100:101]
	v_add_u32_e32 v102, 0x80, v168
	v_cvt_pk_bf16_f32 v97, v98, v99
	global_store_dwordx2 v[106:107], v[96:97], off offset:32
	v_ashrrev_i32_e32 v103, 31, v102
	v_mov_b32_e32 v96, 0
	v_mov_b32_e32 v98, 0
	v_mov_b32_e32 v100, 1.0
	s_cbranch_vccnz .LBB0_195
	v_mov_b32_e32 v98, v212
	v_mov_b32_e32 v99, v213
	v_mov_b32_e32 v100, v99
.LBB0_195:
	v_pk_fma_f32 v[92:93], v[72:73], v[98:99], v[92:93] op_sel_hi:[1,0,1] neg_lo:[1,0,0] neg_hi:[1,0,0]
	v_pk_fma_f32 v[88:89], v[76:77], v[98:99], v[88:89] op_sel_hi:[1,0,1] neg_lo:[1,0,0] neg_hi:[1,0,0]
	v_pk_fma_f32 v[92:93], v[100:101], v[92:93], v[84:85] op_sel_hi:[0,1,1]
	v_mul_f32_e32 v97, 0xbfb8aa3b, v92
	v_exp_f32_e32 v97, v97
	v_pk_fma_f32 v[88:89], v[100:101], v[88:89], v[80:81] op_sel_hi:[0,1,1]
	v_pk_fma_f32 v[90:91], v[78:79], v[98:99], v[90:91] op_sel_hi:[1,0,1] neg_lo:[1,0,0] neg_hi:[1,0,0]
	v_pk_fma_f32 v[68:69], v[56:57], v[98:99], v[68:69] op_sel_hi:[1,0,1] neg_lo:[1,0,0] neg_hi:[1,0,0]
	v_add_f32_e32 v97, 1.0, v97
	v_rcp_f32_e32 v104, v97
	v_mul_f32_e32 v97, 0xbfb8aa3b, v93
	v_exp_f32_e32 v97, v97
	v_pk_fma_f32 v[90:91], v[100:101], v[90:91], v[82:83] op_sel_hi:[0,1,1]
	v_pk_fma_f32 v[68:69], v[100:101], v[68:69], v[60:61] op_sel_hi:[0,1,1]
	v_pk_fma_f32 v[64:65], v[48:49], v[98:99], v[64:65] op_sel_hi:[1,0,1] neg_lo:[1,0,0] neg_hi:[1,0,0]
	v_add_f32_e32 v97, 1.0, v97
	v_rcp_f32_e32 v105, v97
	v_pk_fma_f32 v[64:65], v[100:101], v[64:65], v[52:53] op_sel_hi:[0,1,1]
	v_pk_fma_f32 v[66:67], v[50:51], v[98:99], v[66:67] op_sel_hi:[1,0,1] neg_lo:[1,0,0] neg_hi:[1,0,0]
	s_and_b64 vcc, exec, s[4:5]
	v_pk_mul_f32 v[92:93], v[92:93], v[104:105]
	v_pk_fma_f32 v[66:67], v[100:101], v[66:67], v[54:55] op_sel_hi:[0,1,1]
	v_pk_mul_f32 v[88:89], v[88:89], v[92:93]
	v_pk_fma_f32 v[92:93], v[74:75], v[98:99], v[94:95] op_sel_hi:[1,0,1] neg_lo:[1,0,0] neg_hi:[1,0,0]
	v_cvt_pk_bf16_f32 v88, v88, v89
	v_pk_fma_f32 v[92:93], v[100:101], v[92:93], v[86:87] op_sel_hi:[0,1,1]
	v_mul_f32_e32 v94, 0xbfb8aa3b, v92
	v_mul_f32_e32 v95, 0xbfb8aa3b, v93
	v_exp_f32_e32 v94, v94
	v_exp_f32_e32 v95, v95
	v_add_f32_e32 v94, 1.0, v94
	v_add_f32_e32 v95, 1.0, v95
	v_rcp_f32_e32 v94, v94
	v_rcp_f32_e32 v95, v95
	s_nop 0
	v_pk_mul_f32 v[92:93], v[92:93], v[94:95]
	s_nop 0
	v_pk_mul_f32 v[90:91], v[90:91], v[92:93]
	s_nop 0
	v_cvt_pk_bf16_f32 v89, v90, v91
	v_mov_b64_e32 v[90:91], s[6:7]
	v_mad_i64_i32 v[90:91], s[26:27], v102, s19, v[90:91]
	v_lshl_add_u64 v[90:91], v[166:167], 1, v[90:91]
	global_store_dwordx2 v[90:91], v[88:89], off
	v_mul_f32_e32 v88, 0xbfb8aa3b, v68
	v_mul_f32_e32 v89, 0xbfb8aa3b, v69
	v_exp_f32_e32 v88, v88
	v_exp_f32_e32 v89, v89
	v_add_f32_e32 v88, 1.0, v88
	v_add_f32_e32 v89, 1.0, v89
	v_rcp_f32_e32 v88, v88
	v_rcp_f32_e32 v89, v89
	s_nop 0
	v_pk_mul_f32 v[68:69], v[68:69], v[88:89]
	s_nop 0
	v_pk_mul_f32 v[64:65], v[64:65], v[68:69]
	v_pk_fma_f32 v[68:69], v[58:59], v[98:99], v[70:71] op_sel_hi:[1,0,1] neg_lo:[1,0,0] neg_hi:[1,0,0]
	v_cvt_pk_bf16_f32 v64, v64, v65
	v_pk_fma_f32 v[68:69], v[100:101], v[68:69], v[62:63] op_sel_hi:[0,1,1]
	v_mul_f32_e32 v70, 0xbfb8aa3b, v68
	v_mul_f32_e32 v71, 0xbfb8aa3b, v69
	v_exp_f32_e32 v70, v70
	v_exp_f32_e32 v71, v71
	v_add_f32_e32 v70, 1.0, v70
	v_add_f32_e32 v71, 1.0, v71
	v_rcp_f32_e32 v70, v70
	v_rcp_f32_e32 v71, v71
	s_nop 0
	v_pk_mul_f32 v[68:69], v[68:69], v[70:71]
	s_nop 0
	v_pk_mul_f32 v[66:67], v[66:67], v[68:69]
	s_nop 0
	v_cvt_pk_bf16_f32 v65, v66, v67
	global_store_dwordx2 v[90:91], v[64:65], off offset:32
	v_add_u32_e32 v64, 0x90, v168
	v_ashrrev_i32_e32 v65, 31, v64
	s_cbranch_vccnz .LBB0_197
	v_mov_b32_e32 v96, v214
	v_mov_b32_e32 v97, v215
	v_mov_b32_e32 v108, v97
; __device__ __forceinline__ unsigned pk2(float lo, float hi) { const f32x2_t v = {lo, hi}; const bf16x2_t b = __builtin_convertvector(v, bf16x2_t); return __builtin_bit_cast(unsigned, b); }
;     __device__ __forceinline__ void operator()(const f32x4 (&acc)[2][2][4][2], const pg8::Unit& u, int wr, int wc, int fr, int fq) const {
;     ...
;         for (int ai = 0; ai < 2; ++ai)
; #pragma unroll
;             for (int m = 0; m < 4; ++m) {
;                 const int row = row0 + ai * 128 + m * 16; float mu, rstd; row_stats(stats, row, mu, rstd);
; #pragma unroll
;                 for (int n = 0; n < 2; ++n) {
;                     float hv[4];
; #pragma unroll
;                     for (int j = 0; j < 4; ++j) {
;                         const float gt = rstd * (acc[ai][0][m][n][j] - mu * c1g[n][j]) + c2g[n][j];
;                         const float up = rstd * (acc[ai][1][m][n][j] - mu * c1u[n][j]) + c2u[n][j];
;                         hv[j] = gt * __builtin_amdgcn_rcpf(1.f + __expf(-gt)) * up;
;                     }
;                     u32x2 w; w.x = pk2(hv[0], hv[1]); w.y = pk2(hv[2], hv[3]);
;                     *(u32x2*)(H + (size_t)row * FF_ + hcol0 + 16 * n) = w;
;                 }
.LBB0_197:
	v_pk_fma_f32 v[44:45], v[72:73], v[96:97], v[44:45] op_sel_hi:[1,0,1] neg_lo:[1,0,0] neg_hi:[1,0,0]
	v_pk_fma_f32 v[46:47], v[74:75], v[96:97], v[46:47] op_sel_hi:[1,0,1] neg_lo:[1,0,0] neg_hi:[1,0,0]
	v_pk_fma_f32 v[66:67], v[108:109], v[44:45], v[84:85] op_sel_hi:[0,1,1]
	v_mul_f32_e32 v44, 0xbfb8aa3b, v66
	v_exp_f32_e32 v45, v44
	v_pk_fma_f32 v[46:47], v[108:109], v[46:47], v[86:87] op_sel_hi:[0,1,1]
	v_pk_fma_f32 v[40:41], v[76:77], v[96:97], v[40:41] op_sel_hi:[1,0,1] neg_lo:[1,0,0] neg_hi:[1,0,0]
	v_pk_fma_f32 v[42:43], v[78:79], v[96:97], v[42:43] op_sel_hi:[1,0,1] neg_lo:[1,0,0] neg_hi:[1,0,0]
	v_add_f32_e32 v45, 1.0, v45
	v_rcp_f32_e32 v68, v45
	v_mul_f32_e32 v45, 0xbfb8aa3b, v67
	v_exp_f32_e32 v45, v45
	v_pk_fma_f32 v[40:41], v[108:109], v[40:41], v[80:81] op_sel_hi:[0,1,1]
	v_pk_fma_f32 v[42:43], v[108:109], v[42:43], v[82:83] op_sel_hi:[0,1,1]
	v_pk_fma_f32 v[36:37], v[56:57], v[96:97], v[36:37] op_sel_hi:[1,0,1] neg_lo:[1,0,0] neg_hi:[1,0,0]
	v_add_f32_e32 v45, 1.0, v45
	v_rcp_f32_e32 v69, v45
	v_mul_f32_e32 v45, 0xbfb8aa3b, v46
	v_exp_f32_e32 v45, v45
	v_pk_fma_f32 v[36:37], v[108:109], v[36:37], v[60:61] op_sel_hi:[0,1,1]
	v_pk_mul_f32 v[66:67], v[66:67], v[68:69]
	v_pk_fma_f32 v[32:33], v[48:49], v[96:97], v[32:33] op_sel_hi:[1,0,1] neg_lo:[1,0,0] neg_hi:[1,0,0]
	v_add_f32_e32 v45, 1.0, v45
	v_pk_mul_f32 v[40:41], v[40:41], v[66:67]
	v_rcp_f32_e32 v66, v45
	v_mul_f32_e32 v45, 0xbfb8aa3b, v47
	v_exp_f32_e32 v45, v45
	v_cvt_pk_bf16_f32 v40, v40, v41
	v_pk_fma_f32 v[32:33], v[108:109], v[32:33], v[52:53] op_sel_hi:[0,1,1]
	v_pk_fma_f32 v[34:35], v[50:51], v[96:97], v[34:35] op_sel_hi:[1,0,1] neg_lo:[1,0,0] neg_hi:[1,0,0]
	v_add_f32_e32 v45, 1.0, v45
	v_rcp_f32_e32 v67, v45
	v_pk_fma_f32 v[34:35], v[108:109], v[34:35], v[54:55] op_sel_hi:[0,1,1]
	v_mov_b32_e32 v44, 1.0
	s_and_b64 vcc, exec, s[4:5]
	v_pk_mul_f32 v[46:47], v[46:47], v[66:67]
	s_nop 0
	v_pk_mul_f32 v[42:43], v[42:43], v[46:47]
	s_nop 0
	v_cvt_pk_bf16_f32 v41, v42, v43
	v_mov_b64_e32 v[42:43], s[6:7]
	v_mad_i64_i32 v[42:43], s[26:27], v64, s19, v[42:43]
	v_lshl_add_u64 v[42:43], v[166:167], 1, v[42:43]
	global_store_dwordx2 v[42:43], v[40:41], off
	v_mul_f32_e32 v40, 0xbfb8aa3b, v36
	v_mul_f32_e32 v41, 0xbfb8aa3b, v37
	v_exp_f32_e32 v40, v40
	v_exp_f32_e32 v41, v41
	v_add_f32_e32 v40, 1.0, v40
	v_add_f32_e32 v41, 1.0, v41
	v_rcp_f32_e32 v40, v40
	v_rcp_f32_e32 v41, v41
	s_nop 0
	v_pk_mul_f32 v[36:37], v[36:37], v[40:41]
	s_nop 0
	v_pk_mul_f32 v[32:33], v[32:33], v[36:37]
	v_pk_fma_f32 v[36:37], v[58:59], v[96:97], v[38:39] op_sel_hi:[1,0,1] neg_lo:[1,0,0] neg_hi:[1,0,0]
	v_cvt_pk_bf16_f32 v32, v32, v33
	v_pk_fma_f32 v[36:37], v[108:109], v[36:37], v[62:63] op_sel_hi:[0,1,1]
	v_mul_f32_e32 v38, 0xbfb8aa3b, v36
	v_mul_f32_e32 v39, 0xbfb8aa3b, v37
	v_exp_f32_e32 v38, v38
	v_exp_f32_e32 v39, v39
	v_add_f32_e32 v38, 1.0, v38
	v_add_f32_e32 v39, 1.0, v39
	v_rcp_f32_e32 v38, v38
	v_rcp_f32_e32 v39, v39
	s_nop 0
	v_pk_mul_f32 v[36:37], v[36:37], v[38:39]
	s_nop 0
	v_pk_mul_f32 v[34:35], v[34:35], v[36:37]
	v_add_u32_e32 v38, 0xa0, v168
	v_cvt_pk_bf16_f32 v33, v34, v35
	global_store_dwordx2 v[42:43], v[32:33], off offset:32
	v_ashrrev_i32_e32 v39, 31, v38
	v_mov_b32_e32 v32, 0
	v_mov_b32_e32 v34, 0
	v_mov_b32_e32 v36, 1.0
	s_cbranch_vccnz .LBB0_199
	v_mov_b32_e32 v34, v216
	v_mov_b32_e32 v35, v217
	v_mov_b32_e32 v36, v35
.LBB0_199:
	v_pk_fma_f32 v[28:29], v[72:73], v[34:35], v[28:29] op_sel_hi:[1,0,1] neg_lo:[1,0,0] neg_hi:[1,0,0]
	v_pk_fma_f32 v[24:25], v[76:77], v[34:35], v[24:25] op_sel_hi:[1,0,1] neg_lo:[1,0,0] neg_hi:[1,0,0]
	v_pk_fma_f32 v[28:29], v[36:37], v[28:29], v[84:85] op_sel_hi:[0,1,1]
	v_mul_f32_e32 v33, 0xbfb8aa3b, v28
	v_exp_f32_e32 v33, v33
	v_pk_fma_f32 v[24:25], v[36:37], v[24:25], v[80:81] op_sel_hi:[0,1,1]
	v_pk_fma_f32 v[26:27], v[78:79], v[34:35], v[26:27] op_sel_hi:[1,0,1] neg_lo:[1,0,0] neg_hi:[1,0,0]
	v_pk_fma_f32 v[20:21], v[56:57], v[34:35], v[20:21] op_sel_hi:[1,0,1] neg_lo:[1,0,0] neg_hi:[1,0,0]
	v_add_f32_e32 v33, 1.0, v33
	v_rcp_f32_e32 v40, v33
	v_mul_f32_e32 v33, 0xbfb8aa3b, v29
	v_exp_f32_e32 v33, v33
	v_pk_fma_f32 v[26:27], v[36:37], v[26:27], v[82:83] op_sel_hi:[0,1,1]
	v_pk_fma_f32 v[20:21], v[36:37], v[20:21], v[60:61] op_sel_hi:[0,1,1]
	v_pk_fma_f32 v[16:17], v[48:49], v[34:35], v[16:17] op_sel_hi:[1,0,1] neg_lo:[1,0,0] neg_hi:[1,0,0]
	v_add_f32_e32 v33, 1.0, v33
	v_rcp_f32_e32 v41, v33
	v_pk_fma_f32 v[16:17], v[36:37], v[16:17], v[52:53] op_sel_hi:[0,1,1]
	v_pk_fma_f32 v[18:19], v[50:51], v[34:35], v[18:19] op_sel_hi:[1,0,1] neg_lo:[1,0,0] neg_hi:[1,0,0]
	s_and_b64 vcc, exec, s[4:5]
	v_pk_mul_f32 v[28:29], v[28:29], v[40:41]
	v_pk_fma_f32 v[18:19], v[36:37], v[18:19], v[54:55] op_sel_hi:[0,1,1]
	v_pk_mul_f32 v[24:25], v[24:25], v[28:29]
	v_pk_fma_f32 v[28:29], v[74:75], v[34:35], v[30:31] op_sel_hi:[1,0,1] neg_lo:[1,0,0] neg_hi:[1,0,0]
	v_cvt_pk_bf16_f32 v24, v24, v25
	v_pk_fma_f32 v[28:29], v[36:37], v[28:29], v[86:87] op_sel_hi:[0,1,1]
	v_mul_f32_e32 v30, 0xbfb8aa3b, v28
	v_mul_f32_e32 v31, 0xbfb8aa3b, v29
	v_exp_f32_e32 v30, v30
	v_exp_f32_e32 v31, v31
	v_add_f32_e32 v30, 1.0, v30
	v_add_f32_e32 v31, 1.0, v31
	v_rcp_f32_e32 v30, v30
	v_rcp_f32_e32 v31, v31
	s_nop 0
	v_pk_mul_f32 v[28:29], v[28:29], v[30:31]
	s_nop 0
	v_pk_mul_f32 v[26:27], v[26:27], v[28:29]
	s_nop 0
	v_cvt_pk_bf16_f32 v25, v26, v27
	v_mov_b64_e32 v[26:27], s[6:7]
	v_mad_i64_i32 v[26:27], s[26:27], v38, s19, v[26:27]
	v_lshl_add_u64 v[26:27], v[166:167], 1, v[26:27]
	global_store_dwordx2 v[26:27], v[24:25], off
	v_mul_f32_e32 v24, 0xbfb8aa3b, v20
	v_mul_f32_e32 v25, 0xbfb8aa3b, v21
	v_exp_f32_e32 v24, v24
	v_exp_f32_e32 v25, v25
	v_add_f32_e32 v24, 1.0, v24
	v_add_f32_e32 v25, 1.0, v25
	v_rcp_f32_e32 v24, v24
	v_rcp_f32_e32 v25, v25
	s_nop 0
	v_pk_mul_f32 v[20:21], v[20:21], v[24:25]
	s_nop 0
	v_pk_mul_f32 v[16:17], v[16:17], v[20:21]
	v_pk_fma_f32 v[20:21], v[58:59], v[34:35], v[22:23] op_sel_hi:[1,0,1] neg_lo:[1,0,0] neg_hi:[1,0,0]
	v_cvt_pk_bf16_f32 v16, v16, v17
	v_pk_fma_f32 v[20:21], v[36:37], v[20:21], v[62:63] op_sel_hi:[0,1,1]
	v_mul_f32_e32 v22, 0xbfb8aa3b, v20
	v_mul_f32_e32 v23, 0xbfb8aa3b, v21
	v_exp_f32_e32 v22, v22
	v_exp_f32_e32 v23, v23
	v_add_f32_e32 v22, 1.0, v22
	v_add_f32_e32 v23, 1.0, v23
	v_rcp_f32_e32 v22, v22
	v_rcp_f32_e32 v23, v23
	s_nop 0
	v_pk_mul_f32 v[20:21], v[20:21], v[22:23]
	s_nop 0
	v_pk_mul_f32 v[18:19], v[18:19], v[20:21]
	s_nop 0
	v_cvt_pk_bf16_f32 v17, v18, v19
	global_store_dwordx2 v[26:27], v[16:17], off offset:32
	v_add_u32_e32 v16, 0xb0, v168
	v_ashrrev_i32_e32 v17, 31, v16
	s_cbranch_vccnz .LBB0_180
	v_mov_b32_e32 v32, v218
	v_mov_b32_e32 v33, v219
	v_mov_b32_e32 v44, v33
	s_branch .LBB0_180

;     __device__ __forceinline__ void operator()(const f32x4 (&acc)[2][2][4][2], const pg8::Unit& u, int wr, int wc, int fr, int fq) const {
;         const int row0 = u.pm * 256 + wr * 64 + fr, cc0 = wc * 32 + 4 * fq, pn = u.pn;
;         const float* c1p = c1 + pn * 256 + cc0; const float* c2p = c2 + pn * 256 + cc0;
;         const bool isv = (pn == 2 || pn == 5);
;         bf16_t* dst; unsigned ld;
;         if (pn < 2) { dst = QK + pn * 256; ld = 1024; }
;         else if (pn == 3 || pn == 4) { dst = QK + (pn - 1) * 256; ld = 1024; }
;         else if (pn >= 12) { dst = Z + (pn - 12) * 256; ld = 512; }
;         else if (isv) { dst = VT + (size_t)(pn == 5 ? 16 : 0) * 64 * 4096; ld = 0; }
;         else { dst = PC + (pn - 6) * 256; ld = 1536; }
; #pragma unroll 1
;         for (int ai = 0; ai < 2; ++ai)
; #pragma unroll
;             for (int m = 0; m < 4; ++m) {
;                 const int row = row0 + ai * 128 + m * 16; float mu, rstd; row_stats(stats, row, mu, rstd);
;                 const unsigned vrow = (unsigned)(row >> 12) * (4u * 64u * 4096u) + (unsigned)(row & 4095);
; #pragma unroll
;                 for (int bj = 0; bj < 2; ++bj)
; #pragma unroll
;                     for (int n = 0; n < 2; ++n) {
;                         const int cc = bj * 128 + n * 16;
;                         const f32x4 c1q = *(const f32x4*)(c1p + cc), c2q = *(const f32x4*)(c2p + cc);
.LBB0_1288:
	s_lshl_b64 s[20:21], s[20:21], 2
	v_lshl_add_u64 v[148:149], v[140:141], 0, s[20:21]
	v_lshl_add_u64 v[150:151], v[142:143], 0, s[20:21]
	v_lshl_add_u32 v170, s4, 8, v162
	s_lshl_b32 s13, s11, 4
	s_mov_b32 s4, 0
	s_mov_b64 s[22:23], -1
	global_load_dwordx4 v[204:207], v[148:149], off
	global_load_dwordx4 v[208:211], v[150:151], off
	global_load_dwordx4 v[212:215], v[148:149], off offset:64
	global_load_dwordx4 v[216:219], v[150:151], off offset:64
	global_load_dwordx4 v[220:223], v[148:149], off offset:512
	global_load_dwordx4 v[224:227], v[150:151], off offset:512
	global_load_dwordx4 v[228:231], v[148:149], off offset:576
	global_load_dwordx4 v[232:235], v[150:151], off offset:576
	s_waitcnt vmcnt(0)
	s_branch .LBB0_1290

; __device__ __forceinline__ unsigned pk2(float lo, float hi) { const f32x2_t v = {lo, hi}; const bf16x2_t b = __builtin_convertvector(v, bf16x2_t); return __builtin_bit_cast(unsigned, b); }
;     __device__ __forceinline__ void operator()(const f32x4 (&acc)[2][2][4][2], const pg8::Unit& u, int wr, int wc, int fr, int fq) const {
;     ...
;                 const int row = row0 + ai * 128 + m * 16; float mu, rstd; row_stats(stats, row, mu, rstd);
;                 const unsigned vrow = (unsigned)(row >> 12) * (4u * 64u * 4096u) + (unsigned)(row & 4095);
; #pragma unroll
;                 for (int bj = 0; bj < 2; ++bj)
; #pragma unroll
;                     for (int n = 0; n < 2; ++n) {
;                         const int cc = bj * 128 + n * 16;
;                         const f32x4 c1q = *(const f32x4*)(c1p + cc), c2q = *(const f32x4*)(c2p + cc);
;                         const f32x4 a4 = ai ? acc[1][bj][m][n] : acc[0][bj][m][n];
;                         const f32x4 v = (a4 - c1q * mu) * rstd + c2q;
;                         const unsigned w0 = pk2(v[0], v[1]), w1 = pk2(v[2], v[3]);
.LBB0_1293:
	v_mov_b64_e32 v[132:133], v[204:205]
	v_mov_b64_e32 v[134:135], v[206:207]
	v_mov_b64_e32 v[128:129], v[208:209]
	v_mov_b64_e32 v[130:131], v[210:211]
	s_xor_b64 s[20:21], s[22:23], -1
	s_cmp_lt_i32 s6, 5
	s_cbranch_scc1 .LBB0_1295
	s_cmp_lg_u32 s6, 5
	s_mov_b64 s[24:25], -1
	s_cselect_b64 s[26:27], -1, 0
	s_cbranch_execz .LBB0_1296
	s_branch .LBB0_1297

; __device__ __forceinline__ unsigned pk2(float lo, float hi) { const f32x2_t v = {lo, hi}; const bf16x2_t b = __builtin_convertvector(v, bf16x2_t); return __builtin_bit_cast(unsigned, b); }
;     __device__ __forceinline__ void operator()(const f32x4 (&acc)[2][2][4][2], const pg8::Unit& u, int wr, int wc, int fr, int fq) const {
;     ...
;                         const f32x4 c1q = *(const f32x4*)(c1p + cc), c2q = *(const f32x4*)(c2p + cc);
;                         const f32x4 a4 = ai ? acc[1][bj][m][n] : acc[0][bj][m][n];
;                         const f32x4 v = (a4 - c1q * mu) * rstd + c2q;
;                         const unsigned w0 = pk2(v[0], v[1]), w1 = pk2(v[2], v[3]);
;                         if (!isv) { u32x2 w; w.x = w0; w.y = w1; *(u32x2*)(dst + ((unsigned)row * ld + (unsigned)(cc0 + cc))) = w; }
.LBB0_1297:
	v_cndmask_b32_e64 v159, v95, v127, s[22:23]
	v_cndmask_b32_e64 v158, v94, v126, s[22:23]
	v_cndmask_b32_e64 v161, v93, v125, s[22:23]
	v_cndmask_b32_e64 v160, v92, v124, s[22:23]
	v_pk_fma_f32 v[132:133], v[156:157], v[132:133], v[160:161] op_sel_hi:[0,1,1] neg_lo:[1,0,0] neg_hi:[1,0,0]
	v_pk_fma_f32 v[134:135], v[156:157], v[134:135], v[158:159] op_sel_hi:[0,1,1] neg_lo:[1,0,0] neg_hi:[1,0,0]
	v_mul_lo_u32 v171, v152, s11
	v_pk_fma_f32 v[130:131], v[154:155], v[134:135], v[130:131] op_sel_hi:[0,1,1]
	v_pk_fma_f32 v[128:129], v[154:155], v[132:133], v[128:129] op_sel_hi:[0,1,1]
	v_or_b32_e32 v180, v171, v164
	v_cvt_pk_bf16_f32 v128, v128, v129
	s_andn2_b64 vcc, exec, s[26:27]
	v_cvt_pk_bf16_f32 v129, v130, v131
	s_cbranch_vccnz .LBB0_1299
	v_lshl_add_u64 v[130:131], v[180:181], 1, s[18:19]
	s_mov_b64 s[24:25], 0
	global_store_dwordx2 v[130:131], v[128:129], off

; __device__ __forceinline__ unsigned pk2(float lo, float hi) { const f32x2_t v = {lo, hi}; const bf16x2_t b = __builtin_convertvector(v, bf16x2_t); return __builtin_bit_cast(unsigned, b); }
;     __device__ __forceinline__ void operator()(const f32x4 (&acc)[2][2][4][2], const pg8::Unit& u, int wr, int wc, int fr, int fq) const {
;     ...
;                         const int cc = bj * 128 + n * 16;
;                         const f32x4 c1q = *(const f32x4*)(c1p + cc), c2q = *(const f32x4*)(c2p + cc);
;                         const f32x4 a4 = ai ? acc[1][bj][m][n] : acc[0][bj][m][n];
;                         const f32x4 v = (a4 - c1q * mu) * rstd + c2q;
;                         const unsigned w0 = pk2(v[0], v[1]), w1 = pk2(v[2], v[3]);
.LBB0_1301:
	v_mov_b64_e32 v[132:133], v[212:213]
	v_mov_b64_e32 v[134:135], v[214:215]
	s_nop 0
	v_mov_b64_e32 v[128:129], v[216:217]
	v_mov_b64_e32 v[130:131], v[218:219]
	v_mov_b32_e32 v157, v156
	v_mov_b32_e32 v155, v154
	s_cmp_lt_i32 s6, 5
	s_cbranch_scc1 .LBB0_1303
	s_cmp_lg_u32 s6, 5
	s_mov_b64 s[24:25], -1
	s_cselect_b64 s[26:27], -1, 0
	s_cbranch_execz .LBB0_1304
	s_branch .LBB0_1305

; __device__ __forceinline__ unsigned pk2(float lo, float hi) { const f32x2_t v = {lo, hi}; const bf16x2_t b = __builtin_convertvector(v, bf16x2_t); return __builtin_bit_cast(unsigned, b); }
;     __device__ __forceinline__ void operator()(const f32x4 (&acc)[2][2][4][2], const pg8::Unit& u, int wr, int wc, int fr, int fq) const {
;     ...
;                         const f32x4 c1q = *(const f32x4*)(c1p + cc), c2q = *(const f32x4*)(c2p + cc);
;                         const f32x4 a4 = ai ? acc[1][bj][m][n] : acc[0][bj][m][n];
;                         const f32x4 v = (a4 - c1q * mu) * rstd + c2q;
;                         const unsigned w0 = pk2(v[0], v[1]), w1 = pk2(v[2], v[3]);
;                         if (!isv) { u32x2 w; w.x = w0; w.y = w1; *(u32x2*)(dst + ((unsigned)row * ld + (unsigned)(cc0 + cc))) = w; }
;                         else {
;                             bf16_t* p = dst + (vrow + (unsigned)(cc0 + cc) * 4096u);
;                             p[0] = (bf16_t)(w0 & 0xffff); p[4096] = (bf16_t)(w0 >> 16); p[2 * 4096] = (bf16_t)(w1 & 0xffff); p[3 * 4096] = (bf16_t)(w1 >> 16);
;                         }
.LBB0_1305:
	v_cndmask_b32_e64 v159, v33, v1, s[22:23]
	v_cndmask_b32_e64 v158, v32, v0, s[22:23]
	v_pk_fma_f32 v[132:133], v[156:157], v[132:133], v[158:159] neg_lo:[1,0,0] neg_hi:[1,0,0]
	v_xor_b32_e32 v158, 0x80000000, v156
	v_cndmask_b32_e64 v173, v35, v3, s[22:23]
	v_cndmask_b32_e64 v172, v34, v2, s[22:23]
	v_mov_b32_e32 v159, v158
	v_pk_fma_f32 v[134:135], v[158:159], v[134:135], v[172:173]
	v_mov_b32_e32 v172, v154
	v_mov_b32_e32 v173, v154
	v_pk_fma_f32 v[130:131], v[172:173], v[134:135], v[130:131]
	v_pk_fma_f32 v[128:129], v[154:155], v[132:133], v[128:129]
	s_andn2_b64 vcc, exec, s[26:27]
	v_cvt_pk_bf16_f32 v128, v128, v129
	v_cvt_pk_bf16_f32 v129, v130, v131
	s_cbranch_vccz .LBB0_1309
	s_andn2_b64 vcc, exec, s[24:25]
	s_cbranch_vccz .LBB0_1310
.LBB0_1307:
	v_mov_b64_e32 v[132:133], v[220:221]
	v_mov_b64_e32 v[134:135], v[222:223]
	v_mov_b64_e32 v[128:129], v[224:225]
	v_mov_b64_e32 v[130:131], v[226:227]
	s_cmp_lt_i32 s6, 5
	s_cbranch_scc1 .LBB0_1311

;     __device__ __forceinline__ void operator()(const f32x4 (&acc)[2][2][4][2], const pg8::Unit& u, int wr, int wc, int fr, int fq) const {
;     ...
;                         else {
;                             bf16_t* p = dst + (vrow + (unsigned)(cc0 + cc) * 4096u);
;                             p[0] = (bf16_t)(w0 & 0xffff); p[4096] = (bf16_t)(w0 >> 16); p[2 * 4096] = (bf16_t)(w1 & 0xffff); p[3 * 4096] = (bf16_t)(w1 >> 16);
;                         }
.LBB0_1310:
	v_or_b32_e32 v130, v160, v166
	v_mov_b32_e32 v131, v181
	v_lshl_add_u64 v[130:131], v[130:131], 1, s[18:19]
	v_add_co_u32_e32 v132, vcc, 0x2000, v130
	global_store_short v[130:131], v128, off
	s_nop 0
	v_addc_co_u32_e32 v133, vcc, 0, v131, vcc
	global_store_short_d16_hi v[132:133], v128, off
	v_add_co_u32_e32 v132, vcc, 0x4000, v130
	s_nop 1
	v_addc_co_u32_e32 v133, vcc, 0, v131, vcc
	v_add_co_u32_e32 v130, vcc, 0x6000, v130
	global_store_short v[132:133], v129, off
	s_nop 0
	v_addc_co_u32_e32 v131, vcc, 0, v131, vcc
	global_store_short_d16_hi v[130:131], v129, off
	v_mov_b64_e32 v[132:133], v[220:221]
	v_mov_b64_e32 v[134:135], v[222:223]
	s_nop 0
	v_mov_b64_e32 v[128:129], v[224:225]
	v_mov_b64_e32 v[130:131], v[226:227]
	s_cmp_lt_i32 s6, 5
	s_cbranch_scc0 .LBB0_1308

; __device__ __forceinline__ unsigned pk2(float lo, float hi) { const f32x2_t v = {lo, hi}; const bf16x2_t b = __builtin_convertvector(v, bf16x2_t); return __builtin_bit_cast(unsigned, b); }
;     __device__ __forceinline__ void operator()(const f32x4 (&acc)[2][2][4][2], const pg8::Unit& u, int wr, int wc, int fr, int fq) const {
;     ...
;                         const f32x4 c1q = *(const f32x4*)(c1p + cc), c2q = *(const f32x4*)(c2p + cc);
;                         const f32x4 a4 = ai ? acc[1][bj][m][n] : acc[0][bj][m][n];
;                         const f32x4 v = (a4 - c1q * mu) * rstd + c2q;
;                         const unsigned w0 = pk2(v[0], v[1]), w1 = pk2(v[2], v[3]);
;                         if (!isv) { u32x2 w; w.x = w0; w.y = w1; *(u32x2*)(dst + ((unsigned)row * ld + (unsigned)(cc0 + cc))) = w; }
;                         else {
;                             bf16_t* p = dst + (vrow + (unsigned)(cc0 + cc) * 4096u);
;                             p[0] = (bf16_t)(w0 & 0xffff); p[4096] = (bf16_t)(w0 >> 16); p[2 * 4096] = (bf16_t)(w1 & 0xffff); p[3 * 4096] = (bf16_t)(w1 >> 16);
;                         }
.LBB0_1313:
	v_cndmask_b32_e64 v173, v79, v111, s[22:23]
	v_cndmask_b32_e64 v172, v78, v110, s[22:23]
	v_cndmask_b32_e64 v175, v77, v109, s[22:23]
	v_cndmask_b32_e64 v174, v76, v108, s[22:23]
	v_mov_b32_e32 v159, v158
	v_pk_fma_f32 v[132:133], v[156:157], v[132:133], v[174:175] neg_lo:[1,0,0] neg_hi:[1,0,0]
	v_pk_fma_f32 v[134:135], v[158:159], v[134:135], v[172:173]
	v_mov_b32_e32 v172, v154
	v_mov_b32_e32 v173, v154
	v_pk_fma_f32 v[130:131], v[172:173], v[134:135], v[130:131]
	v_pk_fma_f32 v[128:129], v[154:155], v[132:133], v[128:129]
	s_andn2_b64 vcc, exec, s[26:27]
	v_cvt_pk_bf16_f32 v128, v128, v129
	v_cvt_pk_bf16_f32 v129, v130, v131
	s_cbranch_vccz .LBB0_1317
	s_andn2_b64 vcc, exec, s[24:25]
	s_cbranch_vccz .LBB0_1318
.LBB0_1315:
	v_mov_b64_e32 v[132:133], v[228:229]
	v_mov_b64_e32 v[134:135], v[230:231]
	v_mov_b64_e32 v[128:129], v[232:233]
	v_mov_b64_e32 v[130:131], v[234:235]
	s_cmp_lt_i32 s6, 5
	s_cbranch_scc1 .LBB0_1319

;     __device__ __forceinline__ void operator()(const f32x4 (&acc)[2][2][4][2], const pg8::Unit& u, int wr, int wc, int fr, int fq) const {
;     ...
;                         else {
;                             bf16_t* p = dst + (vrow + (unsigned)(cc0 + cc) * 4096u);
;                             p[0] = (bf16_t)(w0 & 0xffff); p[4096] = (bf16_t)(w0 >> 16); p[2 * 4096] = (bf16_t)(w1 & 0xffff); p[3 * 4096] = (bf16_t)(w1 >> 16);
;                         }
.LBB0_1318:
	v_or_b32_e32 v130, v160, v167
	v_mov_b32_e32 v131, v181
	v_lshl_add_u64 v[130:131], v[130:131], 1, s[18:19]
	v_add_co_u32_e32 v132, vcc, 0x2000, v130
	global_store_short v[130:131], v128, off
	s_nop 0
	v_addc_co_u32_e32 v133, vcc, 0, v131, vcc
	global_store_short_d16_hi v[132:133], v128, off
	v_add_co_u32_e32 v132, vcc, 0x4000, v130
	s_nop 1
	v_addc_co_u32_e32 v133, vcc, 0, v131, vcc
	v_add_co_u32_e32 v130, vcc, 0x6000, v130
	global_store_short v[132:133], v129, off
	s_nop 0
	v_addc_co_u32_e32 v131, vcc, 0, v131, vcc
	global_store_short_d16_hi v[130:131], v129, off
	v_mov_b64_e32 v[132:133], v[228:229]
	v_mov_b64_e32 v[134:135], v[230:231]
	s_nop 0
	v_mov_b64_e32 v[128:129], v[232:233]
	v_mov_b64_e32 v[130:131], v[234:235]
	s_cmp_lt_i32 s6, 5
	s_cbranch_scc0 .LBB0_1316

; __device__ __forceinline__ unsigned pk2(float lo, float hi) { const f32x2_t v = {lo, hi}; const bf16x2_t b = __builtin_convertvector(v, bf16x2_t); return __builtin_bit_cast(unsigned, b); }
;     __device__ __forceinline__ void operator()(const f32x4 (&acc)[2][2][4][2], const pg8::Unit& u, int wr, int wc, int fr, int fq) const {
;     ...
;                         const f32x4 c1q = *(const f32x4*)(c1p + cc), c2q = *(const f32x4*)(c2p + cc);
;                         const f32x4 a4 = ai ? acc[1][bj][m][n] : acc[0][bj][m][n];
;                         const f32x4 v = (a4 - c1q * mu) * rstd + c2q;
;                         const unsigned w0 = pk2(v[0], v[1]), w1 = pk2(v[2], v[3]);
;                         if (!isv) { u32x2 w; w.x = w0; w.y = w1; *(u32x2*)(dst + ((unsigned)row * ld + (unsigned)(cc0 + cc))) = w; }
.LBB0_1321:
	v_cndmask_b32_e64 v173, v51, v19, s[22:23]
	v_cndmask_b32_e64 v172, v50, v18, s[22:23]
	v_cndmask_b32_e64 v175, v49, v17, s[22:23]
	v_cndmask_b32_e64 v174, v48, v16, s[22:23]
	v_mov_b32_e32 v159, v158
	v_pk_fma_f32 v[132:133], v[156:157], v[132:133], v[174:175] neg_lo:[1,0,0] neg_hi:[1,0,0]
	v_pk_fma_f32 v[134:135], v[158:159], v[134:135], v[172:173]
	v_mov_b32_e32 v156, v154
	v_mov_b32_e32 v157, v154
	v_pk_fma_f32 v[130:131], v[156:157], v[134:135], v[130:131]
	v_pk_fma_f32 v[128:129], v[154:155], v[132:133], v[128:129]
	s_andn2_b64 vcc, exec, s[26:27]
	v_cvt_pk_bf16_f32 v128, v128, v129
	v_cvt_pk_bf16_f32 v129, v130, v131
	s_cbranch_vccz .LBB0_1326
	s_andn2_b64 vcc, exec, s[24:25]
	s_cbranch_vccz .LBB0_1327

; __device__ __forceinline__ unsigned pk2(float lo, float hi) { const f32x2_t v = {lo, hi}; const bf16x2_t b = __builtin_convertvector(v, bf16x2_t); return __builtin_bit_cast(unsigned, b); }
;     __device__ __forceinline__ void operator()(const f32x4 (&acc)[2][2][4][2], const pg8::Unit& u, int wr, int wc, int fr, int fq) const {
;     ...
;                 const int row = row0 + ai * 128 + m * 16; float mu, rstd; row_stats(stats, row, mu, rstd);
;                 const unsigned vrow = (unsigned)(row >> 12) * (4u * 64u * 4096u) + (unsigned)(row & 4095);
; #pragma unroll
;                 for (int bj = 0; bj < 2; ++bj)
; #pragma unroll
;                     for (int n = 0; n < 2; ++n) {
;                         const int cc = bj * 128 + n * 16;
;                         const f32x4 c1q = *(const f32x4*)(c1p + cc), c2q = *(const f32x4*)(c2p + cc);
;                         const f32x4 a4 = ai ? acc[1][bj][m][n] : acc[0][bj][m][n];
;                         const f32x4 v = (a4 - c1q * mu) * rstd + c2q;
;                         const unsigned w0 = pk2(v[0], v[1]), w1 = pk2(v[2], v[3]);
.LBB0_1324:
	v_ashrrev_i32_e32 v161, 31, v160
	v_lshl_add_u64 v[128:129], v[160:161], 3, s[54:55]
	global_load_dwordx2 v[156:157], v[128:129], off
	s_waitcnt vmcnt(0)
	v_mov_b32_e32 v154, v157
	v_mov_b64_e32 v[132:133], v[204:205]
	v_mov_b64_e32 v[134:135], v[206:207]
	v_mov_b64_e32 v[128:129], v[208:209]
	v_mov_b64_e32 v[130:131], v[210:211]
	s_cmp_lt_i32 s6, 5
	s_cbranch_scc1 .LBB0_1329

; __device__ __forceinline__ unsigned pk2(float lo, float hi) { const f32x2_t v = {lo, hi}; const bf16x2_t b = __builtin_convertvector(v, bf16x2_t); return __builtin_bit_cast(unsigned, b); }
;     __device__ __forceinline__ void operator()(const f32x4 (&acc)[2][2][4][2], const pg8::Unit& u, int wr, int wc, int fr, int fq) const {
;     ...
;                 const int row = row0 + ai * 128 + m * 16; float mu, rstd; row_stats(stats, row, mu, rstd);
;                 const unsigned vrow = (unsigned)(row >> 12) * (4u * 64u * 4096u) + (unsigned)(row & 4095);
; #pragma unroll
;                 for (int bj = 0; bj < 2; ++bj)
; #pragma unroll
;                     for (int n = 0; n < 2; ++n) {
;                         const int cc = bj * 128 + n * 16;
;                         const f32x4 c1q = *(const f32x4*)(c1p + cc), c2q = *(const f32x4*)(c2p + cc);
;                         const f32x4 a4 = ai ? acc[1][bj][m][n] : acc[0][bj][m][n];
;                         const f32x4 v = (a4 - c1q * mu) * rstd + c2q;
;                         const unsigned w0 = pk2(v[0], v[1]), w1 = pk2(v[2], v[3]);
.LBB0_1328:
	v_mov_b32_e32 v154, 1.0
	v_mov_b32_e32 v156, 0
	v_mov_b64_e32 v[132:133], v[204:205]
	v_mov_b64_e32 v[134:135], v[206:207]
	v_mov_b64_e32 v[128:129], v[208:209]
	v_mov_b64_e32 v[130:131], v[210:211]
	s_cmp_lt_i32 s6, 5
	s_cbranch_scc0 .LBB0_1325

; __device__ __forceinline__ unsigned pk2(float lo, float hi) { const f32x2_t v = {lo, hi}; const bf16x2_t b = __builtin_convertvector(v, bf16x2_t); return __builtin_bit_cast(unsigned, b); }
;     __device__ __forceinline__ void operator()(const f32x4 (&acc)[2][2][4][2], const pg8::Unit& u, int wr, int wc, int fr, int fq) const {
;     ...
;                         const f32x4 c1q = *(const f32x4*)(c1p + cc), c2q = *(const f32x4*)(c2p + cc);
;                         const f32x4 a4 = ai ? acc[1][bj][m][n] : acc[0][bj][m][n];
;                         const f32x4 v = (a4 - c1q * mu) * rstd + c2q;
;                         const unsigned w0 = pk2(v[0], v[1]), w1 = pk2(v[2], v[3]);
;                         if (!isv) { u32x2 w; w.x = w0; w.y = w1; *(u32x2*)(dst + ((unsigned)row * ld + (unsigned)(cc0 + cc))) = w; }
.LBB0_1331:
	v_cndmask_b32_e64 v173, v91, v123, s[22:23]
	v_cndmask_b32_e64 v172, v90, v122, s[22:23]
	v_cndmask_b32_e64 v175, v89, v121, s[22:23]
	v_cndmask_b32_e64 v174, v88, v120, s[22:23]
	v_pk_fma_f32 v[132:133], v[156:157], v[132:133], v[174:175] op_sel_hi:[0,1,1] neg_lo:[1,0,0] neg_hi:[1,0,0]
	v_pk_fma_f32 v[134:135], v[156:157], v[134:135], v[172:173] op_sel_hi:[0,1,1] neg_lo:[1,0,0] neg_hi:[1,0,0]
	v_add_u32_e32 v171, s13, v171
	v_pk_fma_f32 v[130:131], v[154:155], v[134:135], v[130:131] op_sel_hi:[0,1,1]
	v_pk_fma_f32 v[128:129], v[154:155], v[132:133], v[128:129] op_sel_hi:[0,1,1]
	v_or_b32_e32 v158, v171, v164
	v_cvt_pk_bf16_f32 v128, v128, v129
	s_andn2_b64 vcc, exec, s[26:27]
	v_cvt_pk_bf16_f32 v129, v130, v131
	s_cbranch_vccnz .LBB0_1333
	v_mov_b32_e32 v159, v181
	v_lshl_add_u64 v[130:131], v[158:159], 1, s[18:19]
	global_store_dwordx2 v[130:131], v[128:129], off
	s_mov_b64 s[24:25], 0

; __device__ __forceinline__ unsigned pk2(float lo, float hi) { const f32x2_t v = {lo, hi}; const bf16x2_t b = __builtin_convertvector(v, bf16x2_t); return __builtin_bit_cast(unsigned, b); }
;     __device__ __forceinline__ void operator()(const f32x4 (&acc)[2][2][4][2], const pg8::Unit& u, int wr, int wc, int fr, int fq) const {
;     ...
;                         const f32x4 c1q = *(const f32x4*)(c1p + cc), c2q = *(const f32x4*)(c2p + cc);
;                         const f32x4 a4 = ai ? acc[1][bj][m][n] : acc[0][bj][m][n];
;                         const f32x4 v = (a4 - c1q * mu) * rstd + c2q;
;                         const unsigned w0 = pk2(v[0], v[1]), w1 = pk2(v[2], v[3]);
;                         if (!isv) { u32x2 w; w.x = w0; w.y = w1; *(u32x2*)(dst + ((unsigned)row * ld + (unsigned)(cc0 + cc))) = w; }
.LBB0_1339:
	v_cndmask_b32_e64 v161, v37, v5, s[22:23]
	v_cndmask_b32_e64 v160, v36, v4, s[22:23]
	v_pk_fma_f32 v[132:133], v[156:157], v[132:133], v[160:161] neg_lo:[1,0,0] neg_hi:[1,0,0]
	v_xor_b32_e32 v160, 0x80000000, v156
	v_cndmask_b32_e64 v175, v39, v7, s[22:23]
	v_cndmask_b32_e64 v174, v38, v6, s[22:23]
	v_mov_b32_e32 v161, v160
	v_pk_fma_f32 v[134:135], v[160:161], v[134:135], v[174:175]
	v_mov_b32_e32 v174, v154
	v_mov_b32_e32 v175, v154
	v_pk_fma_f32 v[130:131], v[174:175], v[134:135], v[130:131]
	v_pk_fma_f32 v[128:129], v[154:155], v[132:133], v[128:129]
	s_andn2_b64 vcc, exec, s[26:27]
	v_cvt_pk_bf16_f32 v128, v128, v129
	v_cvt_pk_bf16_f32 v129, v130, v131
	s_cbranch_vccz .LBB0_1343
	s_andn2_b64 vcc, exec, s[24:25]
	s_cbranch_vccz .LBB0_1344

;     __device__ __forceinline__ void operator()(const f32x4 (&acc)[2][2][4][2], const pg8::Unit& u, int wr, int wc, int fr, int fq) const {
;     ...
;                         else {
;                             bf16_t* p = dst + (vrow + (unsigned)(cc0 + cc) * 4096u);
;                             p[0] = (bf16_t)(w0 & 0xffff); p[4096] = (bf16_t)(w0 >> 16); p[2 * 4096] = (bf16_t)(w1 & 0xffff); p[3 * 4096] = (bf16_t)(w1 >> 16);
;                         }
.LBB0_1344:
	v_or_b32_e32 v180, v172, v166
	v_lshl_add_u64 v[130:131], v[180:181], 1, s[18:19]
	v_add_co_u32_e32 v132, vcc, 0x2000, v130
	global_store_short v[130:131], v128, off
	s_nop 0
	v_addc_co_u32_e32 v133, vcc, 0, v131, vcc
	global_store_short_d16_hi v[132:133], v128, off
	v_add_co_u32_e32 v132, vcc, 0x4000, v130
	s_nop 1
	v_addc_co_u32_e32 v133, vcc, 0, v131, vcc
	v_add_co_u32_e32 v130, vcc, 0x6000, v130
	global_store_short v[132:133], v129, off
	s_nop 0
	v_addc_co_u32_e32 v131, vcc, 0, v131, vcc
	global_store_short_d16_hi v[130:131], v129, off
	v_mov_b64_e32 v[132:133], v[220:221]
	v_mov_b64_e32 v[134:135], v[222:223]
	s_nop 0
	v_mov_b64_e32 v[128:129], v[224:225]
	v_mov_b64_e32 v[130:131], v[226:227]
	s_cmp_lt_i32 s6, 5
	s_cbranch_scc0 .LBB0_1342

; __device__ __forceinline__ unsigned pk2(float lo, float hi) { const f32x2_t v = {lo, hi}; const bf16x2_t b = __builtin_convertvector(v, bf16x2_t); return __builtin_bit_cast(unsigned, b); }
;     __device__ __forceinline__ void operator()(const f32x4 (&acc)[2][2][4][2], const pg8::Unit& u, int wr, int wc, int fr, int fq) const {
;     ...
;                         const f32x4 c1q = *(const f32x4*)(c1p + cc), c2q = *(const f32x4*)(c2p + cc);
;                         const f32x4 a4 = ai ? acc[1][bj][m][n] : acc[0][bj][m][n];
;                         const f32x4 v = (a4 - c1q * mu) * rstd + c2q;
;                         const unsigned w0 = pk2(v[0], v[1]), w1 = pk2(v[2], v[3]);
;                         if (!isv) { u32x2 w; w.x = w0; w.y = w1; *(u32x2*)(dst + ((unsigned)row * ld + (unsigned)(cc0 + cc))) = w; }
.LBB0_1347:
	v_cndmask_b32_e64 v175, v75, v107, s[22:23]
	v_cndmask_b32_e64 v174, v74, v106, s[22:23]
	v_cndmask_b32_e64 v177, v73, v105, s[22:23]
	v_cndmask_b32_e64 v176, v72, v104, s[22:23]
	v_mov_b32_e32 v161, v160
	v_pk_fma_f32 v[132:133], v[156:157], v[132:133], v[176:177] neg_lo:[1,0,0] neg_hi:[1,0,0]
	v_pk_fma_f32 v[134:135], v[160:161], v[134:135], v[174:175]
	v_mov_b32_e32 v174, v154
	v_mov_b32_e32 v175, v154
	v_pk_fma_f32 v[130:131], v[174:175], v[134:135], v[130:131]
	v_pk_fma_f32 v[128:129], v[154:155], v[132:133], v[128:129]
	s_andn2_b64 vcc, exec, s[26:27]
	v_cvt_pk_bf16_f32 v128, v128, v129
	v_cvt_pk_bf16_f32 v129, v130, v131
	s_cbranch_vccz .LBB0_1351
	s_andn2_b64 vcc, exec, s[24:25]
	s_cbranch_vccz .LBB0_1352

;     __device__ __forceinline__ void operator()(const f32x4 (&acc)[2][2][4][2], const pg8::Unit& u, int wr, int wc, int fr, int fq) const {
;     ...
;                         else {
;                             bf16_t* p = dst + (vrow + (unsigned)(cc0 + cc) * 4096u);
;                             p[0] = (bf16_t)(w0 & 0xffff); p[4096] = (bf16_t)(w0 >> 16); p[2 * 4096] = (bf16_t)(w1 & 0xffff); p[3 * 4096] = (bf16_t)(w1 >> 16);
;                         }
.LBB0_1352:
	v_or_b32_e32 v180, v172, v167
	v_lshl_add_u64 v[130:131], v[180:181], 1, s[18:19]
	v_add_co_u32_e32 v132, vcc, 0x2000, v130
	global_store_short v[130:131], v128, off
	s_nop 0
	v_addc_co_u32_e32 v133, vcc, 0, v131, vcc
	global_store_short_d16_hi v[132:133], v128, off
	v_add_co_u32_e32 v132, vcc, 0x4000, v130
	s_nop 1
	v_addc_co_u32_e32 v133, vcc, 0, v131, vcc
	v_add_co_u32_e32 v130, vcc, 0x6000, v130
	global_store_short v[132:133], v129, off
	s_nop 0
	v_addc_co_u32_e32 v131, vcc, 0, v131, vcc
	global_store_short_d16_hi v[130:131], v129, off
	v_mov_b64_e32 v[132:133], v[228:229]
	v_mov_b64_e32 v[134:135], v[230:231]
	s_nop 0
	v_mov_b64_e32 v[128:129], v[232:233]
	v_mov_b64_e32 v[130:131], v[234:235]
	s_cmp_lt_i32 s6, 5
	s_cbranch_scc0 .LBB0_1350

; __device__ __forceinline__ unsigned pk2(float lo, float hi) { const f32x2_t v = {lo, hi}; const bf16x2_t b = __builtin_convertvector(v, bf16x2_t); return __builtin_bit_cast(unsigned, b); }
;     __device__ __forceinline__ void operator()(const f32x4 (&acc)[2][2][4][2], const pg8::Unit& u, int wr, int wc, int fr, int fq) const {
;     ...
;                         const f32x4 c1q = *(const f32x4*)(c1p + cc), c2q = *(const f32x4*)(c2p + cc);
;                         const f32x4 a4 = ai ? acc[1][bj][m][n] : acc[0][bj][m][n];
;                         const f32x4 v = (a4 - c1q * mu) * rstd + c2q;
;                         const unsigned w0 = pk2(v[0], v[1]), w1 = pk2(v[2], v[3]);
;                         if (!isv) { u32x2 w; w.x = w0; w.y = w1; *(u32x2*)(dst + ((unsigned)row * ld + (unsigned)(cc0 + cc))) = w; }
.LBB0_1355:
	v_cndmask_b32_e64 v175, v55, v23, s[22:23]
	v_cndmask_b32_e64 v174, v54, v22, s[22:23]
	v_cndmask_b32_e64 v177, v53, v21, s[22:23]
	v_cndmask_b32_e64 v176, v52, v20, s[22:23]
	v_mov_b32_e32 v161, v160
	v_pk_fma_f32 v[132:133], v[156:157], v[132:133], v[176:177] neg_lo:[1,0,0] neg_hi:[1,0,0]
	v_pk_fma_f32 v[134:135], v[160:161], v[134:135], v[174:175]
	v_mov_b32_e32 v156, v154
	v_mov_b32_e32 v157, v154
	v_pk_fma_f32 v[130:131], v[156:157], v[134:135], v[130:131]
	v_pk_fma_f32 v[128:129], v[154:155], v[132:133], v[128:129]
	s_andn2_b64 vcc, exec, s[26:27]
	v_cvt_pk_bf16_f32 v128, v128, v129
	v_cvt_pk_bf16_f32 v129, v130, v131
	s_cbranch_vccz .LBB0_1360
	s_andn2_b64 vcc, exec, s[24:25]
	s_cbranch_vccz .LBB0_1361

; __device__ __forceinline__ unsigned pk2(float lo, float hi) { const f32x2_t v = {lo, hi}; const bf16x2_t b = __builtin_convertvector(v, bf16x2_t); return __builtin_bit_cast(unsigned, b); }
;     __device__ __forceinline__ void operator()(const f32x4 (&acc)[2][2][4][2], const pg8::Unit& u, int wr, int wc, int fr, int fq) const {
;     ...
;                         const f32x4 c1q = *(const f32x4*)(c1p + cc), c2q = *(const f32x4*)(c2p + cc);
;                         const f32x4 a4 = ai ? acc[1][bj][m][n] : acc[0][bj][m][n];
;                         const f32x4 v = (a4 - c1q * mu) * rstd + c2q;
;                         const unsigned w0 = pk2(v[0], v[1]), w1 = pk2(v[2], v[3]);
;                         if (!isv) { u32x2 w; w.x = w0; w.y = w1; *(u32x2*)(dst + ((unsigned)row * ld + (unsigned)(cc0 + cc))) = w; }
.LBB0_1365:
	v_cndmask_b32_e64 v173, v87, v119, s[22:23]
	v_cndmask_b32_e64 v172, v86, v118, s[22:23]
	v_cndmask_b32_e64 v175, v85, v117, s[22:23]
	v_cndmask_b32_e64 v174, v84, v116, s[22:23]
	v_pk_fma_f32 v[132:133], v[156:157], v[132:133], v[174:175] op_sel_hi:[0,1,1] neg_lo:[1,0,0] neg_hi:[1,0,0]
	v_pk_fma_f32 v[134:135], v[156:157], v[134:135], v[172:173] op_sel_hi:[0,1,1] neg_lo:[1,0,0] neg_hi:[1,0,0]
	v_add_u32_e32 v171, s13, v171
	v_pk_fma_f32 v[130:131], v[154:155], v[134:135], v[130:131] op_sel_hi:[0,1,1]
	v_pk_fma_f32 v[128:129], v[154:155], v[132:133], v[128:129] op_sel_hi:[0,1,1]
	v_or_b32_e32 v158, v171, v164
	v_cvt_pk_bf16_f32 v128, v128, v129
	s_andn2_b64 vcc, exec, s[26:27]
	v_cvt_pk_bf16_f32 v129, v130, v131
	s_cbranch_vccnz .LBB0_1367
	v_mov_b32_e32 v159, v181
	v_lshl_add_u64 v[130:131], v[158:159], 1, s[18:19]
	global_store_dwordx2 v[130:131], v[128:129], off
	s_mov_b64 s[24:25], 0

; __device__ __forceinline__ unsigned pk2(float lo, float hi) { const f32x2_t v = {lo, hi}; const bf16x2_t b = __builtin_convertvector(v, bf16x2_t); return __builtin_bit_cast(unsigned, b); }
;     __device__ __forceinline__ void operator()(const f32x4 (&acc)[2][2][4][2], const pg8::Unit& u, int wr, int wc, int fr, int fq) const {
;     ...
;                         const f32x4 c1q = *(const f32x4*)(c1p + cc), c2q = *(const f32x4*)(c2p + cc);
;                         const f32x4 a4 = ai ? acc[1][bj][m][n] : acc[0][bj][m][n];
;                         const f32x4 v = (a4 - c1q * mu) * rstd + c2q;
;                         const unsigned w0 = pk2(v[0], v[1]), w1 = pk2(v[2], v[3]);
;                         if (!isv) { u32x2 w; w.x = w0; w.y = w1; *(u32x2*)(dst + ((unsigned)row * ld + (unsigned)(cc0 + cc))) = w; }
.LBB0_1373:
	v_cndmask_b32_e64 v161, v41, v9, s[22:23]
	v_cndmask_b32_e64 v160, v40, v8, s[22:23]
	v_pk_fma_f32 v[132:133], v[156:157], v[132:133], v[160:161] neg_lo:[1,0,0] neg_hi:[1,0,0]
	v_xor_b32_e32 v160, 0x80000000, v156
	v_cndmask_b32_e64 v175, v43, v11, s[22:23]
	v_cndmask_b32_e64 v174, v42, v10, s[22:23]
	v_mov_b32_e32 v161, v160
	v_pk_fma_f32 v[134:135], v[160:161], v[134:135], v[174:175]
	v_mov_b32_e32 v174, v154
	v_mov_b32_e32 v175, v154
	v_pk_fma_f32 v[130:131], v[174:175], v[134:135], v[130:131]
	v_pk_fma_f32 v[128:129], v[154:155], v[132:133], v[128:129]
	s_andn2_b64 vcc, exec, s[26:27]
	v_cvt_pk_bf16_f32 v128, v128, v129
	v_cvt_pk_bf16_f32 v129, v130, v131
	s_cbranch_vccz .LBB0_1377
	s_andn2_b64 vcc, exec, s[24:25]
	s_cbranch_vccz .LBB0_1378

; __device__ __forceinline__ unsigned pk2(float lo, float hi) { const f32x2_t v = {lo, hi}; const bf16x2_t b = __builtin_convertvector(v, bf16x2_t); return __builtin_bit_cast(unsigned, b); }
;     __device__ __forceinline__ void operator()(const f32x4 (&acc)[2][2][4][2], const pg8::Unit& u, int wr, int wc, int fr, int fq) const {
;     ...
;                         const f32x4 c1q = *(const f32x4*)(c1p + cc), c2q = *(const f32x4*)(c2p + cc);
;                         const f32x4 a4 = ai ? acc[1][bj][m][n] : acc[0][bj][m][n];
;                         const f32x4 v = (a4 - c1q * mu) * rstd + c2q;
;                         const unsigned w0 = pk2(v[0], v[1]), w1 = pk2(v[2], v[3]);
;                         if (!isv) { u32x2 w; w.x = w0; w.y = w1; *(u32x2*)(dst + ((unsigned)row * ld + (unsigned)(cc0 + cc))) = w; }
.LBB0_1381:
	v_cndmask_b32_e64 v175, v71, v103, s[22:23]
	v_cndmask_b32_e64 v174, v70, v102, s[22:23]
	v_cndmask_b32_e64 v177, v69, v101, s[22:23]
	v_cndmask_b32_e64 v176, v68, v100, s[22:23]
	v_mov_b32_e32 v161, v160
	v_pk_fma_f32 v[132:133], v[156:157], v[132:133], v[176:177] neg_lo:[1,0,0] neg_hi:[1,0,0]
	v_pk_fma_f32 v[134:135], v[160:161], v[134:135], v[174:175]
	v_mov_b32_e32 v174, v154
	v_mov_b32_e32 v175, v154
	v_pk_fma_f32 v[130:131], v[174:175], v[134:135], v[130:131]
	v_pk_fma_f32 v[128:129], v[154:155], v[132:133], v[128:129]
	s_andn2_b64 vcc, exec, s[26:27]
	v_cvt_pk_bf16_f32 v128, v128, v129
	v_cvt_pk_bf16_f32 v129, v130, v131
	s_cbranch_vccz .LBB0_1385
	s_andn2_b64 vcc, exec, s[24:25]
	s_cbranch_vccz .LBB0_1386

; __device__ __forceinline__ unsigned pk2(float lo, float hi) { const f32x2_t v = {lo, hi}; const bf16x2_t b = __builtin_convertvector(v, bf16x2_t); return __builtin_bit_cast(unsigned, b); }
;     __device__ __forceinline__ void operator()(const f32x4 (&acc)[2][2][4][2], const pg8::Unit& u, int wr, int wc, int fr, int fq) const {
;     ...
;                         const f32x4 c1q = *(const f32x4*)(c1p + cc), c2q = *(const f32x4*)(c2p + cc);
;                         const f32x4 a4 = ai ? acc[1][bj][m][n] : acc[0][bj][m][n];
;                         const f32x4 v = (a4 - c1q * mu) * rstd + c2q;
;                         const unsigned w0 = pk2(v[0], v[1]), w1 = pk2(v[2], v[3]);
;                         if (!isv) { u32x2 w; w.x = w0; w.y = w1; *(u32x2*)(dst + ((unsigned)row * ld + (unsigned)(cc0 + cc))) = w; }
.LBB0_1389:
	v_cndmask_b32_e64 v175, v59, v27, s[22:23]
	v_cndmask_b32_e64 v174, v58, v26, s[22:23]
	v_cndmask_b32_e64 v177, v57, v25, s[22:23]
	v_cndmask_b32_e64 v176, v56, v24, s[22:23]
	v_mov_b32_e32 v161, v160
	v_pk_fma_f32 v[132:133], v[156:157], v[132:133], v[176:177] neg_lo:[1,0,0] neg_hi:[1,0,0]
	v_pk_fma_f32 v[134:135], v[160:161], v[134:135], v[174:175]
	v_mov_b32_e32 v156, v154
	v_mov_b32_e32 v157, v154
	v_pk_fma_f32 v[130:131], v[156:157], v[134:135], v[130:131]
	v_pk_fma_f32 v[128:129], v[154:155], v[132:133], v[128:129]
	s_andn2_b64 vcc, exec, s[26:27]
	v_cvt_pk_bf16_f32 v128, v128, v129
	v_cvt_pk_bf16_f32 v129, v130, v131
	s_cbranch_vccz .LBB0_1394
	s_andn2_b64 vcc, exec, s[24:25]
	s_cbranch_vccz .LBB0_1395

; __device__ __forceinline__ unsigned pk2(float lo, float hi) { const f32x2_t v = {lo, hi}; const bf16x2_t b = __builtin_convertvector(v, bf16x2_t); return __builtin_bit_cast(unsigned, b); }
;     __device__ __forceinline__ void operator()(const f32x4 (&acc)[2][2][4][2], const pg8::Unit& u, int wr, int wc, int fr, int fq) const {
;     ...
;                 const int row = row0 + ai * 128 + m * 16; float mu, rstd; row_stats(stats, row, mu, rstd);
;                 const unsigned vrow = (unsigned)(row >> 12) * (4u * 64u * 4096u) + (unsigned)(row & 4095);
; #pragma unroll
;                 for (int bj = 0; bj < 2; ++bj)
; #pragma unroll
;                     for (int n = 0; n < 2; ++n) {
;                         const int cc = bj * 128 + n * 16;
;                         const f32x4 c1q = *(const f32x4*)(c1p + cc), c2q = *(const f32x4*)(c2p + cc);
;                         const f32x4 a4 = ai ? acc[1][bj][m][n] : acc[0][bj][m][n];
;                         const f32x4 v = (a4 - c1q * mu) * rstd + c2q;
;                         const unsigned w0 = pk2(v[0], v[1]), w1 = pk2(v[2], v[3]);
.LBB0_1392:
	v_ashrrev_i32_e32 v159, 31, v158
	v_lshl_add_u64 v[128:129], v[158:159], 3, s[54:55]
	global_load_dwordx2 v[154:155], v[128:129], off
	s_waitcnt vmcnt(0)
	v_mov_b32_e32 v152, v155
	v_mov_b64_e32 v[132:133], v[204:205]
	v_mov_b64_e32 v[134:135], v[206:207]
	v_mov_b64_e32 v[128:129], v[208:209]
	v_mov_b64_e32 v[130:131], v[210:211]
	s_cmp_lt_i32 s6, 5
	s_cbranch_scc1 .LBB0_1397

; __device__ __forceinline__ unsigned pk2(float lo, float hi) { const f32x2_t v = {lo, hi}; const bf16x2_t b = __builtin_convertvector(v, bf16x2_t); return __builtin_bit_cast(unsigned, b); }
;     __device__ __forceinline__ void operator()(const f32x4 (&acc)[2][2][4][2], const pg8::Unit& u, int wr, int wc, int fr, int fq) const {
;     ...
;                 const int row = row0 + ai * 128 + m * 16; float mu, rstd; row_stats(stats, row, mu, rstd);
;                 const unsigned vrow = (unsigned)(row >> 12) * (4u * 64u * 4096u) + (unsigned)(row & 4095);
; #pragma unroll
;                 for (int bj = 0; bj < 2; ++bj)
; #pragma unroll
;                     for (int n = 0; n < 2; ++n) {
;                         const int cc = bj * 128 + n * 16;
;                         const f32x4 c1q = *(const f32x4*)(c1p + cc), c2q = *(const f32x4*)(c2p + cc);
;                         const f32x4 a4 = ai ? acc[1][bj][m][n] : acc[0][bj][m][n];
;                         const f32x4 v = (a4 - c1q * mu) * rstd + c2q;
;                         const unsigned w0 = pk2(v[0], v[1]), w1 = pk2(v[2], v[3]);
.LBB0_1396:
	v_mov_b32_e32 v152, 1.0
	v_mov_b32_e32 v154, 0
	v_mov_b64_e32 v[132:133], v[204:205]
	v_mov_b64_e32 v[134:135], v[206:207]
	v_mov_b64_e32 v[128:129], v[208:209]
	v_mov_b64_e32 v[130:131], v[210:211]
	s_cmp_lt_i32 s6, 5
	s_cbranch_scc0 .LBB0_1393

; __device__ __forceinline__ unsigned pk2(float lo, float hi) { const f32x2_t v = {lo, hi}; const bf16x2_t b = __builtin_convertvector(v, bf16x2_t); return __builtin_bit_cast(unsigned, b); }
;     __device__ __forceinline__ void operator()(const f32x4 (&acc)[2][2][4][2], const pg8::Unit& u, int wr, int wc, int fr, int fq) const {
;     ...
;                         const f32x4 c1q = *(const f32x4*)(c1p + cc), c2q = *(const f32x4*)(c2p + cc);
;                         const f32x4 a4 = ai ? acc[1][bj][m][n] : acc[0][bj][m][n];
;                         const f32x4 v = (a4 - c1q * mu) * rstd + c2q;
;                         const unsigned w0 = pk2(v[0], v[1]), w1 = pk2(v[2], v[3]);
;                         if (!isv) { u32x2 w; w.x = w0; w.y = w1; *(u32x2*)(dst + ((unsigned)row * ld + (unsigned)(cc0 + cc))) = w; }
.LBB0_1399:
	v_add_u32_e32 v155, s13, v171
	v_cndmask_b32_e64 v161, v83, v115, s[22:23]
	v_cndmask_b32_e64 v160, v82, v114, s[22:23]
	v_cndmask_b32_e64 v173, v81, v113, s[22:23]
	v_cndmask_b32_e64 v172, v80, v112, s[22:23]
	v_pk_fma_f32 v[132:133], v[154:155], v[132:133], v[172:173] op_sel_hi:[0,1,1] neg_lo:[1,0,0] neg_hi:[1,0,0]
	v_pk_fma_f32 v[134:135], v[154:155], v[134:135], v[160:161] op_sel_hi:[0,1,1] neg_lo:[1,0,0] neg_hi:[1,0,0]
	v_pk_fma_f32 v[130:131], v[152:153], v[134:135], v[130:131] op_sel_hi:[0,1,1]
	v_pk_fma_f32 v[128:129], v[152:153], v[132:133], v[128:129] op_sel_hi:[0,1,1]
	v_or_b32_e32 v156, v155, v164
	v_cvt_pk_bf16_f32 v128, v128, v129
	s_andn2_b64 vcc, exec, s[24:25]
	v_cvt_pk_bf16_f32 v129, v130, v131
	s_cbranch_vccnz .LBB0_1401
	v_mov_b32_e32 v157, v181
	v_lshl_add_u64 v[130:131], v[156:157], 1, s[18:19]
	global_store_dwordx2 v[130:131], v[128:129], off
	s_mov_b64 s[4:5], 0

; __device__ __forceinline__ unsigned pk2(float lo, float hi) { const f32x2_t v = {lo, hi}; const bf16x2_t b = __builtin_convertvector(v, bf16x2_t); return __builtin_bit_cast(unsigned, b); }
;     __device__ __forceinline__ void operator()(const f32x4 (&acc)[2][2][4][2], const pg8::Unit& u, int wr, int wc, int fr, int fq) const {
;     ...
;                         const int cc = bj * 128 + n * 16;
;                         const f32x4 c1q = *(const f32x4*)(c1p + cc), c2q = *(const f32x4*)(c2p + cc);
;                         const f32x4 a4 = ai ? acc[1][bj][m][n] : acc[0][bj][m][n];
;                         const f32x4 v = (a4 - c1q * mu) * rstd + c2q;
;                         const unsigned w0 = pk2(v[0], v[1]), w1 = pk2(v[2], v[3]);
.LBB0_1403:
	v_mov_b64_e32 v[132:133], v[212:213]
	v_mov_b64_e32 v[134:135], v[214:215]
	s_nop 0
	v_mov_b64_e32 v[128:129], v[216:217]
	v_mov_b64_e32 v[130:131], v[218:219]
	v_mov_b32_e32 v155, v154
	v_mov_b32_e32 v153, v152
	s_cmp_lt_i32 s6, 5
	s_cbranch_scc1 .LBB0_1405
	s_cmp_lg_u32 s6, 5
	s_mov_b64 s[4:5], -1
	s_cselect_b64 s[24:25], -1, 0
	s_cbranch_execz .LBB0_1406
	s_branch .LBB0_1407

; __device__ __forceinline__ unsigned pk2(float lo, float hi) { const f32x2_t v = {lo, hi}; const bf16x2_t b = __builtin_convertvector(v, bf16x2_t); return __builtin_bit_cast(unsigned, b); }
;     __device__ __forceinline__ void operator()(const f32x4 (&acc)[2][2][4][2], const pg8::Unit& u, int wr, int wc, int fr, int fq) const {
;     ...
;                         const f32x4 c1q = *(const f32x4*)(c1p + cc), c2q = *(const f32x4*)(c2p + cc);
;                         const f32x4 a4 = ai ? acc[1][bj][m][n] : acc[0][bj][m][n];
;                         const f32x4 v = (a4 - c1q * mu) * rstd + c2q;
;                         const unsigned w0 = pk2(v[0], v[1]), w1 = pk2(v[2], v[3]);
;                         if (!isv) { u32x2 w; w.x = w0; w.y = w1; *(u32x2*)(dst + ((unsigned)row * ld + (unsigned)(cc0 + cc))) = w; }
.LBB0_1407:
	v_cndmask_b32_e64 v159, v45, v13, s[22:23]
	v_cndmask_b32_e64 v158, v44, v12, s[22:23]
	v_pk_fma_f32 v[132:133], v[154:155], v[132:133], v[158:159] neg_lo:[1,0,0] neg_hi:[1,0,0]
	v_xor_b32_e32 v158, 0x80000000, v154
	v_cndmask_b32_e64 v173, v47, v15, s[22:23]
	v_cndmask_b32_e64 v172, v46, v14, s[22:23]
	v_mov_b32_e32 v159, v158
	v_pk_fma_f32 v[134:135], v[158:159], v[134:135], v[172:173]
	v_mov_b32_e32 v172, v152
	v_mov_b32_e32 v173, v152
	v_pk_fma_f32 v[130:131], v[172:173], v[134:135], v[130:131]
	v_pk_fma_f32 v[128:129], v[152:153], v[132:133], v[128:129]
	s_andn2_b64 vcc, exec, s[24:25]
	v_cvt_pk_bf16_f32 v128, v128, v129
	v_cvt_pk_bf16_f32 v129, v130, v131
	s_cbranch_vccz .LBB0_1411
	s_andn2_b64 vcc, exec, s[4:5]
	s_cbranch_vccz .LBB0_1412

;     __device__ __forceinline__ void operator()(const f32x4 (&acc)[2][2][4][2], const pg8::Unit& u, int wr, int wc, int fr, int fq) const {
;     ...
;                         else {
;                             bf16_t* p = dst + (vrow + (unsigned)(cc0 + cc) * 4096u);
;                             p[0] = (bf16_t)(w0 & 0xffff); p[4096] = (bf16_t)(w0 >> 16); p[2 * 4096] = (bf16_t)(w1 & 0xffff); p[3 * 4096] = (bf16_t)(w1 >> 16);
;                         }
.LBB0_1412:
	v_or_b32_e32 v180, v160, v166
	v_lshl_add_u64 v[130:131], v[180:181], 1, s[18:19]
	v_add_co_u32_e32 v132, vcc, 0x2000, v130
	global_store_short v[130:131], v128, off
	s_nop 0
	v_addc_co_u32_e32 v133, vcc, 0, v131, vcc
	global_store_short_d16_hi v[132:133], v128, off
	v_add_co_u32_e32 v132, vcc, 0x4000, v130
	s_nop 1
	v_addc_co_u32_e32 v133, vcc, 0, v131, vcc
	v_add_co_u32_e32 v130, vcc, 0x6000, v130
	global_store_short v[132:133], v129, off
	s_nop 0
	v_addc_co_u32_e32 v131, vcc, 0, v131, vcc
	global_store_short_d16_hi v[130:131], v129, off
	v_mov_b64_e32 v[132:133], v[220:221]
	v_mov_b64_e32 v[134:135], v[222:223]
	s_nop 0
	v_mov_b64_e32 v[128:129], v[224:225]
	v_mov_b64_e32 v[130:131], v[226:227]
	s_cmp_lt_i32 s6, 5
	s_cbranch_scc0 .LBB0_1410

; __device__ __forceinline__ unsigned pk2(float lo, float hi) { const f32x2_t v = {lo, hi}; const bf16x2_t b = __builtin_convertvector(v, bf16x2_t); return __builtin_bit_cast(unsigned, b); }
;     __device__ __forceinline__ void operator()(const f32x4 (&acc)[2][2][4][2], const pg8::Unit& u, int wr, int wc, int fr, int fq) const {
;     ...
;                         const f32x4 c1q = *(const f32x4*)(c1p + cc), c2q = *(const f32x4*)(c2p + cc);
;                         const f32x4 a4 = ai ? acc[1][bj][m][n] : acc[0][bj][m][n];
;                         const f32x4 v = (a4 - c1q * mu) * rstd + c2q;
;                         const unsigned w0 = pk2(v[0], v[1]), w1 = pk2(v[2], v[3]);
;                         if (!isv) { u32x2 w; w.x = w0; w.y = w1; *(u32x2*)(dst + ((unsigned)row * ld + (unsigned)(cc0 + cc))) = w; }
.LBB0_1415:
	v_cndmask_b32_e64 v173, v67, v99, s[22:23]
	v_cndmask_b32_e64 v172, v66, v98, s[22:23]
	v_cndmask_b32_e64 v175, v65, v97, s[22:23]
	v_cndmask_b32_e64 v174, v64, v96, s[22:23]
	v_mov_b32_e32 v159, v158
	v_pk_fma_f32 v[132:133], v[154:155], v[132:133], v[174:175] neg_lo:[1,0,0] neg_hi:[1,0,0]
	v_pk_fma_f32 v[134:135], v[158:159], v[134:135], v[172:173]
	v_mov_b32_e32 v172, v152
	v_mov_b32_e32 v173, v152
	v_pk_fma_f32 v[130:131], v[172:173], v[134:135], v[130:131]
	v_pk_fma_f32 v[128:129], v[152:153], v[132:133], v[128:129]
	s_andn2_b64 vcc, exec, s[24:25]
	v_cvt_pk_bf16_f32 v128, v128, v129
	v_cvt_pk_bf16_f32 v129, v130, v131
	s_cbranch_vccz .LBB0_1419
	s_andn2_b64 vcc, exec, s[4:5]
	s_cbranch_vccz .LBB0_1420

;     __device__ __forceinline__ void operator()(const f32x4 (&acc)[2][2][4][2], const pg8::Unit& u, int wr, int wc, int fr, int fq) const {
;     ...
;                         else {
;                             bf16_t* p = dst + (vrow + (unsigned)(cc0 + cc) * 4096u);
;                             p[0] = (bf16_t)(w0 & 0xffff); p[4096] = (bf16_t)(w0 >> 16); p[2 * 4096] = (bf16_t)(w1 & 0xffff); p[3 * 4096] = (bf16_t)(w1 >> 16);
;                         }
.LBB0_1420:
	v_or_b32_e32 v180, v160, v167
	v_lshl_add_u64 v[130:131], v[180:181], 1, s[18:19]
	v_add_co_u32_e32 v132, vcc, 0x2000, v130
	global_store_short v[130:131], v128, off
	s_nop 0
	v_addc_co_u32_e32 v133, vcc, 0, v131, vcc
	global_store_short_d16_hi v[132:133], v128, off
	v_add_co_u32_e32 v132, vcc, 0x4000, v130
	s_nop 1
	v_addc_co_u32_e32 v133, vcc, 0, v131, vcc
	v_add_co_u32_e32 v130, vcc, 0x6000, v130
	global_store_short v[132:133], v129, off
	s_nop 0
	v_addc_co_u32_e32 v131, vcc, 0, v131, vcc
	global_store_short_d16_hi v[130:131], v129, off
	v_mov_b64_e32 v[132:133], v[228:229]
	v_mov_b64_e32 v[134:135], v[230:231]
	s_nop 0
	v_mov_b64_e32 v[128:129], v[232:233]
	v_mov_b64_e32 v[130:131], v[234:235]
	s_cmp_lt_i32 s6, 5
	s_cbranch_scc0 .LBB0_1418

; __device__ __forceinline__ unsigned pk2(float lo, float hi) { const f32x2_t v = {lo, hi}; const bf16x2_t b = __builtin_convertvector(v, bf16x2_t); return __builtin_bit_cast(unsigned, b); }
;     __device__ __forceinline__ void operator()(const f32x4 (&acc)[2][2][4][2], const pg8::Unit& u, int wr, int wc, int fr, int fq) const {
;     ...
;                         const f32x4 c1q = *(const f32x4*)(c1p + cc), c2q = *(const f32x4*)(c2p + cc);
;                         const f32x4 a4 = ai ? acc[1][bj][m][n] : acc[0][bj][m][n];
;                         const f32x4 v = (a4 - c1q * mu) * rstd + c2q;
;                         const unsigned w0 = pk2(v[0], v[1]), w1 = pk2(v[2], v[3]);
;                         if (!isv) { u32x2 w; w.x = w0; w.y = w1; *(u32x2*)(dst + ((unsigned)row * ld + (unsigned)(cc0 + cc))) = w; }
.LBB0_1423:
	v_cndmask_b32_e64 v173, v63, v31, s[22:23]
	v_cndmask_b32_e64 v172, v62, v30, s[22:23]
	v_cndmask_b32_e64 v175, v61, v29, s[22:23]
	v_cndmask_b32_e64 v174, v60, v28, s[22:23]
	v_mov_b32_e32 v159, v158
	v_pk_fma_f32 v[132:133], v[154:155], v[132:133], v[174:175] neg_lo:[1,0,0] neg_hi:[1,0,0]
	v_pk_fma_f32 v[134:135], v[158:159], v[134:135], v[172:173]
	v_mov_b32_e32 v154, v152
	v_mov_b32_e32 v155, v152
	v_pk_fma_f32 v[130:131], v[154:155], v[134:135], v[130:131]
	v_pk_fma_f32 v[128:129], v[152:153], v[132:133], v[128:129]
	s_andn2_b64 vcc, exec, s[24:25]
	v_cvt_pk_bf16_f32 v128, v128, v129
	v_cvt_pk_bf16_f32 v129, v130, v131
	s_cbranch_vccz .LBB0_1425
	s_andn2_b64 vcc, exec, s[4:5]
	s_cbranch_vccnz .LBB0_1289
	s_branch .LBB0_1426

; #define PG8_STAGE(bufoff, gbase, voff) do { _Pragma("unroll") for (int _i = 0; _i < 2; ++_i) \
;         __builtin_amdgcn_global_load_lds((const unsigned*)((const char*)(gbase) + (voff)[_i]), (LAS unsigned*)(lds + (bufoff) + ldsw + _i * 8192), 16, 0, 0); } while (0)
; #define PG8_LDA(dst, b, h) do { _Pragma("unroll") for (int m = 0; m < 4; ++m) _Pragma("unroll") for (int k = 0; k < 2; ++k) dst[m][k] = *(const LAS bf16x8*)(lds + PG8_SA(b, h) + aoff + m * 2048 + k * 1024); } while (0)
; #define PG8_WAIT_V(n) asm volatile("s_waitcnt vmcnt(" #n ")" ::: "memory")
; #define PG8_WAIT_L(n) asm volatile("s_waitcnt lgkmcnt(" #n ")" ::: "memory")
; template <class Epi>
; __device__ __forceinline__ void gemm_phase(const Tb tb, LAS unsigned char* lds, const Gemm g, const StaticOrder& S, const Epi& E) {
;     ...
;         for (int t = 0; t < nt; t += 2) {
;             const bool last = (t == nt - 2);
;             const char* a1 = cA + (size_t)(t + 1) * kstep;
;             const char* a2 = last ? nA : cA + (size_t)(t + 2) * kstep; const char* b2 = last ? nB : cB + (size_t)(t + 2) * kstep;
;             const char* a3 = a2 + kstep; const char* b3 = b2 + kstep;
;             PG8_LDB(B0, 0, 0); PG8_SCHED; PG8_LDA(At, 0, 0); PG8_STAGE(PG8_SA(1, 1), a1 + hstep, voffA);
;             PG8_WAIT_L(8); PG8_BAR; PG8_WAIT_L(0); PG8_MMA(0, 0, At, B0); PG8_BAR; PG8_SCHED;
;             PG8_LDB(B1, 0, 1); PG8_STAGE(PG8_SB(0, 0), b2, voffB);
;             PG8_BAR; PG8_WAIT_L(0); PG8_MMA(0, 1, At, B1); PG8_BAR;
;             PG8_LDA(At, 0, 1); PG8_STAGE(PG8_SA(0, 0), a2, voffA);
;             PG8_BAR; PG8_WAIT_L(0); PG8_MMA(1, 0, At, B0); PG8_BAR; PG8_SCHED;
;             PG8_STAGE(PG8_SB(0, 1), b2 + hstep, voffB);
;             PG8_WAIT_V(6); PG8_BAR; PG8_MMA(1, 1, At, B1); PG8_BAR;
;             PG8_LDB(B0, 1, 0); PG8_SCHED; PG8_LDA(At, 1, 0); PG8_STAGE(PG8_SA(0, 1), a2 + hstep, voffA);
;             PG8_WAIT_L(8); PG8_BAR; PG8_WAIT_L(0); PG8_MMA(0, 0, At, B0); PG8_BAR; PG8_SCHED;
;             PG8_LDB(B1, 1, 1); PG8_STAGE(PG8_SB(1, 0), b3, voffB);
;             PG8_BAR; PG8_WAIT_L(0); PG8_MMA(0, 1, At, B1); PG8_BAR;
;             PG8_LDA(At, 1, 1); PG8_STAGE(PG8_SA(1, 0), a3, voffA);
;             PG8_BAR; PG8_WAIT_L(0); PG8_MMA(1, 0, At, B0); PG8_BAR; PG8_SCHED;
;             PG8_STAGE(PG8_SB(1, 1), b3 + hstep, voffB);
;             PG8_WAIT_V(6); PG8_BAR; PG8_MMA(1, 1, At, B1); PG8_BAR;
.LBB0_1583:
	s_add_u32 s26, s24, 0xfffc0080
	s_addc_u32 s27, s25, -1
	s_add_i32 s49, 0, 0x10000
	v_add_u32_e32 v60, s49, v177
	ds_read_b128 v[48:51], v60
	ds_read_b128 v[52:55], v60 offset:1024
	ds_read_b128 v[56:59], v60 offset:2048
	ds_read_b128 v[60:63], v60 offset:3072
	s_cmp_eq_u32 s48, 12
	s_cselect_b32 s29, s5, s27
	s_cselect_b32 s28, s19, s26
	s_cselect_b32 s27, s17, s47
	s_cselect_b32 s26, s45, s46
	v_lshl_add_u64 v[170:171], s[24:25], 0, v[164:165]
	s_add_i32 m0, s36, 0xc000
	ds_read_b128 v[72:75], v179
	ds_read_b128 v[76:79], v179 offset:1024
	ds_read_b128 v[80:83], v179 offset:2048
	ds_read_b128 v[84:87], v179 offset:3072
	ds_read_b128 v[166:169], v179 offset:4096
	ds_read_b128 v[208:211], v179 offset:5120
	ds_read_b128 v[212:215], v179 offset:6144
	ds_read_b128 v[216:219], v179 offset:7168
	global_load_lds_dwordx4 v[170:171], off
	v_lshl_add_u64 v[170:171], s[24:25], 0, v[162:163]
	s_add_i32 m0, s36, 0xe000
	s_nop 0
	global_load_lds_dwordx4 v[170:171], off
	s_waitcnt lgkmcnt(8)
	s_barrier
	s_waitcnt lgkmcnt(0)
	s_setprio 1
	s_waitcnt lgkmcnt(0)
	v_mfma_f32_16x16x32_bf16 v[156:159], v[48:51], v[72:75], v[156:159]
	v_mfma_f32_16x16x32_bf16 v[148:151], v[56:59], v[72:75], v[148:151]
	v_mfma_f32_16x16x32_bf16 v[140:143], v[48:51], v[80:83], v[140:143]
	v_mfma_f32_16x16x32_bf16 v[132:135], v[56:59], v[80:83], v[132:135]
	v_mfma_f32_16x16x32_bf16 v[124:127], v[48:51], v[166:169], v[124:127]
	v_mfma_f32_16x16x32_bf16 v[116:119], v[56:59], v[166:169], v[116:119]
	v_mfma_f32_16x16x32_bf16 v[108:111], v[48:51], v[212:215], v[108:111]
	v_mfma_f32_16x16x32_bf16 v[100:103], v[56:59], v[212:215], v[100:103]
	v_mfma_f32_16x16x32_bf16 v[156:159], v[52:55], v[76:79], v[156:159]
	v_mfma_f32_16x16x32_bf16 v[148:151], v[60:63], v[76:79], v[148:151]
	v_mfma_f32_16x16x32_bf16 v[140:143], v[52:55], v[84:87], v[140:143]
	v_mfma_f32_16x16x32_bf16 v[132:135], v[60:63], v[84:87], v[132:135]
	v_mfma_f32_16x16x32_bf16 v[124:127], v[52:55], v[208:211], v[124:127]
	v_mfma_f32_16x16x32_bf16 v[116:119], v[60:63], v[208:211], v[116:119]
	v_mfma_f32_16x16x32_bf16 v[108:111], v[52:55], v[216:219], v[108:111]
	v_mfma_f32_16x16x32_bf16 v[100:103], v[60:63], v[216:219], v[100:103]
	s_setprio 0
	s_barrier
	s_add_i32 s52, 0, 0x14000
	v_add_u32_e32 v170, s52, v177
	s_add_i32 s49, s49, s34
	ds_read_b128 v[220:223], v170
	ds_read_b128 v[224:227], v170 offset:1024
	ds_read_b128 v[228:231], v170 offset:2048
	ds_read_b128 v[232:235], v170 offset:3072
	v_lshl_add_u64 v[170:171], s[26:27], 0, v[180:181]
	s_mov_b32 m0, s49
	v_lshl_add_u64 v[174:175], s[26:27], 0, v[160:161]
	global_load_lds_dwordx4 v[170:171], off
	s_add_i32 m0, s49, 0x2000
	s_nop 0
	global_load_lds_dwordx4 v[174:175], off
	s_barrier
	s_waitcnt lgkmcnt(0)
	s_setprio 1
	s_waitcnt lgkmcnt(0)
	v_mfma_f32_16x16x32_bf16 v[152:155], v[220:223], v[72:75], v[152:155]
	v_mfma_f32_16x16x32_bf16 v[72:75], v[228:231], v[72:75], v[144:147]
	v_mfma_f32_16x16x32_bf16 v[152:155], v[224:227], v[76:79], v[152:155]
	v_mfma_f32_16x16x32_bf16 v[72:75], v[232:235], v[76:79], v[72:75]
	v_mfma_f32_16x16x32_bf16 v[76:79], v[220:223], v[80:83], v[136:139]
	v_mfma_f32_16x16x32_bf16 v[80:83], v[228:231], v[80:83], v[128:131]
	v_mfma_f32_16x16x32_bf16 v[112:115], v[228:231], v[166:169], v[112:115]
	v_mfma_f32_16x16x32_bf16 v[104:107], v[220:223], v[212:215], v[104:107]
	v_mfma_f32_16x16x32_bf16 v[96:99], v[228:231], v[212:215], v[96:99]
	v_mfma_f32_16x16x32_bf16 v[76:79], v[224:227], v[84:87], v[76:79]
	v_mfma_f32_16x16x32_bf16 v[80:83], v[232:235], v[84:87], v[80:83]
	v_mfma_f32_16x16x32_bf16 v[84:87], v[220:223], v[166:169], v[120:123]
	v_mfma_f32_16x16x32_bf16 v[112:115], v[232:235], v[208:211], v[112:115]
	v_mfma_f32_16x16x32_bf16 v[104:107], v[224:227], v[216:219], v[104:107]
	v_mfma_f32_16x16x32_bf16 v[96:99], v[232:235], v[216:219], v[96:99]
	v_mfma_f32_16x16x32_bf16 v[84:87], v[224:227], v[208:211], v[84:87]
	s_setprio 0
	s_mov_b32 m0, s36
	v_lshl_add_u64 v[198:199], s[28:29], 0, v[180:181]
	s_barrier
	ds_read_b128 v[120:123], v179 offset:16384
	ds_read_b128 v[128:131], v179 offset:17408
	ds_read_b128 v[136:139], v179 offset:18432
	ds_read_b128 v[144:147], v179 offset:19456
	ds_read_b128 v[166:169], v179 offset:20480
	ds_read_b128 v[208:211], v179 offset:21504
	ds_read_b128 v[212:215], v179 offset:22528
	ds_read_b128 v[216:219], v179 offset:23552
	global_load_lds_dwordx4 v[198:199], off
	v_lshl_add_u64 v[250:251], s[28:29], 0, v[160:161]
	s_mov_b32 m0, s37
	s_nop 0
	global_load_lds_dwordx4 v[250:251], off
	s_barrier
	s_waitcnt lgkmcnt(0)
	s_setprio 1
	s_waitcnt lgkmcnt(0)
	v_mfma_f32_16x16x32_bf16 v[92:95], v[48:51], v[120:123], v[92:95]
	v_mfma_f32_16x16x32_bf16 v[68:71], v[56:59], v[120:123], v[68:71]
	v_mfma_f32_16x16x32_bf16 v[44:47], v[48:51], v[136:139], v[44:47]
	v_mfma_f32_16x16x32_bf16 v[36:39], v[56:59], v[136:139], v[36:39]
	v_mfma_f32_16x16x32_bf16 v[28:31], v[48:51], v[166:169], v[28:31]
	v_mfma_f32_16x16x32_bf16 v[20:23], v[56:59], v[166:169], v[20:23]
	v_mfma_f32_16x16x32_bf16 v[12:15], v[48:51], v[212:215], v[12:15]
	v_mfma_f32_16x16x32_bf16 v[4:7], v[56:59], v[212:215], v[4:7]
	v_mfma_f32_16x16x32_bf16 v[92:95], v[52:55], v[128:131], v[92:95]
	v_mfma_f32_16x16x32_bf16 v[68:71], v[60:63], v[128:131], v[68:71]
	v_mfma_f32_16x16x32_bf16 v[44:47], v[52:55], v[144:147], v[44:47]
	v_mfma_f32_16x16x32_bf16 v[36:39], v[60:63], v[144:147], v[36:39]
	v_mfma_f32_16x16x32_bf16 v[28:31], v[52:55], v[208:211], v[28:31]
	v_mfma_f32_16x16x32_bf16 v[20:23], v[60:63], v[208:211], v[20:23]
	v_mfma_f32_16x16x32_bf16 v[12:15], v[52:55], v[216:219], v[12:15]
	v_mfma_f32_16x16x32_bf16 v[4:7], v[60:63], v[216:219], v[4:7]
	s_setprio 0
	s_barrier
; #define PG8_STAGE(bufoff, gbase, voff) do { _Pragma("unroll") for (int _i = 0; _i < 2; ++_i) \
;         __builtin_amdgcn_global_load_lds((const unsigned*)((const char*)(gbase) + (voff)[_i]), (LAS unsigned*)(lds + (bufoff) + ldsw + _i * 8192), 16, 0, 0); } while (0)
; #define PG8_LDA(dst, b, h) do { _Pragma("unroll") for (int m = 0; m < 4; ++m) _Pragma("unroll") for (int k = 0; k < 2; ++k) dst[m][k] = *(const LAS bf16x8*)(lds + PG8_SA(b, h) + aoff + m * 2048 + k * 1024); } while (0)
; #define PG8_LDB(dst, b, h) do { _Pragma("unroll") for (int n = 0; n < 2; ++n) _Pragma("unroll") for (int k = 0; k < 2; ++k) dst[n][k] = *(const LAS bf16x8*)(lds + PG8_SB(b, h) + boff + n * 2048 + k * 1024); } while (0)
; #define PG8_WAIT_V(n) asm volatile("s_waitcnt vmcnt(" #n ")" ::: "memory")
; #define PG8_WAIT_L(n) asm volatile("s_waitcnt lgkmcnt(" #n ")" ::: "memory")
; #define PG8_BAR __builtin_amdgcn_s_barrier()
; #define PG8_SCHED __builtin_amdgcn_sched_barrier(0)
; template <class Epi>
; __device__ __forceinline__ void gemm_phase(const Tb tb, LAS unsigned char* lds, const Gemm g, const StaticOrder& S, const Epi& E) {
;     ...
;             PG8_LDB(B0, 0, 0); PG8_SCHED; PG8_LDA(At, 0, 0); PG8_STAGE(PG8_SA(1, 1), a1 + hstep, voffA);
;             PG8_WAIT_L(8); PG8_BAR; PG8_WAIT_L(0); PG8_MMA(0, 0, At, B0); PG8_BAR; PG8_SCHED;
;             PG8_LDB(B1, 0, 1); PG8_STAGE(PG8_SB(0, 0), b2, voffB);
;             PG8_BAR; PG8_WAIT_L(0); PG8_MMA(0, 1, At, B1); PG8_BAR;
;             PG8_LDA(At, 0, 1); PG8_STAGE(PG8_SA(0, 0), a2, voffA);
;             PG8_BAR; PG8_WAIT_L(0); PG8_MMA(1, 0, At, B0); PG8_BAR; PG8_SCHED;
;             PG8_STAGE(PG8_SB(0, 1), b2 + hstep, voffB);
;             PG8_WAIT_V(6); PG8_BAR; PG8_MMA(1, 1, At, B1); PG8_BAR;
;             PG8_LDB(B0, 1, 0); PG8_SCHED; PG8_LDA(At, 1, 0); PG8_STAGE(PG8_SA(0, 1), a2 + hstep, voffA);
;             PG8_WAIT_L(8); PG8_BAR; PG8_WAIT_L(0); PG8_MMA(0, 0, At, B0); PG8_BAR; PG8_SCHED;
;             PG8_LDB(B1, 1, 1); PG8_STAGE(PG8_SB(1, 0), b3, voffB);
;             PG8_BAR; PG8_WAIT_L(0); PG8_MMA(0, 1, At, B1); PG8_BAR;
;             PG8_LDA(At, 1, 1); PG8_STAGE(PG8_SA(1, 0), a3, voffA);
;             PG8_BAR; PG8_WAIT_L(0); PG8_MMA(1, 0, At, B0); PG8_BAR; PG8_SCHED;
;             PG8_STAGE(PG8_SB(1, 1), b3 + hstep, voffB);
;             PG8_WAIT_V(6); PG8_BAR; PG8_MMA(1, 1, At, B1); PG8_BAR;
	s_add_u32 s50, s26, 0x40000
	s_addc_u32 s51, s27, 0
	s_add_i32 s49, s52, s34
	v_lshl_add_u64 v[48:49], s[50:51], 0, v[180:181]
	s_mov_b32 m0, s49
	s_nop 0
	global_load_lds_dwordx4 v[48:49], off
	v_lshl_add_u64 v[48:49], s[50:51], 0, v[160:161]
	s_add_i32 m0, s49, 0x2000
	s_nop 0
	global_load_lds_dwordx4 v[48:49], off
	s_waitcnt vmcnt(6)
	s_barrier
	s_setprio 1
	v_mfma_f32_16x16x32_bf16 v[40:43], v[220:223], v[136:139], v[40:43]
	v_mfma_f32_16x16x32_bf16 v[32:35], v[228:231], v[136:139], v[32:35]
	v_mfma_f32_16x16x32_bf16 v[24:27], v[220:223], v[166:169], v[24:27]
	v_mfma_f32_16x16x32_bf16 v[16:19], v[228:231], v[166:169], v[16:19]
	v_mfma_f32_16x16x32_bf16 v[8:11], v[220:223], v[212:215], v[8:11]
	v_mfma_f32_16x16x32_bf16 v[0:3], v[228:231], v[212:215], v[0:3]
	v_mfma_f32_16x16x32_bf16 v[48:51], v[220:223], v[120:123], v[88:91]
	v_mfma_f32_16x16x32_bf16 v[52:55], v[228:231], v[120:123], v[64:67]
	v_mfma_f32_16x16x32_bf16 v[40:43], v[224:227], v[144:147], v[40:43]
	v_mfma_f32_16x16x32_bf16 v[32:35], v[232:235], v[144:147], v[32:35]
	v_mfma_f32_16x16x32_bf16 v[24:27], v[224:227], v[208:211], v[24:27]
	v_mfma_f32_16x16x32_bf16 v[16:19], v[232:235], v[208:211], v[16:19]
	v_mfma_f32_16x16x32_bf16 v[8:11], v[224:227], v[216:219], v[8:11]
	v_mfma_f32_16x16x32_bf16 v[0:3], v[232:235], v[216:219], v[0:3]
	v_mfma_f32_16x16x32_bf16 v[48:51], v[224:227], v[128:131], v[48:51]
	v_mfma_f32_16x16x32_bf16 v[52:55], v[232:235], v[128:131], v[52:55]
	s_setprio 0
	s_add_i32 s49, 0, 0x18000
	v_add_u32_e32 v88, s49, v177
	s_barrier
	ds_read_b128 v[56:59], v88
	ds_read_b128 v[60:63], v88 offset:1024
	ds_read_b128 v[64:67], v88 offset:2048
	ds_read_b128 v[88:91], v88 offset:3072
	s_add_u32 s28, s28, 0x40000
	s_addc_u32 s29, s29, 0
	s_mov_b32 m0, s38
	v_lshl_add_u64 v[136:137], s[28:29], 0, v[180:181]
	ds_read_b128 v[120:123], v179 offset:32768
	ds_read_b128 v[128:131], v179 offset:33792
	ds_read_b128 v[166:169], v179 offset:34816
	ds_read_b128 v[208:211], v179 offset:35840
	ds_read_b128 v[212:215], v179 offset:36864
	ds_read_b128 v[216:219], v179 offset:37888
	ds_read_b128 v[220:223], v179 offset:38912
	ds_read_b128 v[224:227], v179 offset:39936
	global_load_lds_dwordx4 v[136:137], off
	v_lshl_add_u64 v[136:137], s[28:29], 0, v[160:161]
	s_mov_b32 m0, s39
	s_nop 0
	global_load_lds_dwordx4 v[136:137], off
	s_waitcnt lgkmcnt(8)
	s_barrier
	s_waitcnt lgkmcnt(0)
	s_setprio 1
	s_waitcnt lgkmcnt(0)
	v_mfma_f32_16x16x32_bf16 v[136:139], v[56:59], v[120:123], v[156:159]
	v_mfma_f32_16x16x32_bf16 v[156:159], v[60:63], v[128:131], v[136:139]
	v_mfma_f32_16x16x32_bf16 v[136:139], v[64:67], v[120:123], v[148:151]
	v_mfma_f32_16x16x32_bf16 v[148:151], v[88:91], v[128:131], v[136:139]
	v_mfma_f32_16x16x32_bf16 v[136:139], v[56:59], v[166:169], v[140:143]
	v_mfma_f32_16x16x32_bf16 v[132:135], v[64:67], v[166:169], v[132:135]
	v_mfma_f32_16x16x32_bf16 v[124:127], v[56:59], v[212:215], v[124:127]
	v_mfma_f32_16x16x32_bf16 v[116:119], v[64:67], v[212:215], v[116:119]
	v_mfma_f32_16x16x32_bf16 v[108:111], v[56:59], v[220:223], v[108:111]
	v_mfma_f32_16x16x32_bf16 v[100:103], v[64:67], v[220:223], v[100:103]
	v_mfma_f32_16x16x32_bf16 v[140:143], v[60:63], v[208:211], v[136:139]
	v_mfma_f32_16x16x32_bf16 v[132:135], v[88:91], v[208:211], v[132:135]
	v_mfma_f32_16x16x32_bf16 v[124:127], v[60:63], v[216:219], v[124:127]
	v_mfma_f32_16x16x32_bf16 v[116:119], v[88:91], v[216:219], v[116:119]
	v_mfma_f32_16x16x32_bf16 v[108:111], v[60:63], v[224:227], v[108:111]
	v_mfma_f32_16x16x32_bf16 v[100:103], v[88:91], v[224:227], v[100:103]
	s_setprio 0
	s_barrier
	s_add_i32 s28, 0, 0x1c000
	v_add_u32_e32 v136, s28, v177
	s_add_i32 s29, s49, s34
	ds_read_b128 v[228:231], v136
	ds_read_b128 v[232:235], v136 offset:1024
	ds_read_b128 v[242:245], v136 offset:2048
	ds_read_b128 v[204:207], v136 offset:3072
	v_lshl_add_u64 v[136:137], v[170:171], 0, s[0:1]
	s_mov_b32 m0, s29
	s_nop 0
	global_load_lds_dwordx4 v[136:137], off
	v_lshl_add_u64 v[136:137], v[174:175], 0, s[0:1]
	s_add_i32 m0, s29, 0x2000
	s_nop 0
	global_load_lds_dwordx4 v[136:137], off
	s_barrier
	s_waitcnt lgkmcnt(0)
	s_setprio 1
	s_waitcnt lgkmcnt(0)
	v_mfma_f32_16x16x32_bf16 v[72:75], v[242:245], v[120:123], v[72:75]
	v_mfma_f32_16x16x32_bf16 v[136:139], v[228:231], v[120:123], v[152:155]
	v_mfma_f32_16x16x32_bf16 v[144:147], v[204:207], v[128:131], v[72:75]
	v_mfma_f32_16x16x32_bf16 v[72:75], v[228:231], v[166:169], v[76:79]
	v_mfma_f32_16x16x32_bf16 v[152:155], v[232:235], v[128:131], v[136:139]
	v_mfma_f32_16x16x32_bf16 v[136:139], v[232:235], v[208:211], v[72:75]
	v_mfma_f32_16x16x32_bf16 v[72:75], v[242:245], v[166:169], v[80:83]
	v_mfma_f32_16x16x32_bf16 v[128:131], v[204:207], v[208:211], v[72:75]
	v_mfma_f32_16x16x32_bf16 v[72:75], v[228:231], v[212:215], v[84:87]
	v_mfma_f32_16x16x32_bf16 v[120:123], v[232:235], v[216:219], v[72:75]
	v_mfma_f32_16x16x32_bf16 v[72:75], v[242:245], v[212:215], v[112:115]
	v_mfma_f32_16x16x32_bf16 v[112:115], v[204:207], v[216:219], v[72:75]
	v_mfma_f32_16x16x32_bf16 v[72:75], v[228:231], v[220:223], v[104:107]
	v_mfma_f32_16x16x32_bf16 v[104:107], v[232:235], v[224:227], v[72:75]
	v_mfma_f32_16x16x32_bf16 v[72:75], v[242:245], v[220:223], v[96:99]
	v_mfma_f32_16x16x32_bf16 v[96:99], v[204:207], v[224:227], v[72:75]
	s_setprio 0
	s_mov_b32 m0, s40
	v_lshl_add_u64 v[170:171], v[198:199], 0, s[0:1]
	s_barrier
	s_nop 2
	ds_read_b128 v[72:75], v179 offset:49152
	ds_read_b128 v[76:79], v179 offset:50176
	ds_read_b128 v[80:83], v179 offset:51200
	ds_read_b128 v[84:87], v179 offset:52224
	ds_read_b128 v[166:169], v179 offset:53248
	ds_read_b128 v[208:211], v179 offset:54272
	ds_read_b128 v[212:215], v179 offset:55296
	ds_read_b128 v[216:219], v179 offset:56320
	global_load_lds_dwordx4 v[170:171], off
	v_lshl_add_u64 v[170:171], v[250:251], 0, s[0:1]
	s_mov_b32 m0, s41
	s_nop 0
	global_load_lds_dwordx4 v[170:171], off
	s_barrier
; #define PG8_STAGE(bufoff, gbase, voff) do { _Pragma("unroll") for (int _i = 0; _i < 2; ++_i) \
;         __builtin_amdgcn_global_load_lds((const unsigned*)((const char*)(gbase) + (voff)[_i]), (LAS unsigned*)(lds + (bufoff) + ldsw + _i * 8192), 16, 0, 0); } while (0)
; #define PG8_LDA(dst, b, h) do { _Pragma("unroll") for (int m = 0; m < 4; ++m) _Pragma("unroll") for (int k = 0; k < 2; ++k) dst[m][k] = *(const LAS bf16x8*)(lds + PG8_SA(b, h) + aoff + m * 2048 + k * 1024); } while (0)
; #define PG8_LDB(dst, b, h) do { _Pragma("unroll") for (int n = 0; n < 2; ++n) _Pragma("unroll") for (int k = 0; k < 2; ++k) dst[n][k] = *(const LAS bf16x8*)(lds + PG8_SB(b, h) + boff + n * 2048 + k * 1024); } while (0)
; template <class Epi>
; __device__ __forceinline__ void gemm_phase(const Tb tb, LAS unsigned char* lds, const Gemm g, const StaticOrder& S, const Epi& E) {
;     ...
;             PG8_WAIT_V(6); PG8_BAR; PG8_MMA(1, 1, At, B1); PG8_BAR;
;             PG8_LDB(B0, 1, 0); PG8_SCHED; PG8_LDA(At, 1, 0); PG8_STAGE(PG8_SA(0, 1), a2 + hstep, voffA);
;             PG8_WAIT_L(8); PG8_BAR; PG8_WAIT_L(0); PG8_MMA(0, 0, At, B0); PG8_BAR; PG8_SCHED;
;             PG8_LDB(B1, 1, 1); PG8_STAGE(PG8_SB(1, 0), b3, voffB);
;             PG8_BAR; PG8_WAIT_L(0); PG8_MMA(0, 1, At, B1); PG8_BAR;
;             PG8_LDA(At, 1, 1); PG8_STAGE(PG8_SA(1, 0), a3, voffA);
;             PG8_BAR; PG8_WAIT_L(0); PG8_MMA(1, 0, At, B0); PG8_BAR; PG8_SCHED;
;             PG8_STAGE(PG8_SB(1, 1), b3 + hstep, voffB);
;             PG8_WAIT_V(6); PG8_BAR; PG8_MMA(1, 1, At, B1); PG8_BAR;
;     __device__ __forceinline__ void operator()(const f32x4 (&acc)[2][2][4][2], const pg8::Unit& u, int wr, int wc, int fr, int fq) const {
;         const int row0 = u.pm * 256 + wr * 64 + fr, hcol0 = u.pn * 128 + wc * 32 + 4 * fq, ci0 = u.pn * 256 + wc * 32 + 4 * fq;
;         f32x4 c1g[2], c2g[2], c1u[2], c2u[2];
; #pragma unroll
;         for (int n = 0; n < 2; ++n) { c1g[n] = *(const f32x4*)(c1 + ci0 + 16 * n); c2g[n] = *(const f32x4*)(c2 + ci0 + 16 * n); c1u[n] = *(const f32x4*)(c1 + ci0 + 128 + 16 * n); c2u[n] = *(const f32x4*)(c2 + ci0 + 128 + 16 * n); }
; #pragma unroll
;         for (int ai = 0; ai < 2; ++ai)
; #pragma unroll
;             for (int m = 0; m < 4; ++m) {
;                 const int row = row0 + ai * 128 + m * 16; float mu, rstd; row_stats(stats, row, mu, rstd);
	s_waitcnt lgkmcnt(0)
	s_setprio 1
	s_waitcnt lgkmcnt(0)
	v_mfma_f32_16x16x32_bf16 v[92:95], v[56:59], v[72:75], v[92:95]
	v_mfma_f32_16x16x32_bf16 v[68:71], v[64:67], v[72:75], v[68:71]
	v_mfma_f32_16x16x32_bf16 v[44:47], v[56:59], v[80:83], v[44:47]
	v_mfma_f32_16x16x32_bf16 v[36:39], v[64:67], v[80:83], v[36:39]
	v_mfma_f32_16x16x32_bf16 v[28:31], v[56:59], v[166:169], v[28:31]
	v_mfma_f32_16x16x32_bf16 v[20:23], v[64:67], v[166:169], v[20:23]
	v_mfma_f32_16x16x32_bf16 v[12:15], v[56:59], v[212:215], v[12:15]
	v_mfma_f32_16x16x32_bf16 v[4:7], v[64:67], v[212:215], v[4:7]
	v_mfma_f32_16x16x32_bf16 v[92:95], v[60:63], v[76:79], v[92:95]
	v_mfma_f32_16x16x32_bf16 v[68:71], v[88:91], v[76:79], v[68:71]
	v_mfma_f32_16x16x32_bf16 v[44:47], v[60:63], v[84:87], v[44:47]
	v_mfma_f32_16x16x32_bf16 v[36:39], v[88:91], v[84:87], v[36:39]
	v_mfma_f32_16x16x32_bf16 v[28:31], v[60:63], v[208:211], v[28:31]
	v_mfma_f32_16x16x32_bf16 v[20:23], v[88:91], v[208:211], v[20:23]
	v_mfma_f32_16x16x32_bf16 v[12:15], v[60:63], v[216:219], v[12:15]
	v_mfma_f32_16x16x32_bf16 v[4:7], v[88:91], v[216:219], v[4:7]
	s_setprio 0
	s_barrier
	s_add_u32 s26, s26, 0x40080
	s_addc_u32 s27, s27, 0
	s_add_i32 s28, s28, s34
	v_lshl_add_u64 v[56:57], s[26:27], 0, v[180:181]
	s_mov_b32 m0, s28
	s_nop 0
	global_load_lds_dwordx4 v[56:57], off
	v_lshl_add_u64 v[56:57], s[26:27], 0, v[160:161]
	s_add_i32 m0, s28, 0x2000
	s_nop 0
	global_load_lds_dwordx4 v[56:57], off
	s_waitcnt vmcnt(6)
	s_barrier
	s_setprio 1
	v_mfma_f32_16x16x32_bf16 v[48:51], v[228:231], v[72:75], v[48:51]
	v_mfma_f32_16x16x32_bf16 v[88:91], v[232:235], v[76:79], v[48:51]
	v_mfma_f32_16x16x32_bf16 v[48:51], v[242:245], v[72:75], v[52:55]
	v_mfma_f32_16x16x32_bf16 v[40:43], v[228:231], v[80:83], v[40:43]
	v_mfma_f32_16x16x32_bf16 v[32:35], v[242:245], v[80:83], v[32:35]
	v_mfma_f32_16x16x32_bf16 v[24:27], v[228:231], v[166:169], v[24:27]
	v_mfma_f32_16x16x32_bf16 v[16:19], v[242:245], v[166:169], v[16:19]
	v_mfma_f32_16x16x32_bf16 v[8:11], v[228:231], v[212:215], v[8:11]
	v_mfma_f32_16x16x32_bf16 v[0:3], v[242:245], v[212:215], v[0:3]
	v_mfma_f32_16x16x32_bf16 v[64:67], v[204:207], v[76:79], v[48:51]
	v_mfma_f32_16x16x32_bf16 v[40:43], v[232:235], v[84:87], v[40:43]
	v_mfma_f32_16x16x32_bf16 v[32:35], v[204:207], v[84:87], v[32:35]
	v_mfma_f32_16x16x32_bf16 v[24:27], v[232:235], v[208:211], v[24:27]
	v_mfma_f32_16x16x32_bf16 v[16:19], v[204:207], v[208:211], v[16:19]
	v_mfma_f32_16x16x32_bf16 v[8:11], v[232:235], v[216:219], v[8:11]
	v_mfma_f32_16x16x32_bf16 v[0:3], v[204:207], v[216:219], v[0:3]
	s_setprio 0
	s_add_i32 s48, s48, 2
	s_add_u32 s46, s46, 0x100
	s_addc_u32 s47, s47, 0
	s_add_u32 s24, s24, 0x100
	s_addc_u32 s25, s25, 0
	s_cmp_gt_u32 s48, 13
	s_barrier
	s_cbranch_scc0 .LBB0_1583
	v_lshl_or_b32 v48, s44, 8, v178
	v_ashrrev_i32_e32 v49, 31, v48
	v_lshlrev_b64 v[48:49], 2, v[48:49]
	v_lshl_add_u64 v[50:51], s[8:9], 0, v[48:49]
	v_lshl_add_u64 v[52:53], s[12:13], 0, v[48:49]
	global_load_dwordx4 v[72:75], v[50:51], off
	global_load_dwordx4 v[56:59], v[50:51], off offset:64
	global_load_dwordx4 v[84:87], v[52:53], off
	global_load_dwordx4 v[60:63], v[52:53], off offset:64
	global_load_dwordx4 v[76:79], v[50:51], off offset:512
	s_nop 0
	global_load_dwordx4 v[48:51], v[50:51], off offset:576
	s_nop 0
	global_load_dwordx4 v[80:83], v[52:53], off offset:512
	s_nop 0
	global_load_dwordx4 v[52:55], v[52:53], off offset:576
	v_lshl_add_u32 v168, s4, 8, v173
	v_cndmask_b32_e64 v166, 0, 1, s[14:15]
	v_ashrrev_i32_e32 v169, 31, v168
	v_mov_b32_e32 v172, 1.0
	v_mov_b32_e32 v170, 0
	v_cmp_ne_u32_e64 s[4:5], 1, v166
	s_andn2_b64 vcc, exec, s[14:15]
	v_mov_b32_e32 v174, 0
	v_mov_b32_e32 v176, 1.0
	s_cbranch_vccnz .LBB0_1586
	v_lshl_add_u64 v[166:167], v[168:169], 3, s[10:11]
	global_load_dwordx2 v[174:175], v[166:167], off
	global_load_dwordx2 v[206:207], v[166:167], off offset:128
	global_load_dwordx2 v[208:209], v[166:167], off offset:256
	global_load_dwordx2 v[210:211], v[166:167], off offset:384
	global_load_dwordx2 v[212:213], v[166:167], off offset:1024
	global_load_dwordx2 v[214:215], v[166:167], off offset:1152
	global_load_dwordx2 v[216:217], v[166:167], off offset:1280
	global_load_dwordx2 v[218:219], v[166:167], off offset:1408
	s_waitcnt vmcnt(0)
	v_mov_b32_e32 v176, v175
; __device__ __forceinline__ unsigned pk2(float lo, float hi) { const f32x2_t v = {lo, hi}; const bf16x2_t b = __builtin_convertvector(v, bf16x2_t); return __builtin_bit_cast(unsigned, b); }
;     __device__ __forceinline__ void operator()(const f32x4 (&acc)[2][2][4][2], const pg8::Unit& u, int wr, int wc, int fr, int fq) const {
;     ...
;         for (int ai = 0; ai < 2; ++ai)
; #pragma unroll
;             for (int m = 0; m < 4; ++m) {
;                 const int row = row0 + ai * 128 + m * 16; float mu, rstd; row_stats(stats, row, mu, rstd);
; #pragma unroll
;                 for (int n = 0; n < 2; ++n) {
;                     float hv[4];
; #pragma unroll
;                     for (int j = 0; j < 4; ++j) {
;                         const float gt = rstd * (acc[ai][0][m][n][j] - mu * c1g[n][j]) + c2g[n][j];
;                         const float up = rstd * (acc[ai][1][m][n][j] - mu * c1u[n][j]) + c2u[n][j];
;                         hv[j] = gt * __builtin_amdgcn_rcpf(1.f + __expf(-gt)) * up;
;                     }
;                     u32x2 w; w.x = pk2(hv[0], hv[1]); w.y = pk2(hv[2], hv[3]);
;                     *(u32x2*)(H + (size_t)row * FF_ + hcol0 + 16 * n) = w;
;                 }
.LBB0_1586:
	s_waitcnt vmcnt(0)
	v_pk_fma_f32 v[156:157], v[72:73], v[174:175], v[156:157] op_sel_hi:[1,0,1] neg_lo:[1,0,0] neg_hi:[1,0,0]
	v_pk_fma_f32 v[152:153], v[76:77], v[174:175], v[152:153] op_sel_hi:[1,0,1] neg_lo:[1,0,0] neg_hi:[1,0,0]
	v_pk_fma_f32 v[156:157], v[176:177], v[156:157], v[84:85] op_sel_hi:[0,1,1]
	v_mul_f32_e32 v169, 0xbfb8aa3b, v156
	v_exp_f32_e32 v169, v169
	v_pk_fma_f32 v[152:153], v[176:177], v[152:153], v[80:81] op_sel_hi:[0,1,1]
	v_pk_fma_f32 v[154:155], v[78:79], v[174:175], v[154:155] op_sel_hi:[1,0,1] neg_lo:[1,0,0] neg_hi:[1,0,0]
	v_lshl_or_b32 v166, s44, 7, v178
	v_add_f32_e32 v169, 1.0, v169
	v_rcp_f32_e32 v198, v169
	v_mul_f32_e32 v169, 0xbfb8aa3b, v157
	v_exp_f32_e32 v169, v169
	v_pk_fma_f32 v[154:155], v[176:177], v[154:155], v[82:83] op_sel_hi:[0,1,1]
	s_movk_i32 s17, 0x1600
	v_ashrrev_i32_e32 v167, 31, v166
	v_add_f32_e32 v169, 1.0, v169
	v_rcp_f32_e32 v199, v169
	v_pk_fma_f32 v[148:149], v[56:57], v[174:175], v[148:149] op_sel_hi:[1,0,1] neg_lo:[1,0,0] neg_hi:[1,0,0]
	v_pk_fma_f32 v[144:145], v[48:49], v[174:175], v[144:145] op_sel_hi:[1,0,1] neg_lo:[1,0,0] neg_hi:[1,0,0]
	v_pk_fma_f32 v[148:149], v[176:177], v[148:149], v[60:61] op_sel_hi:[0,1,1]
	v_pk_mul_f32 v[156:157], v[156:157], v[198:199]
	v_pk_fma_f32 v[144:145], v[176:177], v[144:145], v[52:53] op_sel_hi:[0,1,1]
	v_pk_mul_f32 v[152:153], v[152:153], v[156:157]
	v_pk_fma_f32 v[156:157], v[74:75], v[174:175], v[158:159] op_sel_hi:[1,0,1] neg_lo:[1,0,0] neg_hi:[1,0,0]
	v_cvt_pk_bf16_f32 v152, v152, v153
	v_pk_fma_f32 v[156:157], v[176:177], v[156:157], v[86:87] op_sel_hi:[0,1,1]
	v_mul_f32_e32 v158, 0xbfb8aa3b, v156
	v_mul_f32_e32 v159, 0xbfb8aa3b, v157
	v_exp_f32_e32 v158, v158
	v_exp_f32_e32 v159, v159
	v_pk_fma_f32 v[146:147], v[50:51], v[174:175], v[146:147] op_sel_hi:[1,0,1] neg_lo:[1,0,0] neg_hi:[1,0,0]
	s_and_b64 vcc, exec, s[4:5]
	v_add_f32_e32 v158, 1.0, v158
	v_add_f32_e32 v159, 1.0, v159
	v_rcp_f32_e32 v158, v158
	v_rcp_f32_e32 v159, v159
	v_pk_fma_f32 v[146:147], v[176:177], v[146:147], v[54:55] op_sel_hi:[0,1,1]
	v_pk_mul_f32 v[156:157], v[156:157], v[158:159]
	s_nop 0
	v_pk_mul_f32 v[154:155], v[154:155], v[156:157]
	s_nop 0
	v_cvt_pk_bf16_f32 v153, v154, v155
	v_mov_b64_e32 v[154:155], s[6:7]
	v_mad_i64_i32 v[154:155], s[24:25], v168, s17, v[154:155]
	v_lshl_add_u64 v[154:155], v[166:167], 1, v[154:155]
	global_store_dwordx2 v[154:155], v[152:153], off
	v_mul_f32_e32 v152, 0xbfb8aa3b, v148
	v_mul_f32_e32 v153, 0xbfb8aa3b, v149
	v_exp_f32_e32 v152, v152
	v_exp_f32_e32 v153, v153
	v_readlane_b32 s24, v254, 19
	v_readlane_b32 s25, v254, 20
	v_add_f32_e32 v152, 1.0, v152
	v_add_f32_e32 v153, 1.0, v153
	v_rcp_f32_e32 v152, v152
	v_rcp_f32_e32 v153, v153
	s_nop 0
	v_pk_mul_f32 v[148:149], v[148:149], v[152:153]
	s_nop 0
	v_pk_mul_f32 v[144:145], v[144:145], v[148:149]
	v_pk_fma_f32 v[148:149], v[58:59], v[174:175], v[150:151] op_sel_hi:[1,0,1] neg_lo:[1,0,0] neg_hi:[1,0,0]
	v_cvt_pk_bf16_f32 v144, v144, v145
	v_pk_fma_f32 v[148:149], v[176:177], v[148:149], v[62:63] op_sel_hi:[0,1,1]
	v_mul_f32_e32 v150, 0xbfb8aa3b, v148
	v_mul_f32_e32 v151, 0xbfb8aa3b, v149
	v_exp_f32_e32 v150, v150
	v_exp_f32_e32 v151, v151
	v_add_f32_e32 v150, 1.0, v150
	v_add_f32_e32 v151, 1.0, v151
	v_rcp_f32_e32 v150, v150
	v_rcp_f32_e32 v151, v151
	s_nop 0
	v_pk_mul_f32 v[148:149], v[148:149], v[150:151]
	s_nop 0
	v_pk_mul_f32 v[146:147], v[146:147], v[148:149]
	s_nop 0
	v_cvt_pk_bf16_f32 v145, v146, v147
	global_store_dwordx2 v[154:155], v[144:145], off offset:32
	s_load_dwordx2 s[48:49], s[24:25], 0x88
	v_or_b32_e32 v144, 16, v168
	v_ashrrev_i32_e32 v145, 31, v144
	s_cbranch_vccnz .LBB0_1588
	v_mov_b32_e32 v170, v206
	v_mov_b32_e32 v171, v207
	v_mov_b32_e32 v172, v171
.LBB0_1588:
	v_pk_fma_f32 v[140:141], v[72:73], v[170:171], v[140:141] op_sel_hi:[1,0,1] neg_lo:[1,0,0] neg_hi:[1,0,0]
	v_pk_fma_f32 v[142:143], v[74:75], v[170:171], v[142:143] op_sel_hi:[1,0,1] neg_lo:[1,0,0] neg_hi:[1,0,0]
	v_pk_fma_f32 v[146:147], v[172:173], v[140:141], v[84:85] op_sel_hi:[0,1,1]
	v_mul_f32_e32 v140, 0xbfb8aa3b, v146
	v_exp_f32_e32 v141, v140
	v_pk_fma_f32 v[142:143], v[172:173], v[142:143], v[86:87] op_sel_hi:[0,1,1]
	v_pk_fma_f32 v[136:137], v[76:77], v[170:171], v[136:137] op_sel_hi:[1,0,1] neg_lo:[1,0,0] neg_hi:[1,0,0]
	v_pk_fma_f32 v[138:139], v[78:79], v[170:171], v[138:139] op_sel_hi:[1,0,1] neg_lo:[1,0,0] neg_hi:[1,0,0]
	v_add_f32_e32 v141, 1.0, v141
	v_rcp_f32_e32 v148, v141
	v_mul_f32_e32 v141, 0xbfb8aa3b, v147
	v_exp_f32_e32 v141, v141
	v_pk_fma_f32 v[136:137], v[172:173], v[136:137], v[80:81] op_sel_hi:[0,1,1]
	v_pk_fma_f32 v[138:139], v[172:173], v[138:139], v[82:83] op_sel_hi:[0,1,1]
	v_pk_fma_f32 v[132:133], v[56:57], v[170:171], v[132:133] op_sel_hi:[1,0,1] neg_lo:[1,0,0] neg_hi:[1,0,0]
	v_add_f32_e32 v141, 1.0, v141
	v_rcp_f32_e32 v149, v141
	v_mul_f32_e32 v141, 0xbfb8aa3b, v142
	v_exp_f32_e32 v141, v141
	v_pk_fma_f32 v[132:133], v[172:173], v[132:133], v[60:61] op_sel_hi:[0,1,1]
	v_pk_mul_f32 v[146:147], v[146:147], v[148:149]
	v_pk_fma_f32 v[128:129], v[48:49], v[170:171], v[128:129] op_sel_hi:[1,0,1] neg_lo:[1,0,0] neg_hi:[1,0,0]
	v_add_f32_e32 v141, 1.0, v141
	v_pk_mul_f32 v[136:137], v[136:137], v[146:147]
	v_rcp_f32_e32 v146, v141
	v_mul_f32_e32 v141, 0xbfb8aa3b, v143
	v_exp_f32_e32 v141, v141
	v_cvt_pk_bf16_f32 v136, v136, v137
	v_pk_fma_f32 v[128:129], v[172:173], v[128:129], v[52:53] op_sel_hi:[0,1,1]
	v_pk_fma_f32 v[130:131], v[50:51], v[170:171], v[130:131] op_sel_hi:[1,0,1] neg_lo:[1,0,0] neg_hi:[1,0,0]
	v_add_f32_e32 v141, 1.0, v141
	v_rcp_f32_e32 v147, v141
	v_pk_fma_f32 v[130:131], v[172:173], v[130:131], v[54:55] op_sel_hi:[0,1,1]
; __device__ __forceinline__ unsigned pk2(float lo, float hi) { const f32x2_t v = {lo, hi}; const bf16x2_t b = __builtin_convertvector(v, bf16x2_t); return __builtin_bit_cast(unsigned, b); }
;     __device__ __forceinline__ void operator()(const f32x4 (&acc)[2][2][4][2], const pg8::Unit& u, int wr, int wc, int fr, int fq) const {
;     ...
;         for (int ai = 0; ai < 2; ++ai)
; #pragma unroll
;             for (int m = 0; m < 4; ++m) {
;                 const int row = row0 + ai * 128 + m * 16; float mu, rstd; row_stats(stats, row, mu, rstd);
; #pragma unroll
;                 for (int n = 0; n < 2; ++n) {
;                     float hv[4];
; #pragma unroll
;                     for (int j = 0; j < 4; ++j) {
;                         const float gt = rstd * (acc[ai][0][m][n][j] - mu * c1g[n][j]) + c2g[n][j];
;                         const float up = rstd * (acc[ai][1][m][n][j] - mu * c1u[n][j]) + c2u[n][j];
;                         hv[j] = gt * __builtin_amdgcn_rcpf(1.f + __expf(-gt)) * up;
;                     }
;                     u32x2 w; w.x = pk2(hv[0], hv[1]); w.y = pk2(hv[2], hv[3]);
;                     *(u32x2*)(H + (size_t)row * FF_ + hcol0 + 16 * n) = w;
;                 }
	v_mov_b32_e32 v140, 1.0
	s_and_b64 vcc, exec, s[4:5]
	v_pk_mul_f32 v[142:143], v[142:143], v[146:147]
	s_nop 0
	v_pk_mul_f32 v[138:139], v[138:139], v[142:143]
	s_nop 0
	v_cvt_pk_bf16_f32 v137, v138, v139
	v_mov_b64_e32 v[138:139], s[6:7]
	v_mad_i64_i32 v[138:139], s[24:25], v144, s17, v[138:139]
	v_lshl_add_u64 v[138:139], v[166:167], 1, v[138:139]
	global_store_dwordx2 v[138:139], v[136:137], off
	v_mul_f32_e32 v136, 0xbfb8aa3b, v132
	v_mul_f32_e32 v137, 0xbfb8aa3b, v133
	v_exp_f32_e32 v136, v136
	v_exp_f32_e32 v137, v137
	v_add_f32_e32 v136, 1.0, v136
	v_add_f32_e32 v137, 1.0, v137
	v_rcp_f32_e32 v136, v136
	v_rcp_f32_e32 v137, v137
	s_nop 0
	v_pk_mul_f32 v[132:133], v[132:133], v[136:137]
	s_nop 0
	v_pk_mul_f32 v[128:129], v[128:129], v[132:133]
	v_pk_fma_f32 v[132:133], v[58:59], v[170:171], v[134:135] op_sel_hi:[1,0,1] neg_lo:[1,0,0] neg_hi:[1,0,0]
	v_cvt_pk_bf16_f32 v128, v128, v129
	v_pk_fma_f32 v[132:133], v[172:173], v[132:133], v[62:63] op_sel_hi:[0,1,1]
	v_mul_f32_e32 v134, 0xbfb8aa3b, v132
	v_mul_f32_e32 v135, 0xbfb8aa3b, v133
	v_exp_f32_e32 v134, v134
	v_exp_f32_e32 v135, v135
	v_add_f32_e32 v134, 1.0, v134
	v_add_f32_e32 v135, 1.0, v135
	v_rcp_f32_e32 v134, v134
	v_rcp_f32_e32 v135, v135
	s_nop 0
	v_pk_mul_f32 v[132:133], v[132:133], v[134:135]
	s_nop 0
	v_pk_mul_f32 v[130:131], v[130:131], v[132:133]
	v_or_b32_e32 v134, 32, v168
	v_cvt_pk_bf16_f32 v129, v130, v131
	global_store_dwordx2 v[138:139], v[128:129], off offset:32
	v_ashrrev_i32_e32 v135, 31, v134
	v_mov_b32_e32 v128, 0
	v_mov_b32_e32 v130, 0
	v_mov_b32_e32 v132, 1.0
	s_cbranch_vccnz .LBB0_1590
	v_mov_b32_e32 v130, v208
	v_mov_b32_e32 v131, v209
	v_mov_b32_e32 v132, v131
.LBB0_1590:
	v_pk_fma_f32 v[124:125], v[72:73], v[130:131], v[124:125] op_sel_hi:[1,0,1] neg_lo:[1,0,0] neg_hi:[1,0,0]
	v_pk_fma_f32 v[120:121], v[76:77], v[130:131], v[120:121] op_sel_hi:[1,0,1] neg_lo:[1,0,0] neg_hi:[1,0,0]
	v_pk_fma_f32 v[124:125], v[132:133], v[124:125], v[84:85] op_sel_hi:[0,1,1]
	v_mul_f32_e32 v129, 0xbfb8aa3b, v124
	v_exp_f32_e32 v129, v129
	v_pk_fma_f32 v[120:121], v[132:133], v[120:121], v[80:81] op_sel_hi:[0,1,1]
	v_pk_fma_f32 v[122:123], v[78:79], v[130:131], v[122:123] op_sel_hi:[1,0,1] neg_lo:[1,0,0] neg_hi:[1,0,0]
	v_pk_fma_f32 v[116:117], v[56:57], v[130:131], v[116:117] op_sel_hi:[1,0,1] neg_lo:[1,0,0] neg_hi:[1,0,0]
	v_add_f32_e32 v129, 1.0, v129
	v_rcp_f32_e32 v136, v129
	v_mul_f32_e32 v129, 0xbfb8aa3b, v125
	v_exp_f32_e32 v129, v129
	v_pk_fma_f32 v[122:123], v[132:133], v[122:123], v[82:83] op_sel_hi:[0,1,1]
	v_pk_fma_f32 v[116:117], v[132:133], v[116:117], v[60:61] op_sel_hi:[0,1,1]
	v_pk_fma_f32 v[112:113], v[48:49], v[130:131], v[112:113] op_sel_hi:[1,0,1] neg_lo:[1,0,0] neg_hi:[1,0,0]
	v_add_f32_e32 v129, 1.0, v129
	v_rcp_f32_e32 v137, v129
	v_pk_fma_f32 v[112:113], v[132:133], v[112:113], v[52:53] op_sel_hi:[0,1,1]
	v_pk_fma_f32 v[114:115], v[50:51], v[130:131], v[114:115] op_sel_hi:[1,0,1] neg_lo:[1,0,0] neg_hi:[1,0,0]
	s_and_b64 vcc, exec, s[4:5]
	v_pk_mul_f32 v[124:125], v[124:125], v[136:137]
	v_pk_fma_f32 v[114:115], v[132:133], v[114:115], v[54:55] op_sel_hi:[0,1,1]
	v_pk_mul_f32 v[120:121], v[120:121], v[124:125]
	v_pk_fma_f32 v[124:125], v[74:75], v[130:131], v[126:127] op_sel_hi:[1,0,1] neg_lo:[1,0,0] neg_hi:[1,0,0]
	v_cvt_pk_bf16_f32 v120, v120, v121
	v_pk_fma_f32 v[124:125], v[132:133], v[124:125], v[86:87] op_sel_hi:[0,1,1]
	v_mul_f32_e32 v126, 0xbfb8aa3b, v124
	v_mul_f32_e32 v127, 0xbfb8aa3b, v125
	v_exp_f32_e32 v126, v126
	v_exp_f32_e32 v127, v127
	v_add_f32_e32 v126, 1.0, v126
	v_add_f32_e32 v127, 1.0, v127
	v_rcp_f32_e32 v126, v126
	v_rcp_f32_e32 v127, v127
	s_nop 0
	v_pk_mul_f32 v[124:125], v[124:125], v[126:127]
	s_nop 0
	v_pk_mul_f32 v[122:123], v[122:123], v[124:125]
	s_nop 0
	v_cvt_pk_bf16_f32 v121, v122, v123
	v_mov_b64_e32 v[122:123], s[6:7]
	v_mad_i64_i32 v[122:123], s[24:25], v134, s17, v[122:123]
	v_lshl_add_u64 v[122:123], v[166:167], 1, v[122:123]
	global_store_dwordx2 v[122:123], v[120:121], off
	v_mul_f32_e32 v120, 0xbfb8aa3b, v116
	v_mul_f32_e32 v121, 0xbfb8aa3b, v117
	v_exp_f32_e32 v120, v120
	v_exp_f32_e32 v121, v121
	v_add_f32_e32 v120, 1.0, v120
	v_add_f32_e32 v121, 1.0, v121
	v_rcp_f32_e32 v120, v120
	v_rcp_f32_e32 v121, v121
	s_nop 0
	v_pk_mul_f32 v[116:117], v[116:117], v[120:121]
	s_nop 0
	v_pk_mul_f32 v[112:113], v[112:113], v[116:117]
	v_pk_fma_f32 v[116:117], v[58:59], v[130:131], v[118:119] op_sel_hi:[1,0,1] neg_lo:[1,0,0] neg_hi:[1,0,0]
	v_cvt_pk_bf16_f32 v112, v112, v113
	v_pk_fma_f32 v[116:117], v[132:133], v[116:117], v[62:63] op_sel_hi:[0,1,1]
	v_mul_f32_e32 v118, 0xbfb8aa3b, v116
	v_mul_f32_e32 v119, 0xbfb8aa3b, v117
	v_exp_f32_e32 v118, v118
	v_exp_f32_e32 v119, v119
	v_add_f32_e32 v118, 1.0, v118
	v_add_f32_e32 v119, 1.0, v119
	v_rcp_f32_e32 v118, v118
	v_rcp_f32_e32 v119, v119
	s_nop 0
	v_pk_mul_f32 v[116:117], v[116:117], v[118:119]
	s_nop 0
	v_pk_mul_f32 v[114:115], v[114:115], v[116:117]
	s_nop 0
	v_cvt_pk_bf16_f32 v113, v114, v115
	global_store_dwordx2 v[122:123], v[112:113], off offset:32
	v_or_b32_e32 v112, 48, v168
	v_ashrrev_i32_e32 v113, 31, v112
	s_cbranch_vccnz .LBB0_1592
	v_mov_b32_e32 v128, v210
	v_mov_b32_e32 v129, v211
	v_mov_b32_e32 v140, v129
; __device__ __forceinline__ unsigned pk2(float lo, float hi) { const f32x2_t v = {lo, hi}; const bf16x2_t b = __builtin_convertvector(v, bf16x2_t); return __builtin_bit_cast(unsigned, b); }
;     __device__ __forceinline__ void operator()(const f32x4 (&acc)[2][2][4][2], const pg8::Unit& u, int wr, int wc, int fr, int fq) const {
;     ...
;         for (int ai = 0; ai < 2; ++ai)
; #pragma unroll
;             for (int m = 0; m < 4; ++m) {
;                 const int row = row0 + ai * 128 + m * 16; float mu, rstd; row_stats(stats, row, mu, rstd);
; #pragma unroll
;                 for (int n = 0; n < 2; ++n) {
;                     float hv[4];
; #pragma unroll
;                     for (int j = 0; j < 4; ++j) {
;                         const float gt = rstd * (acc[ai][0][m][n][j] - mu * c1g[n][j]) + c2g[n][j];
;                         const float up = rstd * (acc[ai][1][m][n][j] - mu * c1u[n][j]) + c2u[n][j];
;                         hv[j] = gt * __builtin_amdgcn_rcpf(1.f + __expf(-gt)) * up;
;                     }
;                     u32x2 w; w.x = pk2(hv[0], hv[1]); w.y = pk2(hv[2], hv[3]);
;                     *(u32x2*)(H + (size_t)row * FF_ + hcol0 + 16 * n) = w;
;                 }
.LBB0_1592:
	v_pk_fma_f32 v[108:109], v[72:73], v[128:129], v[108:109] op_sel_hi:[1,0,1] neg_lo:[1,0,0] neg_hi:[1,0,0]
	v_pk_fma_f32 v[110:111], v[74:75], v[128:129], v[110:111] op_sel_hi:[1,0,1] neg_lo:[1,0,0] neg_hi:[1,0,0]
	v_pk_fma_f32 v[114:115], v[140:141], v[108:109], v[84:85] op_sel_hi:[0,1,1]
	v_mul_f32_e32 v108, 0xbfb8aa3b, v114
	v_exp_f32_e32 v109, v108
	v_pk_fma_f32 v[110:111], v[140:141], v[110:111], v[86:87] op_sel_hi:[0,1,1]
	v_pk_fma_f32 v[104:105], v[76:77], v[128:129], v[104:105] op_sel_hi:[1,0,1] neg_lo:[1,0,0] neg_hi:[1,0,0]
	v_pk_fma_f32 v[106:107], v[78:79], v[128:129], v[106:107] op_sel_hi:[1,0,1] neg_lo:[1,0,0] neg_hi:[1,0,0]
	v_add_f32_e32 v109, 1.0, v109
	v_rcp_f32_e32 v116, v109
	v_mul_f32_e32 v109, 0xbfb8aa3b, v115
	v_exp_f32_e32 v109, v109
	v_pk_fma_f32 v[104:105], v[140:141], v[104:105], v[80:81] op_sel_hi:[0,1,1]
	v_pk_fma_f32 v[106:107], v[140:141], v[106:107], v[82:83] op_sel_hi:[0,1,1]
	v_pk_fma_f32 v[100:101], v[56:57], v[128:129], v[100:101] op_sel_hi:[1,0,1] neg_lo:[1,0,0] neg_hi:[1,0,0]
	v_add_f32_e32 v109, 1.0, v109
	v_rcp_f32_e32 v117, v109
	v_mul_f32_e32 v109, 0xbfb8aa3b, v110
	v_exp_f32_e32 v109, v109
	v_pk_fma_f32 v[100:101], v[140:141], v[100:101], v[60:61] op_sel_hi:[0,1,1]
	v_pk_mul_f32 v[114:115], v[114:115], v[116:117]
	v_pk_fma_f32 v[96:97], v[48:49], v[128:129], v[96:97] op_sel_hi:[1,0,1] neg_lo:[1,0,0] neg_hi:[1,0,0]
	v_add_f32_e32 v109, 1.0, v109
	v_pk_mul_f32 v[104:105], v[104:105], v[114:115]
	v_rcp_f32_e32 v114, v109
	v_mul_f32_e32 v109, 0xbfb8aa3b, v111
	v_exp_f32_e32 v109, v109
	v_cvt_pk_bf16_f32 v104, v104, v105
	v_pk_fma_f32 v[96:97], v[140:141], v[96:97], v[52:53] op_sel_hi:[0,1,1]
	v_pk_fma_f32 v[98:99], v[50:51], v[128:129], v[98:99] op_sel_hi:[1,0,1] neg_lo:[1,0,0] neg_hi:[1,0,0]
	v_add_f32_e32 v109, 1.0, v109
	v_rcp_f32_e32 v115, v109
	v_pk_fma_f32 v[98:99], v[140:141], v[98:99], v[54:55] op_sel_hi:[0,1,1]
	v_mov_b32_e32 v108, 1.0
	s_and_b64 vcc, exec, s[4:5]
	v_pk_mul_f32 v[110:111], v[110:111], v[114:115]
	s_nop 0
	v_pk_mul_f32 v[106:107], v[106:107], v[110:111]
	s_nop 0
	v_cvt_pk_bf16_f32 v105, v106, v107
	v_mov_b64_e32 v[106:107], s[6:7]
	v_mad_i64_i32 v[106:107], s[24:25], v112, s17, v[106:107]
	v_lshl_add_u64 v[106:107], v[166:167], 1, v[106:107]
	global_store_dwordx2 v[106:107], v[104:105], off
	v_mul_f32_e32 v104, 0xbfb8aa3b, v100
	v_mul_f32_e32 v105, 0xbfb8aa3b, v101
	v_exp_f32_e32 v104, v104
	v_exp_f32_e32 v105, v105
	v_add_f32_e32 v104, 1.0, v104
	v_add_f32_e32 v105, 1.0, v105
	v_rcp_f32_e32 v104, v104
	v_rcp_f32_e32 v105, v105
	s_nop 0
	v_pk_mul_f32 v[100:101], v[100:101], v[104:105]
	s_nop 0
	v_pk_mul_f32 v[96:97], v[96:97], v[100:101]
	v_pk_fma_f32 v[100:101], v[58:59], v[128:129], v[102:103] op_sel_hi:[1,0,1] neg_lo:[1,0,0] neg_hi:[1,0,0]
	v_cvt_pk_bf16_f32 v96, v96, v97
	v_pk_fma_f32 v[100:101], v[140:141], v[100:101], v[62:63] op_sel_hi:[0,1,1]
	v_mul_f32_e32 v102, 0xbfb8aa3b, v100
	v_mul_f32_e32 v103, 0xbfb8aa3b, v101
	v_exp_f32_e32 v102, v102
	v_exp_f32_e32 v103, v103
	v_add_f32_e32 v102, 1.0, v102
	v_add_f32_e32 v103, 1.0, v103
	v_rcp_f32_e32 v102, v102
	v_rcp_f32_e32 v103, v103
	s_nop 0
	v_pk_mul_f32 v[100:101], v[100:101], v[102:103]
	s_nop 0
	v_pk_mul_f32 v[98:99], v[98:99], v[100:101]
	v_add_u32_e32 v102, 0x80, v168
	v_cvt_pk_bf16_f32 v97, v98, v99
	global_store_dwordx2 v[106:107], v[96:97], off offset:32
	v_ashrrev_i32_e32 v103, 31, v102
	v_mov_b32_e32 v96, 0
	v_mov_b32_e32 v98, 0
	v_mov_b32_e32 v100, 1.0
	s_cbranch_vccnz .LBB0_1594
	v_mov_b32_e32 v98, v212
	v_mov_b32_e32 v99, v213
	v_mov_b32_e32 v100, v99
.LBB0_1594:
	v_pk_fma_f32 v[92:93], v[72:73], v[98:99], v[92:93] op_sel_hi:[1,0,1] neg_lo:[1,0,0] neg_hi:[1,0,0]
	v_pk_fma_f32 v[88:89], v[76:77], v[98:99], v[88:89] op_sel_hi:[1,0,1] neg_lo:[1,0,0] neg_hi:[1,0,0]
	v_pk_fma_f32 v[92:93], v[100:101], v[92:93], v[84:85] op_sel_hi:[0,1,1]
	v_mul_f32_e32 v97, 0xbfb8aa3b, v92
	v_exp_f32_e32 v97, v97
	v_pk_fma_f32 v[88:89], v[100:101], v[88:89], v[80:81] op_sel_hi:[0,1,1]
	v_pk_fma_f32 v[90:91], v[78:79], v[98:99], v[90:91] op_sel_hi:[1,0,1] neg_lo:[1,0,0] neg_hi:[1,0,0]
	v_pk_fma_f32 v[68:69], v[56:57], v[98:99], v[68:69] op_sel_hi:[1,0,1] neg_lo:[1,0,0] neg_hi:[1,0,0]
	v_add_f32_e32 v97, 1.0, v97
	v_rcp_f32_e32 v104, v97
	v_mul_f32_e32 v97, 0xbfb8aa3b, v93
	v_exp_f32_e32 v97, v97
	v_pk_fma_f32 v[90:91], v[100:101], v[90:91], v[82:83] op_sel_hi:[0,1,1]
	v_pk_fma_f32 v[68:69], v[100:101], v[68:69], v[60:61] op_sel_hi:[0,1,1]
	v_pk_fma_f32 v[64:65], v[48:49], v[98:99], v[64:65] op_sel_hi:[1,0,1] neg_lo:[1,0,0] neg_hi:[1,0,0]
	v_add_f32_e32 v97, 1.0, v97
	v_rcp_f32_e32 v105, v97
	v_pk_fma_f32 v[64:65], v[100:101], v[64:65], v[52:53] op_sel_hi:[0,1,1]
	v_pk_fma_f32 v[66:67], v[50:51], v[98:99], v[66:67] op_sel_hi:[1,0,1] neg_lo:[1,0,0] neg_hi:[1,0,0]
	s_and_b64 vcc, exec, s[4:5]
	v_pk_mul_f32 v[92:93], v[92:93], v[104:105]
	v_pk_fma_f32 v[66:67], v[100:101], v[66:67], v[54:55] op_sel_hi:[0,1,1]
	v_pk_mul_f32 v[88:89], v[88:89], v[92:93]
	v_pk_fma_f32 v[92:93], v[74:75], v[98:99], v[94:95] op_sel_hi:[1,0,1] neg_lo:[1,0,0] neg_hi:[1,0,0]
	v_cvt_pk_bf16_f32 v88, v88, v89
	v_pk_fma_f32 v[92:93], v[100:101], v[92:93], v[86:87] op_sel_hi:[0,1,1]
	v_mul_f32_e32 v94, 0xbfb8aa3b, v92
	v_mul_f32_e32 v95, 0xbfb8aa3b, v93
	v_exp_f32_e32 v94, v94
	v_exp_f32_e32 v95, v95
	v_add_f32_e32 v94, 1.0, v94
	v_add_f32_e32 v95, 1.0, v95
	v_rcp_f32_e32 v94, v94
	v_rcp_f32_e32 v95, v95
	s_nop 0
	v_pk_mul_f32 v[92:93], v[92:93], v[94:95]
	s_nop 0
	v_pk_mul_f32 v[90:91], v[90:91], v[92:93]
	s_nop 0
	v_cvt_pk_bf16_f32 v89, v90, v91
	v_mov_b64_e32 v[90:91], s[6:7]
	v_mad_i64_i32 v[90:91], s[24:25], v102, s17, v[90:91]
	v_lshl_add_u64 v[90:91], v[166:167], 1, v[90:91]
	global_store_dwordx2 v[90:91], v[88:89], off
	v_mul_f32_e32 v88, 0xbfb8aa3b, v68
	v_mul_f32_e32 v89, 0xbfb8aa3b, v69
	v_exp_f32_e32 v88, v88
	v_exp_f32_e32 v89, v89
	v_add_f32_e32 v88, 1.0, v88
	v_add_f32_e32 v89, 1.0, v89
	v_rcp_f32_e32 v88, v88
	v_rcp_f32_e32 v89, v89
	s_nop 0
	v_pk_mul_f32 v[68:69], v[68:69], v[88:89]
	s_nop 0
	v_pk_mul_f32 v[64:65], v[64:65], v[68:69]
	v_pk_fma_f32 v[68:69], v[58:59], v[98:99], v[70:71] op_sel_hi:[1,0,1] neg_lo:[1,0,0] neg_hi:[1,0,0]
	v_cvt_pk_bf16_f32 v64, v64, v65
	v_pk_fma_f32 v[68:69], v[100:101], v[68:69], v[62:63] op_sel_hi:[0,1,1]
	v_mul_f32_e32 v70, 0xbfb8aa3b, v68
	v_mul_f32_e32 v71, 0xbfb8aa3b, v69
	v_exp_f32_e32 v70, v70
	v_exp_f32_e32 v71, v71
	v_add_f32_e32 v70, 1.0, v70
	v_add_f32_e32 v71, 1.0, v71
	v_rcp_f32_e32 v70, v70
	v_rcp_f32_e32 v71, v71
	s_nop 0
	v_pk_mul_f32 v[68:69], v[68:69], v[70:71]
	s_nop 0
	v_pk_mul_f32 v[66:67], v[66:67], v[68:69]
	s_nop 0
	v_cvt_pk_bf16_f32 v65, v66, v67
	global_store_dwordx2 v[90:91], v[64:65], off offset:32
	v_add_u32_e32 v64, 0x90, v168
	v_ashrrev_i32_e32 v65, 31, v64
	s_cbranch_vccnz .LBB0_1596
	v_mov_b32_e32 v96, v214
	v_mov_b32_e32 v97, v215
	v_mov_b32_e32 v108, v97
; __device__ __forceinline__ unsigned pk2(float lo, float hi) { const f32x2_t v = {lo, hi}; const bf16x2_t b = __builtin_convertvector(v, bf16x2_t); return __builtin_bit_cast(unsigned, b); }
;     __device__ __forceinline__ void operator()(const f32x4 (&acc)[2][2][4][2], const pg8::Unit& u, int wr, int wc, int fr, int fq) const {
;     ...
;         for (int ai = 0; ai < 2; ++ai)
; #pragma unroll
;             for (int m = 0; m < 4; ++m) {
;                 const int row = row0 + ai * 128 + m * 16; float mu, rstd; row_stats(stats, row, mu, rstd);
; #pragma unroll
;                 for (int n = 0; n < 2; ++n) {
;                     float hv[4];
; #pragma unroll
;                     for (int j = 0; j < 4; ++j) {
;                         const float gt = rstd * (acc[ai][0][m][n][j] - mu * c1g[n][j]) + c2g[n][j];
;                         const float up = rstd * (acc[ai][1][m][n][j] - mu * c1u[n][j]) + c2u[n][j];
;                         hv[j] = gt * __builtin_amdgcn_rcpf(1.f + __expf(-gt)) * up;
;                     }
;                     u32x2 w; w.x = pk2(hv[0], hv[1]); w.y = pk2(hv[2], hv[3]);
;                     *(u32x2*)(H + (size_t)row * FF_ + hcol0 + 16 * n) = w;
;                 }
.LBB0_1596:
	v_pk_fma_f32 v[44:45], v[72:73], v[96:97], v[44:45] op_sel_hi:[1,0,1] neg_lo:[1,0,0] neg_hi:[1,0,0]
	v_pk_fma_f32 v[46:47], v[74:75], v[96:97], v[46:47] op_sel_hi:[1,0,1] neg_lo:[1,0,0] neg_hi:[1,0,0]
	v_pk_fma_f32 v[66:67], v[108:109], v[44:45], v[84:85] op_sel_hi:[0,1,1]
	v_mul_f32_e32 v44, 0xbfb8aa3b, v66
	v_exp_f32_e32 v45, v44
	v_pk_fma_f32 v[46:47], v[108:109], v[46:47], v[86:87] op_sel_hi:[0,1,1]
	v_pk_fma_f32 v[40:41], v[76:77], v[96:97], v[40:41] op_sel_hi:[1,0,1] neg_lo:[1,0,0] neg_hi:[1,0,0]
	v_pk_fma_f32 v[42:43], v[78:79], v[96:97], v[42:43] op_sel_hi:[1,0,1] neg_lo:[1,0,0] neg_hi:[1,0,0]
	v_add_f32_e32 v45, 1.0, v45
	v_rcp_f32_e32 v68, v45
	v_mul_f32_e32 v45, 0xbfb8aa3b, v67
	v_exp_f32_e32 v45, v45
	v_pk_fma_f32 v[40:41], v[108:109], v[40:41], v[80:81] op_sel_hi:[0,1,1]
	v_pk_fma_f32 v[42:43], v[108:109], v[42:43], v[82:83] op_sel_hi:[0,1,1]
	v_pk_fma_f32 v[36:37], v[56:57], v[96:97], v[36:37] op_sel_hi:[1,0,1] neg_lo:[1,0,0] neg_hi:[1,0,0]
	v_add_f32_e32 v45, 1.0, v45
	v_rcp_f32_e32 v69, v45
	v_mul_f32_e32 v45, 0xbfb8aa3b, v46
	v_exp_f32_e32 v45, v45
	v_pk_fma_f32 v[36:37], v[108:109], v[36:37], v[60:61] op_sel_hi:[0,1,1]
	v_pk_mul_f32 v[66:67], v[66:67], v[68:69]
	v_pk_fma_f32 v[32:33], v[48:49], v[96:97], v[32:33] op_sel_hi:[1,0,1] neg_lo:[1,0,0] neg_hi:[1,0,0]
	v_add_f32_e32 v45, 1.0, v45
	v_pk_mul_f32 v[40:41], v[40:41], v[66:67]
	v_rcp_f32_e32 v66, v45
	v_mul_f32_e32 v45, 0xbfb8aa3b, v47
	v_exp_f32_e32 v45, v45
	v_cvt_pk_bf16_f32 v40, v40, v41
	v_pk_fma_f32 v[32:33], v[108:109], v[32:33], v[52:53] op_sel_hi:[0,1,1]
	v_pk_fma_f32 v[34:35], v[50:51], v[96:97], v[34:35] op_sel_hi:[1,0,1] neg_lo:[1,0,0] neg_hi:[1,0,0]
	v_add_f32_e32 v45, 1.0, v45
	v_rcp_f32_e32 v67, v45
	v_pk_fma_f32 v[34:35], v[108:109], v[34:35], v[54:55] op_sel_hi:[0,1,1]
	v_mov_b32_e32 v44, 1.0
	s_and_b64 vcc, exec, s[4:5]
	v_pk_mul_f32 v[46:47], v[46:47], v[66:67]
	s_nop 0
	v_pk_mul_f32 v[42:43], v[42:43], v[46:47]
	s_nop 0
	v_cvt_pk_bf16_f32 v41, v42, v43
	v_mov_b64_e32 v[42:43], s[6:7]
	v_mad_i64_i32 v[42:43], s[24:25], v64, s17, v[42:43]
	v_lshl_add_u64 v[42:43], v[166:167], 1, v[42:43]
	global_store_dwordx2 v[42:43], v[40:41], off
	v_mul_f32_e32 v40, 0xbfb8aa3b, v36
	v_mul_f32_e32 v41, 0xbfb8aa3b, v37
	v_exp_f32_e32 v40, v40
	v_exp_f32_e32 v41, v41
	v_add_f32_e32 v40, 1.0, v40
	v_add_f32_e32 v41, 1.0, v41
	v_rcp_f32_e32 v40, v40
	v_rcp_f32_e32 v41, v41
	s_nop 0
	v_pk_mul_f32 v[36:37], v[36:37], v[40:41]
	s_nop 0
	v_pk_mul_f32 v[32:33], v[32:33], v[36:37]
	v_pk_fma_f32 v[36:37], v[58:59], v[96:97], v[38:39] op_sel_hi:[1,0,1] neg_lo:[1,0,0] neg_hi:[1,0,0]
	v_cvt_pk_bf16_f32 v32, v32, v33
	v_pk_fma_f32 v[36:37], v[108:109], v[36:37], v[62:63] op_sel_hi:[0,1,1]
	v_mul_f32_e32 v38, 0xbfb8aa3b, v36
	v_mul_f32_e32 v39, 0xbfb8aa3b, v37
	v_exp_f32_e32 v38, v38
	v_exp_f32_e32 v39, v39
	v_add_f32_e32 v38, 1.0, v38
	v_add_f32_e32 v39, 1.0, v39
	v_rcp_f32_e32 v38, v38
	v_rcp_f32_e32 v39, v39
	s_nop 0
	v_pk_mul_f32 v[36:37], v[36:37], v[38:39]
	s_nop 0
	v_pk_mul_f32 v[34:35], v[34:35], v[36:37]
	v_add_u32_e32 v38, 0xa0, v168
	v_cvt_pk_bf16_f32 v33, v34, v35
	global_store_dwordx2 v[42:43], v[32:33], off offset:32
	v_ashrrev_i32_e32 v39, 31, v38
	v_mov_b32_e32 v32, 0
	v_mov_b32_e32 v34, 0
	v_mov_b32_e32 v36, 1.0
	s_cbranch_vccnz .LBB0_1598
	v_mov_b32_e32 v34, v216
	v_mov_b32_e32 v35, v217
	v_mov_b32_e32 v36, v35
.LBB0_1598:
	v_pk_fma_f32 v[28:29], v[72:73], v[34:35], v[28:29] op_sel_hi:[1,0,1] neg_lo:[1,0,0] neg_hi:[1,0,0]
	v_pk_fma_f32 v[24:25], v[76:77], v[34:35], v[24:25] op_sel_hi:[1,0,1] neg_lo:[1,0,0] neg_hi:[1,0,0]
	v_pk_fma_f32 v[28:29], v[36:37], v[28:29], v[84:85] op_sel_hi:[0,1,1]
	v_mul_f32_e32 v33, 0xbfb8aa3b, v28
	v_exp_f32_e32 v33, v33
	v_pk_fma_f32 v[24:25], v[36:37], v[24:25], v[80:81] op_sel_hi:[0,1,1]
	v_pk_fma_f32 v[26:27], v[78:79], v[34:35], v[26:27] op_sel_hi:[1,0,1] neg_lo:[1,0,0] neg_hi:[1,0,0]
	v_pk_fma_f32 v[20:21], v[56:57], v[34:35], v[20:21] op_sel_hi:[1,0,1] neg_lo:[1,0,0] neg_hi:[1,0,0]
	v_add_f32_e32 v33, 1.0, v33
	v_rcp_f32_e32 v40, v33
	v_mul_f32_e32 v33, 0xbfb8aa3b, v29
	v_exp_f32_e32 v33, v33
	v_pk_fma_f32 v[26:27], v[36:37], v[26:27], v[82:83] op_sel_hi:[0,1,1]
	v_pk_fma_f32 v[20:21], v[36:37], v[20:21], v[60:61] op_sel_hi:[0,1,1]
	v_pk_fma_f32 v[16:17], v[48:49], v[34:35], v[16:17] op_sel_hi:[1,0,1] neg_lo:[1,0,0] neg_hi:[1,0,0]
	v_add_f32_e32 v33, 1.0, v33
	v_rcp_f32_e32 v41, v33
	v_pk_fma_f32 v[16:17], v[36:37], v[16:17], v[52:53] op_sel_hi:[0,1,1]
	v_pk_fma_f32 v[18:19], v[50:51], v[34:35], v[18:19] op_sel_hi:[1,0,1] neg_lo:[1,0,0] neg_hi:[1,0,0]
	s_and_b64 vcc, exec, s[4:5]
	v_pk_mul_f32 v[28:29], v[28:29], v[40:41]
	v_pk_fma_f32 v[18:19], v[36:37], v[18:19], v[54:55] op_sel_hi:[0,1,1]
	v_pk_mul_f32 v[24:25], v[24:25], v[28:29]
	v_pk_fma_f32 v[28:29], v[74:75], v[34:35], v[30:31] op_sel_hi:[1,0,1] neg_lo:[1,0,0] neg_hi:[1,0,0]
	v_cvt_pk_bf16_f32 v24, v24, v25
	v_pk_fma_f32 v[28:29], v[36:37], v[28:29], v[86:87] op_sel_hi:[0,1,1]
	v_mul_f32_e32 v30, 0xbfb8aa3b, v28
	v_mul_f32_e32 v31, 0xbfb8aa3b, v29
	v_exp_f32_e32 v30, v30
	v_exp_f32_e32 v31, v31
	v_add_f32_e32 v30, 1.0, v30
	v_add_f32_e32 v31, 1.0, v31
	v_rcp_f32_e32 v30, v30
	v_rcp_f32_e32 v31, v31
	s_nop 0
	v_pk_mul_f32 v[28:29], v[28:29], v[30:31]
	s_nop 0
	v_pk_mul_f32 v[26:27], v[26:27], v[28:29]
	s_nop 0
	v_cvt_pk_bf16_f32 v25, v26, v27
	v_mov_b64_e32 v[26:27], s[6:7]
	v_mad_i64_i32 v[26:27], s[24:25], v38, s17, v[26:27]
	v_lshl_add_u64 v[26:27], v[166:167], 1, v[26:27]
	global_store_dwordx2 v[26:27], v[24:25], off
	v_mul_f32_e32 v24, 0xbfb8aa3b, v20
	v_mul_f32_e32 v25, 0xbfb8aa3b, v21
	v_exp_f32_e32 v24, v24
	v_exp_f32_e32 v25, v25
	v_add_f32_e32 v24, 1.0, v24
	v_add_f32_e32 v25, 1.0, v25
	v_rcp_f32_e32 v24, v24
	v_rcp_f32_e32 v25, v25
	s_nop 0
	v_pk_mul_f32 v[20:21], v[20:21], v[24:25]
	s_nop 0
	v_pk_mul_f32 v[16:17], v[16:17], v[20:21]
	v_pk_fma_f32 v[20:21], v[58:59], v[34:35], v[22:23] op_sel_hi:[1,0,1] neg_lo:[1,0,0] neg_hi:[1,0,0]
	v_cvt_pk_bf16_f32 v16, v16, v17
	v_pk_fma_f32 v[20:21], v[36:37], v[20:21], v[62:63] op_sel_hi:[0,1,1]
	v_mul_f32_e32 v22, 0xbfb8aa3b, v20
	v_mul_f32_e32 v23, 0xbfb8aa3b, v21
	v_exp_f32_e32 v22, v22
	v_exp_f32_e32 v23, v23
	v_add_f32_e32 v22, 1.0, v22
	v_add_f32_e32 v23, 1.0, v23
	v_rcp_f32_e32 v22, v22
	v_rcp_f32_e32 v23, v23
	s_nop 0
	v_pk_mul_f32 v[20:21], v[20:21], v[22:23]
	s_nop 0
	v_pk_mul_f32 v[18:19], v[18:19], v[20:21]
	s_nop 0
	v_cvt_pk_bf16_f32 v17, v18, v19
	global_store_dwordx2 v[26:27], v[16:17], off offset:32
	v_add_u32_e32 v16, 0xb0, v168
	v_ashrrev_i32_e32 v17, 31, v16
	s_cbranch_vccnz .LBB0_1579
	v_mov_b32_e32 v32, v218
	v_mov_b32_e32 v33, v219
	v_mov_b32_e32 v44, v33
	s_branch .LBB0_1579
